# K-loop MFMA block entry: duplicate LDS wait behind the barrier removed and priority raised in front of it, first MFMA follows the barrier directly
# speedup vs baseline: 1.0033x; 1.0033x over previous
; #define PG8_STAGE(bufoff, gbase, voff) do { _Pragma("unroll") for (int _i = 0; _i < 2; ++_i) \
;         __builtin_amdgcn_global_load_lds((const unsigned*)((const char*)(gbase) + (voff)[_i]), (PG8_LAS unsigned*)(lds + (bufoff) + ldsw + _i * 8192), 16, 0, 0); } while (0)
; #define PG8_LDA(dst, b, h) do { _Pragma("unroll") for (int m = 0; m < 4; ++m) _Pragma("unroll") for (int k = 0; k < 2; ++k) dst[m][k] = *(const PG8_LAS bf16x8*)(lds + PG8_SA(b, h) + aoff + m * 2048 + k * 1024); } while (0)
; #define PG8_LDB(dst, b, h) do { _Pragma("unroll") for (int n = 0; n < 2; ++n) _Pragma("unroll") for (int k = 0; k < 2; ++k) dst[n][k] = *(const PG8_LAS bf16x8*)(lds + PG8_SB(b, h) + boff + n * 2048 + k * 1024); } while (0)
; #define PG8_MMA(ai, bj, At, Bt) do { __builtin_amdgcn_s_setprio(1); _Pragma("unroll") for (int m = 0; m < 4; ++m) _Pragma("unroll") for (int n = 0; n < 2; ++n) _Pragma("unroll") for (int k = 0; k < 2; ++k) \
;         acc[ai][bj][m][n] = __builtin_amdgcn_mfma_f32_16x16x32_bf16(Bt[n][k], At[m][k], acc[ai][bj][m][n], 0, 0, 0); __builtin_amdgcn_s_setprio(0); } while (0)
; #define PG8_WAIT_V(n) asm volatile("s_waitcnt vmcnt(" #n ")" ::: "memory")
; #define PG8_WAIT_VN(n) asm volatile("s_waitcnt vmcnt(%0)" :: "n"(n) : "memory")
; #define PG8_WAIT_L(n) asm volatile("s_waitcnt lgkmcnt(" #n ")" ::: "memory")
; #define PG8_BAR __builtin_amdgcn_s_barrier()
; #define PG8_SCHED __builtin_amdgcn_sched_barrier(0)
; template <class Epi, class Sched, bool ALIGN_EPI = false, bool SP2 = false>
; __device__ __forceinline__ void gemm_phase(PG8_LAS unsigned char* lds, const Gemm g, const Sched& S, const Epi& E, const int wave_id) {
;     ...
;             PG8_WAIT_VN(8 + Epi::NS); if (strict) PG8_WAIT_V(8); PG8_WAIT_L(0); PG8_BAR; PG8_MMA(1, 0, At, B0); PG8_MMA(1, 1, At, B1); PG8_BAR; PG8_SCHED;
;             PG8_LDB(B0, 1, 0); PG8_LDB(B1, 1, 1); PG8_SCHED; PG8_LDA(At, 1, 0); PG8_STAGE(PG8_SA(0, 1), a2 + hstep, voffA);
;             PG8_WAIT_V(8); PG8_WAIT_L(0); PG8_BAR; PG8_MMA(0, 0, At, B0); PG8_MMA(0, 1, At, B1); PG8_BAR; PG8_SCHED;
.LBB0_157:
	s_waitcnt lgkmcnt(0)
	s_setprio 1
	s_barrier
	v_mfma_f32_16x16x32_bf16 v[62:65], v[146:149], v[186:189], v[62:65]
	v_mfma_f32_16x16x32_bf16 v[58:61], v[154:157], v[186:189], v[58:61]
	v_mfma_f32_16x16x32_bf16 v[54:57], v[146:149], v[178:181], v[54:57]
	v_mfma_f32_16x16x32_bf16 v[50:53], v[154:157], v[178:181], v[50:53]
	v_mfma_f32_16x16x32_bf16 v[30:33], v[146:149], v[170:173], v[30:33]
	v_mfma_f32_16x16x32_bf16 v[26:29], v[154:157], v[170:173], v[26:29]
	v_mfma_f32_16x16x32_bf16 v[22:25], v[146:149], v[162:165], v[22:25]
	v_mfma_f32_16x16x32_bf16 v[18:21], v[154:157], v[162:165], v[18:21]
	v_mfma_f32_16x16x32_bf16 v[62:65], v[150:153], v[190:193], v[62:65]
	v_mfma_f32_16x16x32_bf16 v[58:61], v[158:161], v[190:193], v[58:61]
	v_mfma_f32_16x16x32_bf16 v[54:57], v[150:153], v[182:185], v[54:57]
	v_mfma_f32_16x16x32_bf16 v[50:53], v[158:161], v[182:185], v[50:53]
	v_mfma_f32_16x16x32_bf16 v[30:33], v[150:153], v[174:177], v[30:33]
	v_mfma_f32_16x16x32_bf16 v[26:29], v[158:161], v[174:177], v[26:29]
	v_mfma_f32_16x16x32_bf16 v[22:25], v[150:153], v[166:169], v[22:25]
	v_mfma_f32_16x16x32_bf16 v[18:21], v[158:161], v[166:169], v[18:21]
	s_setprio 0
	s_setprio 1
	v_mfma_f32_16x16x32_bf16 v[46:49], v[130:133], v[186:189], v[46:49]
	v_mfma_f32_16x16x32_bf16 v[42:45], v[138:141], v[186:189], v[42:45]
	v_mfma_f32_16x16x32_bf16 v[38:41], v[130:133], v[178:181], v[38:41]
	v_mfma_f32_16x16x32_bf16 v[34:37], v[138:141], v[178:181], v[34:37]
	v_mfma_f32_16x16x32_bf16 v[14:17], v[130:133], v[170:173], v[14:17]
	v_mfma_f32_16x16x32_bf16 v[10:13], v[138:141], v[170:173], v[10:13]
	v_mfma_f32_16x16x32_bf16 v[6:9], v[130:133], v[162:165], v[6:9]
	v_mfma_f32_16x16x32_bf16 v[2:5], v[138:141], v[162:165], v[2:5]
	v_mfma_f32_16x16x32_bf16 v[46:49], v[134:137], v[190:193], v[46:49]
	v_mfma_f32_16x16x32_bf16 v[42:45], v[142:145], v[190:193], v[42:45]
	v_mfma_f32_16x16x32_bf16 v[38:41], v[134:137], v[182:185], v[38:41]
	v_mfma_f32_16x16x32_bf16 v[34:37], v[142:145], v[182:185], v[34:37]
	v_mfma_f32_16x16x32_bf16 v[14:17], v[134:137], v[174:177], v[14:17]
	v_mfma_f32_16x16x32_bf16 v[10:13], v[142:145], v[174:177], v[10:13]
	v_mfma_f32_16x16x32_bf16 v[6:9], v[134:137], v[166:169], v[6:9]
	v_mfma_f32_16x16x32_bf16 v[2:5], v[142:145], v[166:169], v[2:5]
	s_setprio 0
	s_barrier
	s_add_i32 s28, 0, 0x18000
	s_add_i32 s29, 0, 0x1c000
	v_add_u32_e32 v142, s28, v246
	v_add_u32_e32 v158, s29, v246
	ds_read_b128 v[130:133], v142
	ds_read_b128 v[134:137], v142 offset:1024
	ds_read_b128 v[138:141], v142 offset:2048
	ds_read_b128 v[142:145], v142 offset:3072
	ds_read_b128 v[146:149], v158
	ds_read_b128 v[150:153], v158 offset:1024
	ds_read_b128 v[154:157], v158 offset:2048
	ds_read_b128 v[158:161], v158 offset:3072
	s_add_u32 s26, s26, 0x40000
	s_addc_u32 s27, s27, 0
	s_mov_b32 m0, s52
	v_lshl_add_u64 v[194:195], s[26:27], 0, v[210:211]
	ds_read_b128 v[162:165], v249 offset:32768
	ds_read_b128 v[166:169], v249 offset:33792
	ds_read_b128 v[170:173], v249 offset:34816
	ds_read_b128 v[174:177], v249 offset:35840
	ds_read_b128 v[178:181], v249 offset:36864
	ds_read_b128 v[182:185], v249 offset:37888
	ds_read_b128 v[186:189], v249 offset:38912
	ds_read_b128 v[190:193], v249 offset:39936
	global_load_lds_dwordx4 v[194:195], off
	v_lshl_add_u64 v[194:195], s[26:27], 0, v[214:215]
	s_mov_b32 m0, s54
	s_nop 0
	global_load_lds_dwordx4 v[194:195], off
	s_waitcnt vmcnt(18)
	s_cmp_eq_u32 s100, 0
	s_cbranch_scc1 .Lthird_wait_relaxed_6
	s_waitcnt vmcnt(8)
; #define PG8_STAGE(bufoff, gbase, voff) do { _Pragma("unroll") for (int _i = 0; _i < 2; ++_i) \
;         __builtin_amdgcn_global_load_lds((const unsigned*)((const char*)(gbase) + (voff)[_i]), (PG8_LAS unsigned*)(lds + (bufoff) + ldsw + _i * 8192), 16, 0, 0); } while (0)
; #define PG8_LDA(dst, b, h) do { _Pragma("unroll") for (int m = 0; m < 4; ++m) _Pragma("unroll") for (int k = 0; k < 2; ++k) dst[m][k] = *(const PG8_LAS bf16x8*)(lds + PG8_SA(b, h) + aoff + m * 2048 + k * 1024); } while (0)
; #define PG8_MMA(ai, bj, At, Bt) do { __builtin_amdgcn_s_setprio(1); _Pragma("unroll") for (int m = 0; m < 4; ++m) _Pragma("unroll") for (int n = 0; n < 2; ++n) _Pragma("unroll") for (int k = 0; k < 2; ++k) \
;         acc[ai][bj][m][n] = __builtin_amdgcn_mfma_f32_16x16x32_bf16(Bt[n][k], At[m][k], acc[ai][bj][m][n], 0, 0, 0); __builtin_amdgcn_s_setprio(0); } while (0)
; #define PG8_WAIT_V(n) asm volatile("s_waitcnt vmcnt(" #n ")" ::: "memory")
; #define PG8_WAIT_L(n) asm volatile("s_waitcnt lgkmcnt(" #n ")" ::: "memory")
; #define PG8_BAR __builtin_amdgcn_s_barrier()
; #define PG8_SCHED __builtin_amdgcn_sched_barrier(0)
; template <class Epi, class Sched, bool ALIGN_EPI = false, bool SP2 = false>
; __device__ __forceinline__ void gemm_phase(PG8_LAS unsigned char* lds, const Gemm g, const Sched& S, const Epi& E, const int wave_id) {
;     ...
;             PG8_WAIT_V(8); PG8_WAIT_L(0); PG8_BAR; PG8_MMA(0, 0, At, B0); PG8_MMA(0, 1, At, B1); PG8_BAR; PG8_SCHED;
;             PG8_LDA(At, 1, 1); PG8_STAGE(PG8_SB(1, 0), b3, voffB); PG8_STAGE(PG8_SB(1, 1), b3 + hstep, voffB); PG8_STAGE(PG8_SA(1, 0), a3, voffA);
;             PG8_WAIT_V(8); PG8_WAIT_L(0); PG8_BAR; PG8_MMA(1, 0, At, B0); PG8_MMA(1, 1, At, B1); PG8_BAR; PG8_SCHED;
.Lthird_wait_relaxed_6:
	s_waitcnt lgkmcnt(0)
	s_setprio 1
	s_barrier
	v_mfma_f32_16x16x32_bf16 v[126:129], v[130:133], v[162:165], v[126:129]
	v_mfma_f32_16x16x32_bf16 v[122:125], v[138:141], v[162:165], v[122:125]
	v_mfma_f32_16x16x32_bf16 v[118:121], v[130:133], v[170:173], v[118:121]
	v_mfma_f32_16x16x32_bf16 v[114:117], v[138:141], v[170:173], v[114:117]
	v_mfma_f32_16x16x32_bf16 v[94:97], v[130:133], v[178:181], v[94:97]
	v_mfma_f32_16x16x32_bf16 v[90:93], v[138:141], v[178:181], v[90:93]
	v_mfma_f32_16x16x32_bf16 v[86:89], v[130:133], v[186:189], v[86:89]
	v_mfma_f32_16x16x32_bf16 v[82:85], v[138:141], v[186:189], v[82:85]
	v_mfma_f32_16x16x32_bf16 v[126:129], v[134:137], v[166:169], v[126:129]
	v_mfma_f32_16x16x32_bf16 v[122:125], v[142:145], v[166:169], v[122:125]
	v_mfma_f32_16x16x32_bf16 v[118:121], v[134:137], v[174:177], v[118:121]
	v_mfma_f32_16x16x32_bf16 v[114:117], v[142:145], v[174:177], v[114:117]
	v_mfma_f32_16x16x32_bf16 v[94:97], v[134:137], v[182:185], v[94:97]
	v_mfma_f32_16x16x32_bf16 v[90:93], v[142:145], v[182:185], v[90:93]
	v_mfma_f32_16x16x32_bf16 v[86:89], v[134:137], v[190:193], v[86:89]
	v_mfma_f32_16x16x32_bf16 v[82:85], v[142:145], v[190:193], v[82:85]
	s_setprio 0
	s_setprio 1
	v_mfma_f32_16x16x32_bf16 v[110:113], v[146:149], v[162:165], v[110:113]
	v_mfma_f32_16x16x32_bf16 v[106:109], v[154:157], v[162:165], v[106:109]
	v_mfma_f32_16x16x32_bf16 v[102:105], v[146:149], v[170:173], v[102:105]
	v_mfma_f32_16x16x32_bf16 v[98:101], v[154:157], v[170:173], v[98:101]
	v_mfma_f32_16x16x32_bf16 v[78:81], v[146:149], v[178:181], v[78:81]
	v_mfma_f32_16x16x32_bf16 v[74:77], v[154:157], v[178:181], v[74:77]
	v_mfma_f32_16x16x32_bf16 v[70:73], v[146:149], v[186:189], v[70:73]
	v_mfma_f32_16x16x32_bf16 v[66:69], v[154:157], v[186:189], v[66:69]
	v_mfma_f32_16x16x32_bf16 v[110:113], v[150:153], v[166:169], v[110:113]
	v_mfma_f32_16x16x32_bf16 v[106:109], v[158:161], v[166:169], v[106:109]
	v_mfma_f32_16x16x32_bf16 v[102:105], v[150:153], v[174:177], v[102:105]
	v_mfma_f32_16x16x32_bf16 v[98:101], v[158:161], v[174:177], v[98:101]
	v_mfma_f32_16x16x32_bf16 v[78:81], v[150:153], v[182:185], v[78:81]
	v_mfma_f32_16x16x32_bf16 v[74:77], v[158:161], v[182:185], v[74:77]
	v_mfma_f32_16x16x32_bf16 v[70:73], v[150:153], v[190:193], v[70:73]
	v_mfma_f32_16x16x32_bf16 v[66:69], v[158:161], v[190:193], v[66:69]
	s_setprio 0
	s_barrier
	s_add_i32 s26, s28, s40
	v_lshl_add_u64 v[194:195], v[232:233], 0, s[64:65]
	s_mov_b32 m0, s26
	ds_read_b128 v[162:165], v249 offset:49152
	ds_read_b128 v[166:169], v249 offset:50176
	ds_read_b128 v[170:173], v249 offset:51200
	ds_read_b128 v[174:177], v249 offset:52224
	ds_read_b128 v[178:181], v249 offset:53248
	ds_read_b128 v[182:185], v249 offset:54272
	ds_read_b128 v[186:189], v249 offset:55296
	ds_read_b128 v[190:193], v249 offset:56320
	global_load_lds_dwordx4 v[194:195], off
	s_add_i32 m0, s26, 0x2000
	s_add_u32 s24, s24, 0x40080
	v_lshl_add_u64 v[194:195], v[230:231], 0, s[64:65]
	s_addc_u32 s25, s25, 0
	s_add_i32 s26, s29, s40
	global_load_lds_dwordx4 v[194:195], off
	v_lshl_add_u64 v[194:195], s[24:25], 0, v[212:213]
	s_mov_b32 m0, s26
	s_nop 0
	global_load_lds_dwordx4 v[194:195], off
	v_lshl_add_u64 v[194:195], s[24:25], 0, v[216:217]
	s_add_i32 m0, s26, 0x2000
	s_nop 0
	global_load_lds_dwordx4 v[194:195], off
	v_lshl_add_u64 v[194:195], v[226:227], 0, s[64:65]
	s_mov_b32 m0, s57
	s_nop 0
	global_load_lds_dwordx4 v[194:195], off
	v_lshl_add_u64 v[194:195], v[228:229], 0, s[64:65]
	s_mov_b32 m0, s62
	s_nop 0
	global_load_lds_dwordx4 v[194:195], off
	s_waitcnt vmcnt(8)
	s_waitcnt lgkmcnt(0)
	s_setprio 1
	s_barrier
	v_mfma_f32_16x16x32_bf16 v[62:65], v[130:133], v[162:165], v[62:65]
	v_mfma_f32_16x16x32_bf16 v[58:61], v[138:141], v[162:165], v[58:61]
	v_mfma_f32_16x16x32_bf16 v[54:57], v[130:133], v[170:173], v[54:57]
	v_mfma_f32_16x16x32_bf16 v[50:53], v[138:141], v[170:173], v[50:53]
	v_mfma_f32_16x16x32_bf16 v[30:33], v[130:133], v[178:181], v[30:33]
	v_mfma_f32_16x16x32_bf16 v[26:29], v[138:141], v[178:181], v[26:29]
	v_mfma_f32_16x16x32_bf16 v[22:25], v[130:133], v[186:189], v[22:25]
	v_mfma_f32_16x16x32_bf16 v[18:21], v[138:141], v[186:189], v[18:21]
	v_mfma_f32_16x16x32_bf16 v[62:65], v[134:137], v[166:169], v[62:65]
	v_mfma_f32_16x16x32_bf16 v[58:61], v[142:145], v[166:169], v[58:61]
	v_mfma_f32_16x16x32_bf16 v[54:57], v[134:137], v[174:177], v[54:57]
	v_mfma_f32_16x16x32_bf16 v[50:53], v[142:145], v[174:177], v[50:53]
	v_mfma_f32_16x16x32_bf16 v[30:33], v[134:137], v[182:185], v[30:33]
	v_mfma_f32_16x16x32_bf16 v[26:29], v[142:145], v[182:185], v[26:29]
	v_mfma_f32_16x16x32_bf16 v[22:25], v[134:137], v[190:193], v[22:25]
	v_mfma_f32_16x16x32_bf16 v[18:21], v[142:145], v[190:193], v[18:21]
	s_setprio 0
	s_setprio 1
	v_mfma_f32_16x16x32_bf16 v[46:49], v[146:149], v[162:165], v[46:49]
	v_mfma_f32_16x16x32_bf16 v[42:45], v[154:157], v[162:165], v[42:45]
	v_mfma_f32_16x16x32_bf16 v[38:41], v[146:149], v[170:173], v[38:41]
	v_mfma_f32_16x16x32_bf16 v[34:37], v[154:157], v[170:173], v[34:37]
	v_mfma_f32_16x16x32_bf16 v[14:17], v[146:149], v[178:181], v[14:17]
	v_mfma_f32_16x16x32_bf16 v[10:13], v[154:157], v[178:181], v[10:13]
	v_mfma_f32_16x16x32_bf16 v[6:9], v[146:149], v[186:189], v[6:9]
	v_mfma_f32_16x16x32_bf16 v[2:5], v[154:157], v[186:189], v[2:5]
	v_mfma_f32_16x16x32_bf16 v[46:49], v[150:153], v[166:169], v[46:49]
	v_mfma_f32_16x16x32_bf16 v[42:45], v[158:161], v[166:169], v[42:45]
	v_mfma_f32_16x16x32_bf16 v[38:41], v[150:153], v[174:177], v[38:41]
	v_mfma_f32_16x16x32_bf16 v[34:37], v[158:161], v[174:177], v[34:37]
	v_mfma_f32_16x16x32_bf16 v[14:17], v[150:153], v[182:185], v[14:17]
	v_mfma_f32_16x16x32_bf16 v[10:13], v[158:161], v[182:185], v[10:13]
	v_mfma_f32_16x16x32_bf16 v[6:9], v[150:153], v[190:193], v[6:9]
	v_mfma_f32_16x16x32_bf16 v[2:5], v[158:161], v[190:193], v[2:5]
	s_setprio 0
	s_barrier
	s_add_i32 s76, s76, 2
	s_add_u32 s22, s22, 0x100
	s_addc_u32 s23, s23, 0
	s_cmp_gt_u32 s76, 13
	s_cbranch_scc1 .LBB0_162

; #define PG8_STAGE(bufoff, gbase, voff) do { _Pragma("unroll") for (int _i = 0; _i < 2; ++_i) \
;         __builtin_amdgcn_global_load_lds((const unsigned*)((const char*)(gbase) + (voff)[_i]), (PG8_LAS unsigned*)(lds + (bufoff) + ldsw + _i * 8192), 16, 0, 0); } while (0)
; #define PG8_LDA(dst, b, h) do { _Pragma("unroll") for (int m = 0; m < 4; ++m) _Pragma("unroll") for (int k = 0; k < 2; ++k) dst[m][k] = *(const PG8_LAS bf16x8*)(lds + PG8_SA(b, h) + aoff + m * 2048 + k * 1024); } while (0)
; #define PG8_MMA(ai, bj, At, Bt) do { __builtin_amdgcn_s_setprio(1); _Pragma("unroll") for (int m = 0; m < 4; ++m) _Pragma("unroll") for (int n = 0; n < 2; ++n) _Pragma("unroll") for (int k = 0; k < 2; ++k) \
;         acc[ai][bj][m][n] = __builtin_amdgcn_mfma_f32_16x16x32_bf16(Bt[n][k], At[m][k], acc[ai][bj][m][n], 0, 0, 0); __builtin_amdgcn_s_setprio(0); } while (0)
; #define PG8_WAIT_V(n) asm volatile("s_waitcnt vmcnt(" #n ")" ::: "memory")
; #define PG8_WAIT_VN(n) asm volatile("s_waitcnt vmcnt(%0)" :: "n"(n) : "memory")
; #define PG8_WAIT_L(n) asm volatile("s_waitcnt lgkmcnt(" #n ")" ::: "memory")
; #define PG8_BAR __builtin_amdgcn_s_barrier()
; #define PG8_SCHED __builtin_amdgcn_sched_barrier(0)
; template <class Epi, class Sched, bool ALIGN_EPI = false, bool SP2 = false>
; __device__ __forceinline__ void gemm_phase(PG8_LAS unsigned char* lds, const Gemm g, const Sched& S, const Epi& E, const int wave_id) {
;     ...
;         for (int t = 0; t < nt; t += 2) {
;             const bool last = (t == nt - 2);
;             const char* a1 = cA + (size_t)(t + 1) * kstep;
;             const char* a2 = last ? nA : cA + (size_t)(t + 2) * kstep; const char* b2 = last ? nB : cB + (size_t)(t + 2) * kstep;
;             const char* a3 = a2 + kstep; const char* b3 = b2 + kstep;
;     ...
;             PG8_WAIT_VN(8 + Epi::NS); if (strict) PG8_WAIT_V(8); PG8_WAIT_L(0); PG8_BAR; PG8_MMA(0, 0, At, B0); PG8_MMA(0, 1, At, B1); PG8_BAR; PG8_SCHED;
;             PG8_LDA(At, 0, 1); PG8_STAGE(PG8_SB(0, 0), b2, voffB); PG8_STAGE(PG8_SB(0, 1), b2 + hstep, voffB); PG8_STAGE(PG8_SA(0, 0), a2, voffA);
;             PG8_WAIT_VN(8 + Epi::NS); if (strict) PG8_WAIT_V(8); PG8_WAIT_L(0); PG8_BAR; PG8_MMA(1, 0, At, B0); PG8_MMA(1, 1, At, B1); PG8_BAR; PG8_SCHED;
.LBB0_160:
	s_add_u32 s24, s20, s22
	s_addc_u32 s25, s21, s23
	s_add_u32 s24, s24, 0x100
	s_addc_u32 s25, s25, 0
	s_add_u32 s53, s74, s22
	s_addc_u32 s78, s75, s23
	s_cmpk_eq_i32 s22, 0x700
	s_cselect_b32 s27, s13, s25
	s_cselect_b32 s26, s68, s24
	s_cselect_b32 s25, s11, s78
	s_cselect_b32 s24, s69, s53
	s_waitcnt lgkmcnt(0)
	s_setprio 1
	s_barrier
	v_mfma_f32_16x16x32_bf16 v[126:129], v[146:149], v[186:189], v[126:129]
	v_mfma_f32_16x16x32_bf16 v[122:125], v[154:157], v[186:189], v[122:125]
	v_mfma_f32_16x16x32_bf16 v[118:121], v[146:149], v[178:181], v[118:121]
	v_mfma_f32_16x16x32_bf16 v[114:117], v[154:157], v[178:181], v[114:117]
	v_mfma_f32_16x16x32_bf16 v[94:97], v[146:149], v[170:173], v[94:97]
	v_mfma_f32_16x16x32_bf16 v[90:93], v[154:157], v[170:173], v[90:93]
	v_mfma_f32_16x16x32_bf16 v[86:89], v[146:149], v[162:165], v[86:89]
	v_mfma_f32_16x16x32_bf16 v[82:85], v[154:157], v[162:165], v[82:85]
	v_mfma_f32_16x16x32_bf16 v[126:129], v[150:153], v[190:193], v[126:129]
	v_mfma_f32_16x16x32_bf16 v[122:125], v[158:161], v[190:193], v[122:125]
	v_mfma_f32_16x16x32_bf16 v[118:121], v[150:153], v[182:185], v[118:121]
	v_mfma_f32_16x16x32_bf16 v[114:117], v[158:161], v[182:185], v[114:117]
	v_mfma_f32_16x16x32_bf16 v[94:97], v[150:153], v[174:177], v[94:97]
	v_mfma_f32_16x16x32_bf16 v[90:93], v[158:161], v[174:177], v[90:93]
	v_mfma_f32_16x16x32_bf16 v[86:89], v[150:153], v[166:169], v[86:89]
	v_mfma_f32_16x16x32_bf16 v[82:85], v[158:161], v[166:169], v[82:85]
	s_setprio 0
	s_setprio 1
	v_mfma_f32_16x16x32_bf16 v[110:113], v[130:133], v[186:189], v[110:113]
	v_mfma_f32_16x16x32_bf16 v[106:109], v[138:141], v[186:189], v[106:109]
	v_mfma_f32_16x16x32_bf16 v[102:105], v[130:133], v[178:181], v[102:105]
	v_mfma_f32_16x16x32_bf16 v[98:101], v[138:141], v[178:181], v[98:101]
	v_mfma_f32_16x16x32_bf16 v[78:81], v[130:133], v[170:173], v[78:81]
	v_mfma_f32_16x16x32_bf16 v[74:77], v[138:141], v[170:173], v[74:77]
	v_mfma_f32_16x16x32_bf16 v[70:73], v[130:133], v[162:165], v[70:73]
	v_mfma_f32_16x16x32_bf16 v[66:69], v[138:141], v[162:165], v[66:69]
	v_mfma_f32_16x16x32_bf16 v[110:113], v[134:137], v[190:193], v[110:113]
	v_mfma_f32_16x16x32_bf16 v[106:109], v[142:145], v[190:193], v[106:109]
	v_mfma_f32_16x16x32_bf16 v[102:105], v[134:137], v[182:185], v[102:105]
	v_mfma_f32_16x16x32_bf16 v[98:101], v[142:145], v[182:185], v[98:101]
	v_mfma_f32_16x16x32_bf16 v[78:81], v[134:137], v[174:177], v[78:81]
	v_mfma_f32_16x16x32_bf16 v[74:77], v[142:145], v[174:177], v[74:77]
	v_mfma_f32_16x16x32_bf16 v[70:73], v[134:137], v[166:169], v[70:73]
	v_mfma_f32_16x16x32_bf16 v[66:69], v[142:145], v[166:169], v[66:69]
	s_setprio 0
	s_barrier
	s_mov_b32 m0, s42
	v_lshl_add_u64 v[232:233], s[24:25], 0, v[212:213]
	s_add_u32 s90, s24, 0x40000
	ds_read_b128 v[186:189], v249 offset:16384
	ds_read_b128 v[190:193], v249 offset:17408
	ds_read_b128 v[178:181], v249 offset:18432
	ds_read_b128 v[182:185], v249 offset:19456
	ds_read_b128 v[170:173], v249 offset:20480
	ds_read_b128 v[174:177], v249 offset:21504
	ds_read_b128 v[162:165], v249 offset:22528
	ds_read_b128 v[166:169], v249 offset:23552
	global_load_lds_dwordx4 v[232:233], off
	v_lshl_add_u64 v[230:231], s[24:25], 0, v[216:217]
	s_mov_b32 m0, s43
	s_addc_u32 s91, s25, 0
	global_load_lds_dwordx4 v[230:231], off
	v_lshl_add_u64 v[194:195], s[90:91], 0, v[212:213]
	s_mov_b32 m0, s49
	v_lshl_add_u64 v[226:227], s[26:27], 0, v[210:211]
	global_load_lds_dwordx4 v[194:195], off
	v_lshl_add_u64 v[194:195], s[90:91], 0, v[216:217]
	s_mov_b32 m0, s50
	v_lshl_add_u64 v[228:229], s[26:27], 0, v[214:215]
	global_load_lds_dwordx4 v[194:195], off
	s_mov_b32 m0, s41
	s_andn2_b64 vcc, exec, s[28:29]
	global_load_lds_dwordx4 v[226:227], off
	s_mov_b32 m0, s51
	s_nop 0
	global_load_lds_dwordx4 v[228:229], off
	s_waitcnt vmcnt(16)
	s_cbranch_vccnz .LBB0_157
	s_waitcnt vmcnt(8)
	s_branch .LBB0_157

; #define PG8_STAGE(bufoff, gbase, voff) do { _Pragma("unroll") for (int _i = 0; _i < 2; ++_i) \
;         __builtin_amdgcn_global_load_lds((const unsigned*)((const char*)(gbase) + (voff)[_i]), (PG8_LAS unsigned*)(lds + (bufoff) + ldsw + _i * 8192), 16, 0, 0); } while (0)
; #define PG8_LDA(dst, b, h) do { _Pragma("unroll") for (int m = 0; m < 4; ++m) _Pragma("unroll") for (int k = 0; k < 2; ++k) dst[m][k] = *(const PG8_LAS bf16x8*)(lds + PG8_SA(b, h) + aoff + m * 2048 + k * 1024); } while (0)
; #define PG8_LDB(dst, b, h) do { _Pragma("unroll") for (int n = 0; n < 2; ++n) _Pragma("unroll") for (int k = 0; k < 2; ++k) dst[n][k] = *(const PG8_LAS bf16x8*)(lds + PG8_SB(b, h) + boff + n * 2048 + k * 1024); } while (0)
; #define PG8_MMA(ai, bj, At, Bt) do { __builtin_amdgcn_s_setprio(1); _Pragma("unroll") for (int m = 0; m < 4; ++m) _Pragma("unroll") for (int n = 0; n < 2; ++n) _Pragma("unroll") for (int k = 0; k < 2; ++k) \
;         acc[ai][bj][m][n] = __builtin_amdgcn_mfma_f32_16x16x32_bf16(Bt[n][k], At[m][k], acc[ai][bj][m][n], 0, 0, 0); __builtin_amdgcn_s_setprio(0); } while (0)
; #define PG8_WAIT_V(n) asm volatile("s_waitcnt vmcnt(" #n ")" ::: "memory")
; #define PG8_WAIT_VN(n) asm volatile("s_waitcnt vmcnt(%0)" :: "n"(n) : "memory")
; #define PG8_WAIT_L(n) asm volatile("s_waitcnt lgkmcnt(" #n ")" ::: "memory")
; #define PG8_BAR __builtin_amdgcn_s_barrier()
; #define PG8_SCHED __builtin_amdgcn_sched_barrier(0)
; template <class Epi, class Sched, bool ALIGN_EPI = false, bool SP2 = false>
; __device__ __forceinline__ void gemm_phase(PG8_LAS unsigned char* lds, const Gemm g, const Sched& S, const Epi& E, const int wave_id) {
;     ...
;             PG8_WAIT_VN(8 + Epi::NS); if (strict) PG8_WAIT_V(8); PG8_WAIT_L(0); PG8_BAR; PG8_MMA(1, 0, At, B0); PG8_MMA(1, 1, At, B1); PG8_BAR; PG8_SCHED;
;             PG8_LDB(B0, 1, 0); PG8_LDB(B1, 1, 1); PG8_SCHED; PG8_LDA(At, 1, 0); PG8_STAGE(PG8_SA(0, 1), a2 + hstep, voffA);
;             PG8_WAIT_V(8); PG8_WAIT_L(0); PG8_BAR; PG8_MMA(0, 0, At, B0); PG8_MMA(0, 1, At, B1); PG8_BAR; PG8_SCHED;
.LBB0_235:
	s_waitcnt lgkmcnt(0)
	s_setprio 1
	s_barrier
	v_mfma_f32_16x16x32_bf16 v[62:65], v[146:149], v[186:189], v[62:65]
	v_mfma_f32_16x16x32_bf16 v[58:61], v[154:157], v[186:189], v[58:61]
	v_mfma_f32_16x16x32_bf16 v[46:49], v[146:149], v[178:181], v[46:49]
	v_mfma_f32_16x16x32_bf16 v[42:45], v[154:157], v[178:181], v[42:45]
	v_mfma_f32_16x16x32_bf16 v[30:33], v[146:149], v[170:173], v[30:33]
	v_mfma_f32_16x16x32_bf16 v[26:29], v[154:157], v[170:173], v[26:29]
	v_mfma_f32_16x16x32_bf16 v[14:17], v[146:149], v[162:165], v[14:17]
	v_mfma_f32_16x16x32_bf16 v[10:13], v[154:157], v[162:165], v[10:13]
	v_mfma_f32_16x16x32_bf16 v[62:65], v[150:153], v[190:193], v[62:65]
	v_mfma_f32_16x16x32_bf16 v[58:61], v[158:161], v[190:193], v[58:61]
	v_mfma_f32_16x16x32_bf16 v[46:49], v[150:153], v[182:185], v[46:49]
	v_mfma_f32_16x16x32_bf16 v[42:45], v[158:161], v[182:185], v[42:45]
	v_mfma_f32_16x16x32_bf16 v[30:33], v[150:153], v[174:177], v[30:33]
	v_mfma_f32_16x16x32_bf16 v[26:29], v[158:161], v[174:177], v[26:29]
	v_mfma_f32_16x16x32_bf16 v[14:17], v[150:153], v[166:169], v[14:17]
	v_mfma_f32_16x16x32_bf16 v[10:13], v[158:161], v[166:169], v[10:13]
	s_setprio 0
	s_setprio 1
	v_mfma_f32_16x16x32_bf16 v[54:57], v[130:133], v[186:189], v[54:57]
	v_mfma_f32_16x16x32_bf16 v[50:53], v[138:141], v[186:189], v[50:53]
	v_mfma_f32_16x16x32_bf16 v[38:41], v[130:133], v[178:181], v[38:41]
	v_mfma_f32_16x16x32_bf16 v[34:37], v[138:141], v[178:181], v[34:37]
	v_mfma_f32_16x16x32_bf16 v[22:25], v[130:133], v[170:173], v[22:25]
	v_mfma_f32_16x16x32_bf16 v[18:21], v[138:141], v[170:173], v[18:21]
	v_mfma_f32_16x16x32_bf16 v[6:9], v[130:133], v[162:165], v[6:9]
	v_mfma_f32_16x16x32_bf16 v[2:5], v[138:141], v[162:165], v[2:5]
	v_mfma_f32_16x16x32_bf16 v[54:57], v[134:137], v[190:193], v[54:57]
	v_mfma_f32_16x16x32_bf16 v[50:53], v[142:145], v[190:193], v[50:53]
	v_mfma_f32_16x16x32_bf16 v[38:41], v[134:137], v[182:185], v[38:41]
	v_mfma_f32_16x16x32_bf16 v[34:37], v[142:145], v[182:185], v[34:37]
	v_mfma_f32_16x16x32_bf16 v[22:25], v[134:137], v[174:177], v[22:25]
	v_mfma_f32_16x16x32_bf16 v[18:21], v[142:145], v[174:177], v[18:21]
	v_mfma_f32_16x16x32_bf16 v[6:9], v[134:137], v[166:169], v[6:9]
	v_mfma_f32_16x16x32_bf16 v[2:5], v[142:145], v[166:169], v[2:5]
	s_setprio 0
	s_barrier
	s_add_i32 s20, 0, 0x18000
	s_add_i32 s21, 0, 0x1c000
	v_add_u32_e32 v142, s20, v246
	v_add_u32_e32 v158, s21, v246
	ds_read_b128 v[130:133], v142
	ds_read_b128 v[134:137], v142 offset:1024
	ds_read_b128 v[138:141], v142 offset:2048
	ds_read_b128 v[142:145], v142 offset:3072
	ds_read_b128 v[146:149], v158
	ds_read_b128 v[150:153], v158 offset:1024
	ds_read_b128 v[154:157], v158 offset:2048
	ds_read_b128 v[158:161], v158 offset:3072
	s_add_u32 s18, s18, 0xb0000
	s_addc_u32 s19, s19, 0
	s_mov_b32 m0, s39
	v_lshl_add_u64 v[194:195], s[18:19], 0, v[210:211]
	ds_read_b128 v[162:165], v247 offset:32768
	ds_read_b128 v[166:169], v247 offset:33792
	ds_read_b128 v[170:173], v247 offset:34816
	ds_read_b128 v[174:177], v247 offset:35840
	ds_read_b128 v[178:181], v247 offset:36864
	ds_read_b128 v[182:185], v247 offset:37888
	ds_read_b128 v[186:189], v247 offset:38912
	ds_read_b128 v[190:193], v247 offset:39936
	global_load_lds_dwordx4 v[194:195], off
	v_lshl_add_u64 v[194:195], s[18:19], 0, v[214:215]
	s_mov_b32 m0, s40
	s_nop 0
	global_load_lds_dwordx4 v[194:195], off
	s_waitcnt vmcnt(26)
	s_cmp_eq_u32 s100, 0
	s_cbranch_scc1 .Lthird_wait_relaxed_5
	s_waitcnt vmcnt(8)
; #define PG8_STAGE(bufoff, gbase, voff) do { _Pragma("unroll") for (int _i = 0; _i < 2; ++_i) \
;         __builtin_amdgcn_global_load_lds((const unsigned*)((const char*)(gbase) + (voff)[_i]), (PG8_LAS unsigned*)(lds + (bufoff) + ldsw + _i * 8192), 16, 0, 0); } while (0)
; #define PG8_LDA(dst, b, h) do { _Pragma("unroll") for (int m = 0; m < 4; ++m) _Pragma("unroll") for (int k = 0; k < 2; ++k) dst[m][k] = *(const PG8_LAS bf16x8*)(lds + PG8_SA(b, h) + aoff + m * 2048 + k * 1024); } while (0)
; #define PG8_MMA(ai, bj, At, Bt) do { __builtin_amdgcn_s_setprio(1); _Pragma("unroll") for (int m = 0; m < 4; ++m) _Pragma("unroll") for (int n = 0; n < 2; ++n) _Pragma("unroll") for (int k = 0; k < 2; ++k) \
;         acc[ai][bj][m][n] = __builtin_amdgcn_mfma_f32_16x16x32_bf16(Bt[n][k], At[m][k], acc[ai][bj][m][n], 0, 0, 0); __builtin_amdgcn_s_setprio(0); } while (0)
; #define PG8_WAIT_V(n) asm volatile("s_waitcnt vmcnt(" #n ")" ::: "memory")
; #define PG8_WAIT_L(n) asm volatile("s_waitcnt lgkmcnt(" #n ")" ::: "memory")
; #define PG8_BAR __builtin_amdgcn_s_barrier()
; #define PG8_SCHED __builtin_amdgcn_sched_barrier(0)
; template <class Epi, class Sched, bool ALIGN_EPI = false, bool SP2 = false>
; __device__ __forceinline__ void gemm_phase(PG8_LAS unsigned char* lds, const Gemm g, const Sched& S, const Epi& E, const int wave_id) {
;     ...
;             PG8_WAIT_V(8); PG8_WAIT_L(0); PG8_BAR; PG8_MMA(0, 0, At, B0); PG8_MMA(0, 1, At, B1); PG8_BAR; PG8_SCHED;
;             PG8_LDA(At, 1, 1); PG8_STAGE(PG8_SB(1, 0), b3, voffB); PG8_STAGE(PG8_SB(1, 1), b3 + hstep, voffB); PG8_STAGE(PG8_SA(1, 0), a3, voffA);
;             PG8_WAIT_V(8); PG8_WAIT_L(0); PG8_BAR; PG8_MMA(1, 0, At, B0); PG8_MMA(1, 1, At, B1); PG8_BAR; PG8_SCHED;
.Lthird_wait_relaxed_5:
	s_waitcnt lgkmcnt(0)
	s_setprio 1
	s_barrier
	v_mfma_f32_16x16x32_bf16 v[126:129], v[130:133], v[162:165], v[126:129]
	v_mfma_f32_16x16x32_bf16 v[122:125], v[138:141], v[162:165], v[122:125]
	v_mfma_f32_16x16x32_bf16 v[110:113], v[130:133], v[170:173], v[110:113]
	v_mfma_f32_16x16x32_bf16 v[106:109], v[138:141], v[170:173], v[106:109]
	v_mfma_f32_16x16x32_bf16 v[94:97], v[130:133], v[178:181], v[94:97]
	v_mfma_f32_16x16x32_bf16 v[90:93], v[138:141], v[178:181], v[90:93]
	v_mfma_f32_16x16x32_bf16 v[78:81], v[130:133], v[186:189], v[78:81]
	v_mfma_f32_16x16x32_bf16 v[74:77], v[138:141], v[186:189], v[74:77]
	v_mfma_f32_16x16x32_bf16 v[126:129], v[134:137], v[166:169], v[126:129]
	v_mfma_f32_16x16x32_bf16 v[122:125], v[142:145], v[166:169], v[122:125]
	v_mfma_f32_16x16x32_bf16 v[110:113], v[134:137], v[174:177], v[110:113]
	v_mfma_f32_16x16x32_bf16 v[106:109], v[142:145], v[174:177], v[106:109]
	v_mfma_f32_16x16x32_bf16 v[94:97], v[134:137], v[182:185], v[94:97]
	v_mfma_f32_16x16x32_bf16 v[90:93], v[142:145], v[182:185], v[90:93]
	v_mfma_f32_16x16x32_bf16 v[78:81], v[134:137], v[190:193], v[78:81]
	v_mfma_f32_16x16x32_bf16 v[74:77], v[142:145], v[190:193], v[74:77]
	s_setprio 0
	s_setprio 1
	v_mfma_f32_16x16x32_bf16 v[118:121], v[146:149], v[162:165], v[118:121]
	v_mfma_f32_16x16x32_bf16 v[114:117], v[154:157], v[162:165], v[114:117]
	v_mfma_f32_16x16x32_bf16 v[102:105], v[146:149], v[170:173], v[102:105]
	v_mfma_f32_16x16x32_bf16 v[98:101], v[154:157], v[170:173], v[98:101]
	v_mfma_f32_16x16x32_bf16 v[86:89], v[146:149], v[178:181], v[86:89]
	v_mfma_f32_16x16x32_bf16 v[82:85], v[154:157], v[178:181], v[82:85]
	v_mfma_f32_16x16x32_bf16 v[70:73], v[146:149], v[186:189], v[70:73]
	v_mfma_f32_16x16x32_bf16 v[66:69], v[154:157], v[186:189], v[66:69]
	v_mfma_f32_16x16x32_bf16 v[118:121], v[150:153], v[166:169], v[118:121]
	v_mfma_f32_16x16x32_bf16 v[114:117], v[158:161], v[166:169], v[114:117]
	v_mfma_f32_16x16x32_bf16 v[102:105], v[150:153], v[174:177], v[102:105]
	v_mfma_f32_16x16x32_bf16 v[98:101], v[158:161], v[174:177], v[98:101]
	v_mfma_f32_16x16x32_bf16 v[86:89], v[150:153], v[182:185], v[86:89]
	v_mfma_f32_16x16x32_bf16 v[82:85], v[158:161], v[182:185], v[82:85]
	v_mfma_f32_16x16x32_bf16 v[70:73], v[150:153], v[190:193], v[70:73]
	v_mfma_f32_16x16x32_bf16 v[66:69], v[158:161], v[190:193], v[66:69]
	s_setprio 0
	s_barrier
	s_add_i32 s18, s20, s30
	v_lshl_add_u64 v[194:195], v[232:233], 0, s[64:65]
	s_mov_b32 m0, s18
	ds_read_b128 v[162:165], v247 offset:49152
	ds_read_b128 v[166:169], v247 offset:50176
	ds_read_b128 v[170:173], v247 offset:51200
	ds_read_b128 v[174:177], v247 offset:52224
	ds_read_b128 v[178:181], v247 offset:53248
	ds_read_b128 v[182:185], v247 offset:54272
	ds_read_b128 v[186:189], v247 offset:55296
	ds_read_b128 v[190:193], v247 offset:56320
	global_load_lds_dwordx4 v[194:195], off
	s_add_i32 m0, s18, 0x2000
	s_add_u32 s16, s16, 0xb0080
	v_lshl_add_u64 v[194:195], v[230:231], 0, s[64:65]
	s_addc_u32 s17, s17, 0
	s_add_i32 s18, s21, s30
	global_load_lds_dwordx4 v[194:195], off
	v_lshl_add_u64 v[194:195], s[16:17], 0, v[212:213]
	s_mov_b32 m0, s18
	s_nop 0
	global_load_lds_dwordx4 v[194:195], off
	v_lshl_add_u64 v[194:195], s[16:17], 0, v[216:217]
	s_add_i32 m0, s18, 0x2000
	s_nop 0
	global_load_lds_dwordx4 v[194:195], off
	v_lshl_add_u64 v[194:195], v[226:227], 0, s[64:65]
	s_mov_b32 m0, s42
	s_nop 0
	global_load_lds_dwordx4 v[194:195], off
	v_lshl_add_u64 v[194:195], v[228:229], 0, s[64:65]
	s_mov_b32 m0, s43
	s_nop 0
	global_load_lds_dwordx4 v[194:195], off
	s_waitcnt vmcnt(8)
	s_waitcnt lgkmcnt(0)
	s_setprio 1
	s_barrier
	v_mfma_f32_16x16x32_bf16 v[62:65], v[130:133], v[162:165], v[62:65]
	v_mfma_f32_16x16x32_bf16 v[58:61], v[138:141], v[162:165], v[58:61]
	v_mfma_f32_16x16x32_bf16 v[46:49], v[130:133], v[170:173], v[46:49]
	v_mfma_f32_16x16x32_bf16 v[42:45], v[138:141], v[170:173], v[42:45]
	v_mfma_f32_16x16x32_bf16 v[30:33], v[130:133], v[178:181], v[30:33]
	v_mfma_f32_16x16x32_bf16 v[26:29], v[138:141], v[178:181], v[26:29]
	v_mfma_f32_16x16x32_bf16 v[14:17], v[130:133], v[186:189], v[14:17]
	v_mfma_f32_16x16x32_bf16 v[10:13], v[138:141], v[186:189], v[10:13]
	v_mfma_f32_16x16x32_bf16 v[62:65], v[134:137], v[166:169], v[62:65]
	v_mfma_f32_16x16x32_bf16 v[58:61], v[142:145], v[166:169], v[58:61]
	v_mfma_f32_16x16x32_bf16 v[46:49], v[134:137], v[174:177], v[46:49]
	v_mfma_f32_16x16x32_bf16 v[42:45], v[142:145], v[174:177], v[42:45]
	v_mfma_f32_16x16x32_bf16 v[30:33], v[134:137], v[182:185], v[30:33]
	v_mfma_f32_16x16x32_bf16 v[26:29], v[142:145], v[182:185], v[26:29]
	v_mfma_f32_16x16x32_bf16 v[14:17], v[134:137], v[190:193], v[14:17]
	v_mfma_f32_16x16x32_bf16 v[10:13], v[142:145], v[190:193], v[10:13]
	s_setprio 0
	s_setprio 1
	v_mfma_f32_16x16x32_bf16 v[54:57], v[146:149], v[162:165], v[54:57]
	v_mfma_f32_16x16x32_bf16 v[50:53], v[154:157], v[162:165], v[50:53]
	v_mfma_f32_16x16x32_bf16 v[38:41], v[146:149], v[170:173], v[38:41]
	v_mfma_f32_16x16x32_bf16 v[34:37], v[154:157], v[170:173], v[34:37]
	v_mfma_f32_16x16x32_bf16 v[22:25], v[146:149], v[178:181], v[22:25]
	v_mfma_f32_16x16x32_bf16 v[18:21], v[154:157], v[178:181], v[18:21]
	v_mfma_f32_16x16x32_bf16 v[6:9], v[146:149], v[186:189], v[6:9]
	v_mfma_f32_16x16x32_bf16 v[2:5], v[154:157], v[186:189], v[2:5]
	v_mfma_f32_16x16x32_bf16 v[54:57], v[150:153], v[166:169], v[54:57]
	v_mfma_f32_16x16x32_bf16 v[50:53], v[158:161], v[166:169], v[50:53]
	v_mfma_f32_16x16x32_bf16 v[38:41], v[150:153], v[174:177], v[38:41]
	v_mfma_f32_16x16x32_bf16 v[34:37], v[158:161], v[174:177], v[34:37]
	v_mfma_f32_16x16x32_bf16 v[22:25], v[150:153], v[182:185], v[22:25]
	v_mfma_f32_16x16x32_bf16 v[18:21], v[158:161], v[182:185], v[18:21]
	v_mfma_f32_16x16x32_bf16 v[6:9], v[150:153], v[190:193], v[6:9]
	v_mfma_f32_16x16x32_bf16 v[2:5], v[158:161], v[190:193], v[2:5]
	s_setprio 0
	s_barrier
	s_add_i32 s63, s63, 2
	s_add_u32 s14, s14, 0x100
	s_addc_u32 s15, s15, 0
	s_cmp_gt_u32 s63, 41
	s_cbranch_scc1 .LBB0_240

; #define PG8_STAGE(bufoff, gbase, voff) do { _Pragma("unroll") for (int _i = 0; _i < 2; ++_i) \
;         __builtin_amdgcn_global_load_lds((const unsigned*)((const char*)(gbase) + (voff)[_i]), (PG8_LAS unsigned*)(lds + (bufoff) + ldsw + _i * 8192), 16, 0, 0); } while (0)
; #define PG8_LDA(dst, b, h) do { _Pragma("unroll") for (int m = 0; m < 4; ++m) _Pragma("unroll") for (int k = 0; k < 2; ++k) dst[m][k] = *(const PG8_LAS bf16x8*)(lds + PG8_SA(b, h) + aoff + m * 2048 + k * 1024); } while (0)
; #define PG8_LDB(dst, b, h) do { _Pragma("unroll") for (int n = 0; n < 2; ++n) _Pragma("unroll") for (int k = 0; k < 2; ++k) dst[n][k] = *(const PG8_LAS bf16x8*)(lds + PG8_SB(b, h) + boff + n * 2048 + k * 1024); } while (0)
; #define PG8_WAIT_V(n) asm volatile("s_waitcnt vmcnt(" #n ")" ::: "memory")
; #define PG8_WAIT_VN(n) asm volatile("s_waitcnt vmcnt(%0)" :: "n"(n) : "memory")
; #define PG8_WAIT_L(n) asm volatile("s_waitcnt lgkmcnt(" #n ")" ::: "memory")
; #define PG8_BAR __builtin_amdgcn_s_barrier()
; template <class Epi, class Sched, bool ALIGN_EPI = false, bool SP2 = false>
; __device__ __forceinline__ void gemm_phase(PG8_LAS unsigned char* lds, const Gemm g, const Sched& S, const Epi& E, const int wave_id) {
;     ...
;             const bool last = (t == nt - 2);
;             const char* a1 = cA + (size_t)(t + 1) * kstep;
;             const char* a2 = last ? nA : cA + (size_t)(t + 2) * kstep; const char* b2 = last ? nB : cB + (size_t)(t + 2) * kstep;
;             const char* a3 = a2 + kstep; const char* b3 = b2 + kstep;
;             if (last && has_next) S.a_ready(nxt);
;             if constexpr (SP2) {
;             int tz_ = __builtin_amdgcn_readfirstlane(t | (ui > 0 ? 0 : 1)); asm volatile("" : "+s"(tz_));
;             const bool strict = !(Epi::NS > 0 && tz_ == 0);
;             PG8_LDB(B0, 0, 0); PG8_LDB(B1, 0, 1); PG8_SCHED; PG8_LDA(At, 0, 0); PG8_STAGE(PG8_SA(1, 1), a1 + hstep, voffA);
;             PG8_WAIT_VN(8 + Epi::NS); if (strict) PG8_WAIT_V(8); PG8_WAIT_L(0); PG8_BAR; PG8_MMA(0, 0, At, B0); PG8_MMA(0, 1, At, B1); PG8_BAR; PG8_SCHED;
;             PG8_LDA(At, 0, 1); PG8_STAGE(PG8_SB(0, 0), b2, voffB); PG8_STAGE(PG8_SB(0, 1), b2 + hstep, voffB); PG8_STAGE(PG8_SA(0, 0), a2, voffA);
;             PG8_WAIT_VN(8 + Epi::NS); if (strict) PG8_WAIT_V(8); PG8_WAIT_L(0); PG8_BAR; PG8_MMA(1, 0, At, B0); PG8_MMA(1, 1, At, B1); PG8_BAR; PG8_SCHED;
.LBB0_238:
	s_add_u32 s16, s12, s14
	s_addc_u32 s17, s13, s15
	s_add_u32 s16, s16, 0x100
	s_addc_u32 s17, s17, 0
	s_add_u32 s53, s57, s14
	s_addc_u32 s67, s62, s15
	s_cmpk_eq_i32 s14, 0x1500
	s_cselect_b32 s19, s7, s17
	s_cselect_b32 s18, s6, s16
	s_cselect_b32 s17, s11, s67
	s_cselect_b32 s16, s10, s53
	s_waitcnt lgkmcnt(0)
	s_setprio 1
	s_barrier
	v_mfma_f32_16x16x32_bf16 v[126:129], v[146:149], v[186:189], v[126:129]
	v_mfma_f32_16x16x32_bf16 v[122:125], v[154:157], v[186:189], v[122:125]
	v_mfma_f32_16x16x32_bf16 v[110:113], v[146:149], v[178:181], v[110:113]
	v_mfma_f32_16x16x32_bf16 v[106:109], v[154:157], v[178:181], v[106:109]
	v_mfma_f32_16x16x32_bf16 v[94:97], v[146:149], v[170:173], v[94:97]
	v_mfma_f32_16x16x32_bf16 v[90:93], v[154:157], v[170:173], v[90:93]
	v_mfma_f32_16x16x32_bf16 v[78:81], v[146:149], v[162:165], v[78:81]
	v_mfma_f32_16x16x32_bf16 v[74:77], v[154:157], v[162:165], v[74:77]
	v_mfma_f32_16x16x32_bf16 v[126:129], v[150:153], v[190:193], v[126:129]
	v_mfma_f32_16x16x32_bf16 v[122:125], v[158:161], v[190:193], v[122:125]
	v_mfma_f32_16x16x32_bf16 v[110:113], v[150:153], v[182:185], v[110:113]
	v_mfma_f32_16x16x32_bf16 v[106:109], v[158:161], v[182:185], v[106:109]
	v_mfma_f32_16x16x32_bf16 v[94:97], v[150:153], v[174:177], v[94:97]
	v_mfma_f32_16x16x32_bf16 v[90:93], v[158:161], v[174:177], v[90:93]
	v_mfma_f32_16x16x32_bf16 v[78:81], v[150:153], v[166:169], v[78:81]
	v_mfma_f32_16x16x32_bf16 v[74:77], v[158:161], v[166:169], v[74:77]
	s_setprio 0
	s_setprio 1
	v_mfma_f32_16x16x32_bf16 v[118:121], v[130:133], v[186:189], v[118:121]
	v_mfma_f32_16x16x32_bf16 v[114:117], v[138:141], v[186:189], v[114:117]
	v_mfma_f32_16x16x32_bf16 v[102:105], v[130:133], v[178:181], v[102:105]
	v_mfma_f32_16x16x32_bf16 v[98:101], v[138:141], v[178:181], v[98:101]
	v_mfma_f32_16x16x32_bf16 v[86:89], v[130:133], v[170:173], v[86:89]
	v_mfma_f32_16x16x32_bf16 v[82:85], v[138:141], v[170:173], v[82:85]
	v_mfma_f32_16x16x32_bf16 v[70:73], v[130:133], v[162:165], v[70:73]
	v_mfma_f32_16x16x32_bf16 v[66:69], v[138:141], v[162:165], v[66:69]
	v_mfma_f32_16x16x32_bf16 v[118:121], v[134:137], v[190:193], v[118:121]
	v_mfma_f32_16x16x32_bf16 v[114:117], v[142:145], v[190:193], v[114:117]
	v_mfma_f32_16x16x32_bf16 v[102:105], v[134:137], v[182:185], v[102:105]
	v_mfma_f32_16x16x32_bf16 v[98:101], v[142:145], v[182:185], v[98:101]
	v_mfma_f32_16x16x32_bf16 v[86:89], v[134:137], v[174:177], v[86:89]
	v_mfma_f32_16x16x32_bf16 v[82:85], v[142:145], v[174:177], v[82:85]
	v_mfma_f32_16x16x32_bf16 v[70:73], v[134:137], v[166:169], v[70:73]
	v_mfma_f32_16x16x32_bf16 v[66:69], v[142:145], v[166:169], v[66:69]
	s_setprio 0
	s_barrier
	s_mov_b32 m0, s34
	v_lshl_add_u64 v[232:233], s[16:17], 0, v[212:213]
	s_add_u32 s68, s16, 0xb0000
	ds_read_b128 v[186:189], v247 offset:16384
	ds_read_b128 v[190:193], v247 offset:17408
	ds_read_b128 v[178:181], v247 offset:18432
	ds_read_b128 v[182:185], v247 offset:19456
	ds_read_b128 v[170:173], v247 offset:20480
	ds_read_b128 v[174:177], v247 offset:21504
	ds_read_b128 v[162:165], v247 offset:22528
	ds_read_b128 v[166:169], v247 offset:23552
	global_load_lds_dwordx4 v[232:233], off
	v_lshl_add_u64 v[230:231], s[16:17], 0, v[216:217]
	s_mov_b32 m0, s35
	s_addc_u32 s69, s17, 0
	global_load_lds_dwordx4 v[230:231], off
	v_lshl_add_u64 v[194:195], s[68:69], 0, v[212:213]
	s_mov_b32 m0, s36
	v_lshl_add_u64 v[226:227], s[18:19], 0, v[210:211]
	global_load_lds_dwordx4 v[194:195], off
	v_lshl_add_u64 v[194:195], s[68:69], 0, v[216:217]
	s_mov_b32 m0, s37
	v_lshl_add_u64 v[228:229], s[18:19], 0, v[214:215]
	global_load_lds_dwordx4 v[194:195], off
	s_mov_b32 m0, s31
	s_andn2_b64 vcc, exec, s[20:21]
	global_load_lds_dwordx4 v[226:227], off
	s_mov_b32 m0, s38
	s_nop 0
	global_load_lds_dwordx4 v[228:229], off
	s_waitcnt vmcnt(24)
	s_cbranch_vccnz .LBB0_235
	s_waitcnt vmcnt(8)
	s_branch .LBB0_235

; #define PG8_STAGE(bufoff, gbase, voff) do { _Pragma("unroll") for (int _i = 0; _i < 2; ++_i) \
;         __builtin_amdgcn_global_load_lds((const unsigned*)((const char*)(gbase) + (voff)[_i]), (PG8_LAS unsigned*)(lds + (bufoff) + ldsw + _i * 8192), 16, 0, 0); } while (0)
; #define PG8_LDA(dst, b, h) do { _Pragma("unroll") for (int m = 0; m < 4; ++m) _Pragma("unroll") for (int k = 0; k < 2; ++k) dst[m][k] = *(const PG8_LAS bf16x8*)(lds + PG8_SA(b, h) + aoff + m * 2048 + k * 1024); } while (0)
; #define PG8_LDB(dst, b, h) do { _Pragma("unroll") for (int n = 0; n < 2; ++n) _Pragma("unroll") for (int k = 0; k < 2; ++k) dst[n][k] = *(const PG8_LAS bf16x8*)(lds + PG8_SB(b, h) + boff + n * 2048 + k * 1024); } while (0)
; #define PG8_MMA(ai, bj, At, Bt) do { __builtin_amdgcn_s_setprio(1); _Pragma("unroll") for (int m = 0; m < 4; ++m) _Pragma("unroll") for (int n = 0; n < 2; ++n) _Pragma("unroll") for (int k = 0; k < 2; ++k) \
;         acc[ai][bj][m][n] = __builtin_amdgcn_mfma_f32_16x16x32_bf16(Bt[n][k], At[m][k], acc[ai][bj][m][n], 0, 0, 0); __builtin_amdgcn_s_setprio(0); } while (0)
; #define PG8_WAIT_V(n) asm volatile("s_waitcnt vmcnt(" #n ")" ::: "memory")
; #define PG8_WAIT_VN(n) asm volatile("s_waitcnt vmcnt(%0)" :: "n"(n) : "memory")
; #define PG8_WAIT_L(n) asm volatile("s_waitcnt lgkmcnt(" #n ")" ::: "memory")
; #define PG8_BAR __builtin_amdgcn_s_barrier()
; #define PG8_SCHED __builtin_amdgcn_sched_barrier(0)
; template <class Epi, class Sched, bool ALIGN_EPI = false, bool SP2 = false>
; __device__ __forceinline__ void gemm_phase(PG8_LAS unsigned char* lds, const Gemm g, const Sched& S, const Epi& E, const int wave_id) {
;     ...
;             PG8_WAIT_VN(8 + Epi::NS); if (strict) PG8_WAIT_V(8); PG8_WAIT_L(0); PG8_BAR; PG8_MMA(1, 0, At, B0); PG8_MMA(1, 1, At, B1); PG8_BAR; PG8_SCHED;
;             PG8_LDB(B0, 1, 0); PG8_LDB(B1, 1, 1); PG8_SCHED; PG8_LDA(At, 1, 0); PG8_STAGE(PG8_SA(0, 1), a2 + hstep, voffA);
;             PG8_WAIT_V(8); PG8_WAIT_L(0); PG8_BAR; PG8_MMA(0, 0, At, B0); PG8_MMA(0, 1, At, B1); PG8_BAR; PG8_SCHED;
.LBB0_304:
	s_waitcnt lgkmcnt(0)
	s_setprio 1
	s_barrier
	v_mfma_f32_16x16x32_bf16 v[62:65], v[146:149], v[186:189], v[62:65]
	v_mfma_f32_16x16x32_bf16 v[58:61], v[154:157], v[186:189], v[58:61]
	v_mfma_f32_16x16x32_bf16 v[54:57], v[146:149], v[178:181], v[54:57]
	v_mfma_f32_16x16x32_bf16 v[50:53], v[154:157], v[178:181], v[50:53]
	v_mfma_f32_16x16x32_bf16 v[42:45], v[146:149], v[170:173], v[42:45]
	v_mfma_f32_16x16x32_bf16 v[34:37], v[154:157], v[170:173], v[34:37]
	v_mfma_f32_16x16x32_bf16 v[26:29], v[146:149], v[162:165], v[26:29]
	v_mfma_f32_16x16x32_bf16 v[18:21], v[154:157], v[162:165], v[18:21]
	v_mfma_f32_16x16x32_bf16 v[62:65], v[150:153], v[190:193], v[62:65]
	v_mfma_f32_16x16x32_bf16 v[58:61], v[158:161], v[190:193], v[58:61]
	v_mfma_f32_16x16x32_bf16 v[54:57], v[150:153], v[182:185], v[54:57]
	v_mfma_f32_16x16x32_bf16 v[50:53], v[158:161], v[182:185], v[50:53]
	v_mfma_f32_16x16x32_bf16 v[42:45], v[150:153], v[174:177], v[42:45]
	v_mfma_f32_16x16x32_bf16 v[34:37], v[158:161], v[174:177], v[34:37]
	v_mfma_f32_16x16x32_bf16 v[26:29], v[150:153], v[166:169], v[26:29]
	v_mfma_f32_16x16x32_bf16 v[18:21], v[158:161], v[166:169], v[18:21]
	s_setprio 0
	s_setprio 1
	v_mfma_f32_16x16x32_bf16 v[46:49], v[130:133], v[186:189], v[46:49]
	v_mfma_f32_16x16x32_bf16 v[38:41], v[138:141], v[186:189], v[38:41]
	v_mfma_f32_16x16x32_bf16 v[30:33], v[130:133], v[178:181], v[30:33]
	v_mfma_f32_16x16x32_bf16 v[22:25], v[138:141], v[178:181], v[22:25]
	v_mfma_f32_16x16x32_bf16 v[14:17], v[130:133], v[170:173], v[14:17]
	v_mfma_f32_16x16x32_bf16 v[10:13], v[138:141], v[170:173], v[10:13]
	v_mfma_f32_16x16x32_bf16 v[6:9], v[130:133], v[162:165], v[6:9]
	v_mfma_f32_16x16x32_bf16 v[2:5], v[138:141], v[162:165], v[2:5]
	v_mfma_f32_16x16x32_bf16 v[46:49], v[134:137], v[190:193], v[46:49]
	v_mfma_f32_16x16x32_bf16 v[38:41], v[142:145], v[190:193], v[38:41]
	v_mfma_f32_16x16x32_bf16 v[30:33], v[134:137], v[182:185], v[30:33]
	v_mfma_f32_16x16x32_bf16 v[22:25], v[142:145], v[182:185], v[22:25]
	v_mfma_f32_16x16x32_bf16 v[14:17], v[134:137], v[174:177], v[14:17]
	v_mfma_f32_16x16x32_bf16 v[10:13], v[142:145], v[174:177], v[10:13]
	v_mfma_f32_16x16x32_bf16 v[6:9], v[134:137], v[166:169], v[6:9]
	v_mfma_f32_16x16x32_bf16 v[2:5], v[142:145], v[166:169], v[2:5]
	s_setprio 0
	s_barrier
	s_add_i32 s16, 0, 0x18000
	s_add_i32 s17, 0, 0x1c000
	v_add_u32_e32 v142, s16, v231
	v_add_u32_e32 v158, s17, v231
	ds_read_b128 v[130:133], v142
	ds_read_b128 v[134:137], v142 offset:1024
	ds_read_b128 v[138:141], v142 offset:2048
	ds_read_b128 v[142:145], v142 offset:3072
	ds_read_b128 v[146:149], v158
	ds_read_b128 v[150:153], v158 offset:1024
	ds_read_b128 v[154:157], v158 offset:2048
	ds_read_b128 v[158:161], v158 offset:3072
	s_add_u32 s14, s14, 0xb0000
	s_addc_u32 s15, s15, 0
	s_mov_b32 m0, s29
	v_lshl_add_u64 v[194:195], s[14:15], 0, v[216:217]
	ds_read_b128 v[162:165], v232 offset:32768
	ds_read_b128 v[166:169], v232 offset:33792
	ds_read_b128 v[170:173], v232 offset:34816
	ds_read_b128 v[174:177], v232 offset:35840
	ds_read_b128 v[178:181], v232 offset:36864
	ds_read_b128 v[182:185], v232 offset:37888
	ds_read_b128 v[186:189], v232 offset:38912
	ds_read_b128 v[190:193], v232 offset:39936
	global_load_lds_dwordx4 v[194:195], off
	v_lshl_add_u64 v[194:195], s[14:15], 0, v[212:213]
	s_mov_b32 m0, s30
	s_nop 0
	global_load_lds_dwordx4 v[194:195], off
	s_waitcnt vmcnt(8)
	s_waitcnt lgkmcnt(0)
	s_setprio 1
	s_barrier
	v_mfma_f32_16x16x32_bf16 v[126:129], v[130:133], v[162:165], v[126:129]
	v_mfma_f32_16x16x32_bf16 v[122:125], v[138:141], v[162:165], v[122:125]
	v_mfma_f32_16x16x32_bf16 v[118:121], v[130:133], v[170:173], v[118:121]
	v_mfma_f32_16x16x32_bf16 v[114:117], v[138:141], v[170:173], v[114:117]
	v_mfma_f32_16x16x32_bf16 v[110:113], v[130:133], v[178:181], v[110:113]
	v_mfma_f32_16x16x32_bf16 v[102:105], v[138:141], v[178:181], v[102:105]
	v_mfma_f32_16x16x32_bf16 v[94:97], v[130:133], v[186:189], v[94:97]
	v_mfma_f32_16x16x32_bf16 v[86:89], v[138:141], v[186:189], v[86:89]
	v_mfma_f32_16x16x32_bf16 v[126:129], v[134:137], v[166:169], v[126:129]
	v_mfma_f32_16x16x32_bf16 v[122:125], v[142:145], v[166:169], v[122:125]
	v_mfma_f32_16x16x32_bf16 v[118:121], v[134:137], v[174:177], v[118:121]
	v_mfma_f32_16x16x32_bf16 v[114:117], v[142:145], v[174:177], v[114:117]
	v_mfma_f32_16x16x32_bf16 v[110:113], v[134:137], v[182:185], v[110:113]
	v_mfma_f32_16x16x32_bf16 v[102:105], v[142:145], v[182:185], v[102:105]
	v_mfma_f32_16x16x32_bf16 v[94:97], v[134:137], v[190:193], v[94:97]
	v_mfma_f32_16x16x32_bf16 v[86:89], v[142:145], v[190:193], v[86:89]
	s_setprio 0
	s_setprio 1
	v_mfma_f32_16x16x32_bf16 v[106:109], v[146:149], v[162:165], v[106:109]
	v_mfma_f32_16x16x32_bf16 v[98:101], v[154:157], v[162:165], v[98:101]
	v_mfma_f32_16x16x32_bf16 v[90:93], v[146:149], v[170:173], v[90:93]
	v_mfma_f32_16x16x32_bf16 v[82:85], v[154:157], v[170:173], v[82:85]
	v_mfma_f32_16x16x32_bf16 v[78:81], v[146:149], v[178:181], v[78:81]
	v_mfma_f32_16x16x32_bf16 v[74:77], v[154:157], v[178:181], v[74:77]
	v_mfma_f32_16x16x32_bf16 v[70:73], v[146:149], v[186:189], v[70:73]
	v_mfma_f32_16x16x32_bf16 v[66:69], v[154:157], v[186:189], v[66:69]
	v_mfma_f32_16x16x32_bf16 v[106:109], v[150:153], v[166:169], v[106:109]
	v_mfma_f32_16x16x32_bf16 v[98:101], v[158:161], v[166:169], v[98:101]
	v_mfma_f32_16x16x32_bf16 v[90:93], v[150:153], v[174:177], v[90:93]
	v_mfma_f32_16x16x32_bf16 v[82:85], v[158:161], v[174:177], v[82:85]
	v_mfma_f32_16x16x32_bf16 v[78:81], v[150:153], v[182:185], v[78:81]
	v_mfma_f32_16x16x32_bf16 v[74:77], v[158:161], v[182:185], v[74:77]
	v_mfma_f32_16x16x32_bf16 v[70:73], v[150:153], v[190:193], v[70:73]
	v_mfma_f32_16x16x32_bf16 v[66:69], v[158:161], v[190:193], v[66:69]
	s_setprio 0
	s_barrier
; #define PG8_STAGE(bufoff, gbase, voff) do { _Pragma("unroll") for (int _i = 0; _i < 2; ++_i) \
;         __builtin_amdgcn_global_load_lds((const unsigned*)((const char*)(gbase) + (voff)[_i]), (PG8_LAS unsigned*)(lds + (bufoff) + ldsw + _i * 8192), 16, 0, 0); } while (0)
; #define PG8_LDA(dst, b, h) do { _Pragma("unroll") for (int m = 0; m < 4; ++m) _Pragma("unroll") for (int k = 0; k < 2; ++k) dst[m][k] = *(const PG8_LAS bf16x8*)(lds + PG8_SA(b, h) + aoff + m * 2048 + k * 1024); } while (0)
; #define PG8_MMA(ai, bj, At, Bt) do { __builtin_amdgcn_s_setprio(1); _Pragma("unroll") for (int m = 0; m < 4; ++m) _Pragma("unroll") for (int n = 0; n < 2; ++n) _Pragma("unroll") for (int k = 0; k < 2; ++k) \
;         acc[ai][bj][m][n] = __builtin_amdgcn_mfma_f32_16x16x32_bf16(Bt[n][k], At[m][k], acc[ai][bj][m][n], 0, 0, 0); __builtin_amdgcn_s_setprio(0); } while (0)
; #define PG8_WAIT_V(n) asm volatile("s_waitcnt vmcnt(" #n ")" ::: "memory")
; #define PG8_WAIT_L(n) asm volatile("s_waitcnt lgkmcnt(" #n ")" ::: "memory")
; #define PG8_BAR __builtin_amdgcn_s_barrier()
; #define PG8_SCHED __builtin_amdgcn_sched_barrier(0)
; template <class Epi, class Sched, bool ALIGN_EPI = false, bool SP2 = false>
; __device__ __forceinline__ void gemm_phase(PG8_LAS unsigned char* lds, const Gemm g, const Sched& S, const Epi& E, const int wave_id) {
;     ...
;             PG8_LDA(At, 1, 1); PG8_STAGE(PG8_SB(1, 0), b3, voffB); PG8_STAGE(PG8_SB(1, 1), b3 + hstep, voffB); PG8_STAGE(PG8_SA(1, 0), a3, voffA);
;             PG8_WAIT_V(8); PG8_WAIT_L(0); PG8_BAR; PG8_MMA(1, 0, At, B0); PG8_MMA(1, 1, At, B1); PG8_BAR; PG8_SCHED;
	s_add_i32 s14, s16, s21
	v_lshl_add_u64 v[194:195], v[228:229], 0, s[64:65]
	s_mov_b32 m0, s14
	ds_read_b128 v[162:165], v232 offset:49152
	ds_read_b128 v[166:169], v232 offset:50176
	ds_read_b128 v[170:173], v232 offset:51200
	ds_read_b128 v[174:177], v232 offset:52224
	ds_read_b128 v[178:181], v232 offset:53248
	ds_read_b128 v[182:185], v232 offset:54272
	ds_read_b128 v[186:189], v232 offset:55296
	ds_read_b128 v[190:193], v232 offset:56320
	global_load_lds_dwordx4 v[194:195], off
	s_add_i32 m0, s14, 0x2000
	s_add_u32 s12, s12, 0xb0080
	v_lshl_add_u64 v[194:195], v[226:227], 0, s[64:65]
	s_addc_u32 s13, s13, 0
	s_add_i32 s14, s17, s21
	global_load_lds_dwordx4 v[194:195], off
	v_lshl_add_u64 v[194:195], s[12:13], 0, v[214:215]
	s_mov_b32 m0, s14
	s_nop 0
	global_load_lds_dwordx4 v[194:195], off
	v_lshl_add_u64 v[194:195], s[12:13], 0, v[210:211]
	s_add_i32 m0, s14, 0x2000
	s_nop 0
	global_load_lds_dwordx4 v[194:195], off
	v_lshl_add_u64 v[194:195], v[222:223], 0, s[64:65]
	s_mov_b32 m0, s31
	s_nop 0
	global_load_lds_dwordx4 v[194:195], off
	v_lshl_add_u64 v[194:195], v[224:225], 0, s[64:65]
	s_mov_b32 m0, s34
	s_nop 0
	global_load_lds_dwordx4 v[194:195], off
	s_waitcnt vmcnt(8)
	s_waitcnt lgkmcnt(0)
	s_setprio 1
	s_barrier
	v_mfma_f32_16x16x32_bf16 v[62:65], v[130:133], v[162:165], v[62:65]
	v_mfma_f32_16x16x32_bf16 v[58:61], v[138:141], v[162:165], v[58:61]
	v_mfma_f32_16x16x32_bf16 v[54:57], v[130:133], v[170:173], v[54:57]
	v_mfma_f32_16x16x32_bf16 v[50:53], v[138:141], v[170:173], v[50:53]
	v_mfma_f32_16x16x32_bf16 v[42:45], v[130:133], v[178:181], v[42:45]
	v_mfma_f32_16x16x32_bf16 v[34:37], v[138:141], v[178:181], v[34:37]
	v_mfma_f32_16x16x32_bf16 v[26:29], v[130:133], v[186:189], v[26:29]
	v_mfma_f32_16x16x32_bf16 v[18:21], v[138:141], v[186:189], v[18:21]
	v_mfma_f32_16x16x32_bf16 v[62:65], v[134:137], v[166:169], v[62:65]
	v_mfma_f32_16x16x32_bf16 v[58:61], v[142:145], v[166:169], v[58:61]
	v_mfma_f32_16x16x32_bf16 v[54:57], v[134:137], v[174:177], v[54:57]
	v_mfma_f32_16x16x32_bf16 v[50:53], v[142:145], v[174:177], v[50:53]
	v_mfma_f32_16x16x32_bf16 v[42:45], v[134:137], v[182:185], v[42:45]
	v_mfma_f32_16x16x32_bf16 v[34:37], v[142:145], v[182:185], v[34:37]
	v_mfma_f32_16x16x32_bf16 v[26:29], v[134:137], v[190:193], v[26:29]
	v_mfma_f32_16x16x32_bf16 v[18:21], v[142:145], v[190:193], v[18:21]
	s_setprio 0
	s_setprio 1
	v_mfma_f32_16x16x32_bf16 v[46:49], v[146:149], v[162:165], v[46:49]
	v_mfma_f32_16x16x32_bf16 v[38:41], v[154:157], v[162:165], v[38:41]
	v_mfma_f32_16x16x32_bf16 v[30:33], v[146:149], v[170:173], v[30:33]
	v_mfma_f32_16x16x32_bf16 v[22:25], v[154:157], v[170:173], v[22:25]
	v_mfma_f32_16x16x32_bf16 v[14:17], v[146:149], v[178:181], v[14:17]
	v_mfma_f32_16x16x32_bf16 v[10:13], v[154:157], v[178:181], v[10:13]
	v_mfma_f32_16x16x32_bf16 v[6:9], v[146:149], v[186:189], v[6:9]
	v_mfma_f32_16x16x32_bf16 v[2:5], v[154:157], v[186:189], v[2:5]
	v_mfma_f32_16x16x32_bf16 v[46:49], v[150:153], v[166:169], v[46:49]
	v_mfma_f32_16x16x32_bf16 v[38:41], v[158:161], v[166:169], v[38:41]
	v_mfma_f32_16x16x32_bf16 v[30:33], v[150:153], v[174:177], v[30:33]
	v_mfma_f32_16x16x32_bf16 v[22:25], v[158:161], v[174:177], v[22:25]
	v_mfma_f32_16x16x32_bf16 v[14:17], v[150:153], v[182:185], v[14:17]
	v_mfma_f32_16x16x32_bf16 v[10:13], v[158:161], v[182:185], v[10:13]
	v_mfma_f32_16x16x32_bf16 v[6:9], v[150:153], v[190:193], v[6:9]
	v_mfma_f32_16x16x32_bf16 v[2:5], v[158:161], v[190:193], v[2:5]
	s_setprio 0
	s_barrier
	s_add_u32 s10, s10, 0x100
	s_addc_u32 s11, s11, 0
	s_cmp_gt_u32 s39, 19
	v_readlane_b32 s40, v254, 55
	s_cbranch_scc1 .LBB0_309

; #define PG8_STAGE(bufoff, gbase, voff) do { _Pragma("unroll") for (int _i = 0; _i < 2; ++_i) \
;         __builtin_amdgcn_global_load_lds((const unsigned*)((const char*)(gbase) + (voff)[_i]), (PG8_LAS unsigned*)(lds + (bufoff) + ldsw + _i * 8192), 16, 0, 0); } while (0)
; #define PG8_LDA(dst, b, h) do { _Pragma("unroll") for (int m = 0; m < 4; ++m) _Pragma("unroll") for (int k = 0; k < 2; ++k) dst[m][k] = *(const PG8_LAS bf16x8*)(lds + PG8_SA(b, h) + aoff + m * 2048 + k * 1024); } while (0)
; #define PG8_LDB(dst, b, h) do { _Pragma("unroll") for (int n = 0; n < 2; ++n) _Pragma("unroll") for (int k = 0; k < 2; ++k) dst[n][k] = *(const PG8_LAS bf16x8*)(lds + PG8_SB(b, h) + boff + n * 2048 + k * 1024); } while (0)
; #define PG8_WAIT_V(n) asm volatile("s_waitcnt vmcnt(" #n ")" ::: "memory")
; #define PG8_WAIT_VN(n) asm volatile("s_waitcnt vmcnt(%0)" :: "n"(n) : "memory")
; #define PG8_WAIT_L(n) asm volatile("s_waitcnt lgkmcnt(" #n ")" ::: "memory")
; #define PG8_BAR __builtin_amdgcn_s_barrier()
; template <class Epi, class Sched, bool ALIGN_EPI = false, bool SP2 = false>
; __device__ __forceinline__ void gemm_phase(PG8_LAS unsigned char* lds, const Gemm g, const Sched& S, const Epi& E, const int wave_id) {
;     ...
;             const bool last = (t == nt - 2);
;             const char* a1 = cA + (size_t)(t + 1) * kstep;
;             const char* a2 = last ? nA : cA + (size_t)(t + 2) * kstep; const char* b2 = last ? nB : cB + (size_t)(t + 2) * kstep;
;             const char* a3 = a2 + kstep; const char* b3 = b2 + kstep;
;             if (last && has_next) S.a_ready(nxt);
;             if constexpr (SP2) {
;             int tz_ = __builtin_amdgcn_readfirstlane(t | (ui > 0 ? 0 : 1)); asm volatile("" : "+s"(tz_));
;             const bool strict = !(Epi::NS > 0 && tz_ == 0);
;             PG8_LDB(B0, 0, 0); PG8_LDB(B1, 0, 1); PG8_SCHED; PG8_LDA(At, 0, 0); PG8_STAGE(PG8_SA(1, 1), a1 + hstep, voffA);
;             PG8_WAIT_VN(8 + Epi::NS); if (strict) PG8_WAIT_V(8); PG8_WAIT_L(0); PG8_BAR; PG8_MMA(0, 0, At, B0); PG8_MMA(0, 1, At, B1); PG8_BAR; PG8_SCHED;
;             PG8_LDA(At, 0, 1); PG8_STAGE(PG8_SB(0, 0), b2, voffB); PG8_STAGE(PG8_SB(0, 1), b2 + hstep, voffB); PG8_STAGE(PG8_SA(0, 0), a2, voffA);
;             PG8_WAIT_VN(8 + Epi::NS); if (strict) PG8_WAIT_V(8); PG8_WAIT_L(0); PG8_BAR; PG8_MMA(1, 0, At, B0); PG8_MMA(1, 1, At, B1); PG8_BAR; PG8_SCHED;
.LBB0_307:
	s_add_u32 s12, s37, s10
	s_addc_u32 s13, s38, s11
	s_add_u32 s12, s12, 0x26300100
	s_addc_u32 s13, s13, 0
	s_add_u32 s40, s35, s10
	s_addc_u32 s41, s36, s11
	s_cmpk_eq_i32 s10, 0xa00
	s_cselect_b32 s15, s9, s13
	s_cselect_b32 s14, s8, s12
	s_cselect_b32 s13, s7, s41
	s_cselect_b32 s12, s6, s40
	s_waitcnt lgkmcnt(0)
	s_setprio 1
	s_barrier
	v_mfma_f32_16x16x32_bf16 v[126:129], v[146:149], v[186:189], v[126:129]
	v_mfma_f32_16x16x32_bf16 v[122:125], v[154:157], v[186:189], v[122:125]
	v_mfma_f32_16x16x32_bf16 v[118:121], v[146:149], v[178:181], v[118:121]
	v_mfma_f32_16x16x32_bf16 v[114:117], v[154:157], v[178:181], v[114:117]
	v_mfma_f32_16x16x32_bf16 v[110:113], v[146:149], v[170:173], v[110:113]
	v_mfma_f32_16x16x32_bf16 v[102:105], v[154:157], v[170:173], v[102:105]
	v_mfma_f32_16x16x32_bf16 v[94:97], v[146:149], v[162:165], v[94:97]
	v_mfma_f32_16x16x32_bf16 v[86:89], v[154:157], v[162:165], v[86:89]
	v_mfma_f32_16x16x32_bf16 v[126:129], v[150:153], v[190:193], v[126:129]
	v_mfma_f32_16x16x32_bf16 v[122:125], v[158:161], v[190:193], v[122:125]
	v_mfma_f32_16x16x32_bf16 v[118:121], v[150:153], v[182:185], v[118:121]
	v_mfma_f32_16x16x32_bf16 v[114:117], v[158:161], v[182:185], v[114:117]
	v_mfma_f32_16x16x32_bf16 v[110:113], v[150:153], v[174:177], v[110:113]
	v_mfma_f32_16x16x32_bf16 v[102:105], v[158:161], v[174:177], v[102:105]
	v_mfma_f32_16x16x32_bf16 v[94:97], v[150:153], v[166:169], v[94:97]
	v_mfma_f32_16x16x32_bf16 v[86:89], v[158:161], v[166:169], v[86:89]
	s_setprio 0
	s_setprio 1
	v_mfma_f32_16x16x32_bf16 v[106:109], v[130:133], v[186:189], v[106:109]
	v_mfma_f32_16x16x32_bf16 v[98:101], v[138:141], v[186:189], v[98:101]
	v_mfma_f32_16x16x32_bf16 v[90:93], v[130:133], v[178:181], v[90:93]
	v_mfma_f32_16x16x32_bf16 v[82:85], v[138:141], v[178:181], v[82:85]
	v_mfma_f32_16x16x32_bf16 v[78:81], v[130:133], v[170:173], v[78:81]
	v_mfma_f32_16x16x32_bf16 v[74:77], v[138:141], v[170:173], v[74:77]
	v_mfma_f32_16x16x32_bf16 v[70:73], v[130:133], v[162:165], v[70:73]
	v_mfma_f32_16x16x32_bf16 v[66:69], v[138:141], v[162:165], v[66:69]
	v_mfma_f32_16x16x32_bf16 v[106:109], v[134:137], v[190:193], v[106:109]
	v_mfma_f32_16x16x32_bf16 v[98:101], v[142:145], v[190:193], v[98:101]
	v_mfma_f32_16x16x32_bf16 v[90:93], v[134:137], v[182:185], v[90:93]
	v_mfma_f32_16x16x32_bf16 v[82:85], v[142:145], v[182:185], v[82:85]
	v_mfma_f32_16x16x32_bf16 v[78:81], v[134:137], v[174:177], v[78:81]
	v_mfma_f32_16x16x32_bf16 v[74:77], v[142:145], v[174:177], v[74:77]
	v_mfma_f32_16x16x32_bf16 v[70:73], v[134:137], v[166:169], v[70:73]
	v_mfma_f32_16x16x32_bf16 v[66:69], v[142:145], v[166:169], v[66:69]
	s_setprio 0
	s_barrier
	s_mov_b32 m0, s23
	v_lshl_add_u64 v[228:229], s[12:13], 0, v[214:215]
	s_add_u32 s40, s12, 0xb0000
	ds_read_b128 v[186:189], v232 offset:16384
	ds_read_b128 v[190:193], v232 offset:17408
	ds_read_b128 v[178:181], v232 offset:18432
	ds_read_b128 v[182:185], v232 offset:19456
	ds_read_b128 v[170:173], v232 offset:20480
	ds_read_b128 v[174:177], v232 offset:21504
	ds_read_b128 v[162:165], v232 offset:22528
	ds_read_b128 v[166:169], v232 offset:23552
	global_load_lds_dwordx4 v[228:229], off
	v_lshl_add_u64 v[226:227], s[12:13], 0, v[210:211]
	s_mov_b32 m0, s24
	s_addc_u32 s41, s13, 0
	global_load_lds_dwordx4 v[226:227], off
	v_lshl_add_u64 v[194:195], s[40:41], 0, v[214:215]
	s_mov_b32 m0, s25
	v_lshl_add_u64 v[222:223], s[14:15], 0, v[216:217]
	global_load_lds_dwordx4 v[194:195], off
	v_lshl_add_u64 v[194:195], s[40:41], 0, v[210:211]
	s_mov_b32 m0, s26
	v_lshl_add_u64 v[224:225], s[14:15], 0, v[212:213]
	global_load_lds_dwordx4 v[194:195], off
	s_mov_b32 m0, s22
	s_andn2_b64 vcc, exec, s[16:17]
	global_load_lds_dwordx4 v[222:223], off
	s_mov_b32 m0, s28
	s_nop 0
	global_load_lds_dwordx4 v[224:225], off
	s_waitcnt vmcnt(24)
	s_cbranch_vccnz .LBB0_304
	s_waitcnt vmcnt(8)
	s_branch .LBB0_304

; #define PG8_STAGE(bufoff, gbase, voff) do { _Pragma("unroll") for (int _i = 0; _i < 2; ++_i) \
;         __builtin_amdgcn_global_load_lds((const unsigned*)((const char*)(gbase) + (voff)[_i]), (PG8_LAS unsigned*)(lds + (bufoff) + ldsw + _i * 8192), 16, 0, 0); } while (0)
; #define PG8_LDA(dst, b, h) do { _Pragma("unroll") for (int m = 0; m < 4; ++m) _Pragma("unroll") for (int k = 0; k < 2; ++k) dst[m][k] = *(const PG8_LAS bf16x8*)(lds + PG8_SA(b, h) + aoff + m * 2048 + k * 1024); } while (0)
; #define PG8_LDB(dst, b, h) do { _Pragma("unroll") for (int n = 0; n < 2; ++n) _Pragma("unroll") for (int k = 0; k < 2; ++k) dst[n][k] = *(const PG8_LAS bf16x8*)(lds + PG8_SB(b, h) + boff + n * 2048 + k * 1024); } while (0)
; #define PG8_MMA(ai, bj, At, Bt) do { __builtin_amdgcn_s_setprio(1); _Pragma("unroll") for (int m = 0; m < 4; ++m) _Pragma("unroll") for (int n = 0; n < 2; ++n) _Pragma("unroll") for (int k = 0; k < 2; ++k) \
;         acc[ai][bj][m][n] = __builtin_amdgcn_mfma_f32_16x16x32_bf16(Bt[n][k], At[m][k], acc[ai][bj][m][n], 0, 0, 0); __builtin_amdgcn_s_setprio(0); } while (0)
; #define PG8_WAIT_V(n) asm volatile("s_waitcnt vmcnt(" #n ")" ::: "memory")
; #define PG8_WAIT_VN(n) asm volatile("s_waitcnt vmcnt(%0)" :: "n"(n) : "memory")
; #define PG8_WAIT_L(n) asm volatile("s_waitcnt lgkmcnt(" #n ")" ::: "memory")
; #define PG8_BAR __builtin_amdgcn_s_barrier()
; #define PG8_SCHED __builtin_amdgcn_sched_barrier(0)
; template <class Epi, class Sched, bool ALIGN_EPI = false, bool SP2 = false>
; __device__ __forceinline__ void gemm_phase(PG8_LAS unsigned char* lds, const Gemm g, const Sched& S, const Epi& E, const int wave_id) {
;     ...
;             PG8_WAIT_VN(8 + Epi::NS); if (strict) PG8_WAIT_V(8); PG8_WAIT_L(0); PG8_BAR; PG8_MMA(1, 0, At, B0); PG8_MMA(1, 1, At, B1); PG8_BAR; PG8_SCHED;
;             PG8_LDB(B0, 1, 0); PG8_LDB(B1, 1, 1); PG8_SCHED; PG8_LDA(At, 1, 0); PG8_STAGE(PG8_SA(0, 1), a2 + hstep, voffA);
;             PG8_WAIT_V(8); PG8_WAIT_L(0); PG8_BAR; PG8_MMA(0, 0, At, B0); PG8_MMA(0, 1, At, B1); PG8_BAR; PG8_SCHED;
.LBB0_420:
	s_waitcnt lgkmcnt(0)
	s_setprio 1
	s_barrier
	v_mfma_f32_16x16x32_bf16 v[62:65], v[146:149], v[186:189], v[62:65]
	v_mfma_f32_16x16x32_bf16 v[58:61], v[154:157], v[186:189], v[58:61]
	v_mfma_f32_16x16x32_bf16 v[46:49], v[146:149], v[178:181], v[46:49]
	v_mfma_f32_16x16x32_bf16 v[42:45], v[154:157], v[178:181], v[42:45]
	v_mfma_f32_16x16x32_bf16 v[30:33], v[146:149], v[170:173], v[30:33]
	v_mfma_f32_16x16x32_bf16 v[26:29], v[154:157], v[170:173], v[26:29]
	v_mfma_f32_16x16x32_bf16 v[14:17], v[146:149], v[162:165], v[14:17]
	v_mfma_f32_16x16x32_bf16 v[10:13], v[154:157], v[162:165], v[10:13]
	v_mfma_f32_16x16x32_bf16 v[62:65], v[150:153], v[190:193], v[62:65]
	v_mfma_f32_16x16x32_bf16 v[58:61], v[158:161], v[190:193], v[58:61]
	v_mfma_f32_16x16x32_bf16 v[46:49], v[150:153], v[182:185], v[46:49]
	v_mfma_f32_16x16x32_bf16 v[42:45], v[158:161], v[182:185], v[42:45]
	v_mfma_f32_16x16x32_bf16 v[30:33], v[150:153], v[174:177], v[30:33]
	v_mfma_f32_16x16x32_bf16 v[26:29], v[158:161], v[174:177], v[26:29]
	v_mfma_f32_16x16x32_bf16 v[14:17], v[150:153], v[166:169], v[14:17]
	v_mfma_f32_16x16x32_bf16 v[10:13], v[158:161], v[166:169], v[10:13]
	s_setprio 0
	s_setprio 1
	v_mfma_f32_16x16x32_bf16 v[54:57], v[130:133], v[186:189], v[54:57]
	v_mfma_f32_16x16x32_bf16 v[50:53], v[138:141], v[186:189], v[50:53]
	v_mfma_f32_16x16x32_bf16 v[38:41], v[130:133], v[178:181], v[38:41]
	v_mfma_f32_16x16x32_bf16 v[34:37], v[138:141], v[178:181], v[34:37]
	v_mfma_f32_16x16x32_bf16 v[22:25], v[130:133], v[170:173], v[22:25]
	v_mfma_f32_16x16x32_bf16 v[18:21], v[138:141], v[170:173], v[18:21]
	v_mfma_f32_16x16x32_bf16 v[6:9], v[130:133], v[162:165], v[6:9]
	v_mfma_f32_16x16x32_bf16 v[2:5], v[138:141], v[162:165], v[2:5]
	v_mfma_f32_16x16x32_bf16 v[54:57], v[134:137], v[190:193], v[54:57]
	v_mfma_f32_16x16x32_bf16 v[50:53], v[142:145], v[190:193], v[50:53]
	v_mfma_f32_16x16x32_bf16 v[38:41], v[134:137], v[182:185], v[38:41]
	v_mfma_f32_16x16x32_bf16 v[34:37], v[142:145], v[182:185], v[34:37]
	v_mfma_f32_16x16x32_bf16 v[22:25], v[134:137], v[174:177], v[22:25]
	v_mfma_f32_16x16x32_bf16 v[18:21], v[142:145], v[174:177], v[18:21]
	v_mfma_f32_16x16x32_bf16 v[6:9], v[134:137], v[166:169], v[6:9]
	v_mfma_f32_16x16x32_bf16 v[2:5], v[142:145], v[166:169], v[2:5]
	s_setprio 0
	s_barrier
	s_add_i32 s34, 0, 0x18000
	s_add_i32 s35, 0, 0x1c000
	v_add_u32_e32 v142, s34, v246
	v_add_u32_e32 v158, s35, v246
	ds_read_b128 v[130:133], v142
	ds_read_b128 v[134:137], v142 offset:1024
	ds_read_b128 v[138:141], v142 offset:2048
	ds_read_b128 v[142:145], v142 offset:3072
	ds_read_b128 v[146:149], v158
	ds_read_b128 v[150:153], v158 offset:1024
	ds_read_b128 v[154:157], v158 offset:2048
	ds_read_b128 v[158:161], v158 offset:3072
	s_add_u32 s14, s14, 0x40000
	s_addc_u32 s15, s15, 0
	s_mov_b32 m0, s3
	v_lshl_add_u64 v[194:195], s[14:15], 0, v[210:211]
	ds_read_b128 v[162:165], v247 offset:32768
	ds_read_b128 v[166:169], v247 offset:33792
	ds_read_b128 v[170:173], v247 offset:34816
	ds_read_b128 v[174:177], v247 offset:35840
	ds_read_b128 v[178:181], v247 offset:36864
	ds_read_b128 v[182:185], v247 offset:37888
	ds_read_b128 v[186:189], v247 offset:38912
	ds_read_b128 v[190:193], v247 offset:39936
	global_load_lds_dwordx4 v[194:195], off
	v_lshl_add_u64 v[194:195], s[14:15], 0, v[214:215]
	s_mov_b32 m0, s4
	s_nop 0
	global_load_lds_dwordx4 v[194:195], off
	s_waitcnt vmcnt(26)
	s_cmp_eq_u32 s100, 0
	s_cbranch_scc1 .Lthird_wait_relaxed_4
	s_waitcnt vmcnt(8)
; #define PG8_STAGE(bufoff, gbase, voff) do { _Pragma("unroll") for (int _i = 0; _i < 2; ++_i) \
;         __builtin_amdgcn_global_load_lds((const unsigned*)((const char*)(gbase) + (voff)[_i]), (PG8_LAS unsigned*)(lds + (bufoff) + ldsw + _i * 8192), 16, 0, 0); } while (0)
; #define PG8_LDA(dst, b, h) do { _Pragma("unroll") for (int m = 0; m < 4; ++m) _Pragma("unroll") for (int k = 0; k < 2; ++k) dst[m][k] = *(const PG8_LAS bf16x8*)(lds + PG8_SA(b, h) + aoff + m * 2048 + k * 1024); } while (0)
; #define PG8_MMA(ai, bj, At, Bt) do { __builtin_amdgcn_s_setprio(1); _Pragma("unroll") for (int m = 0; m < 4; ++m) _Pragma("unroll") for (int n = 0; n < 2; ++n) _Pragma("unroll") for (int k = 0; k < 2; ++k) \
;         acc[ai][bj][m][n] = __builtin_amdgcn_mfma_f32_16x16x32_bf16(Bt[n][k], At[m][k], acc[ai][bj][m][n], 0, 0, 0); __builtin_amdgcn_s_setprio(0); } while (0)
; #define PG8_WAIT_V(n) asm volatile("s_waitcnt vmcnt(" #n ")" ::: "memory")
; #define PG8_WAIT_L(n) asm volatile("s_waitcnt lgkmcnt(" #n ")" ::: "memory")
; #define PG8_BAR __builtin_amdgcn_s_barrier()
; #define PG8_SCHED __builtin_amdgcn_sched_barrier(0)
; template <class Epi, class Sched, bool ALIGN_EPI = false, bool SP2 = false>
; __device__ __forceinline__ void gemm_phase(PG8_LAS unsigned char* lds, const Gemm g, const Sched& S, const Epi& E, const int wave_id) {
;     ...
;             PG8_WAIT_V(8); PG8_WAIT_L(0); PG8_BAR; PG8_MMA(0, 0, At, B0); PG8_MMA(0, 1, At, B1); PG8_BAR; PG8_SCHED;
;             PG8_LDA(At, 1, 1); PG8_STAGE(PG8_SB(1, 0), b3, voffB); PG8_STAGE(PG8_SB(1, 1), b3 + hstep, voffB); PG8_STAGE(PG8_SA(1, 0), a3, voffA);
;             PG8_WAIT_V(8); PG8_WAIT_L(0); PG8_BAR; PG8_MMA(1, 0, At, B0); PG8_MMA(1, 1, At, B1); PG8_BAR; PG8_SCHED;
.Lthird_wait_relaxed_4:
	s_waitcnt lgkmcnt(0)
	s_setprio 1
	s_barrier
	v_mfma_f32_16x16x32_bf16 v[126:129], v[130:133], v[162:165], v[126:129]
	v_mfma_f32_16x16x32_bf16 v[122:125], v[138:141], v[162:165], v[122:125]
	v_mfma_f32_16x16x32_bf16 v[110:113], v[130:133], v[170:173], v[110:113]
	v_mfma_f32_16x16x32_bf16 v[106:109], v[138:141], v[170:173], v[106:109]
	v_mfma_f32_16x16x32_bf16 v[94:97], v[130:133], v[178:181], v[94:97]
	v_mfma_f32_16x16x32_bf16 v[90:93], v[138:141], v[178:181], v[90:93]
	v_mfma_f32_16x16x32_bf16 v[78:81], v[130:133], v[186:189], v[78:81]
	v_mfma_f32_16x16x32_bf16 v[74:77], v[138:141], v[186:189], v[74:77]
	v_mfma_f32_16x16x32_bf16 v[126:129], v[134:137], v[166:169], v[126:129]
	v_mfma_f32_16x16x32_bf16 v[122:125], v[142:145], v[166:169], v[122:125]
	v_mfma_f32_16x16x32_bf16 v[110:113], v[134:137], v[174:177], v[110:113]
	v_mfma_f32_16x16x32_bf16 v[106:109], v[142:145], v[174:177], v[106:109]
	v_mfma_f32_16x16x32_bf16 v[94:97], v[134:137], v[182:185], v[94:97]
	v_mfma_f32_16x16x32_bf16 v[90:93], v[142:145], v[182:185], v[90:93]
	v_mfma_f32_16x16x32_bf16 v[78:81], v[134:137], v[190:193], v[78:81]
	v_mfma_f32_16x16x32_bf16 v[74:77], v[142:145], v[190:193], v[74:77]
	s_setprio 0
	s_setprio 1
	v_mfma_f32_16x16x32_bf16 v[118:121], v[146:149], v[162:165], v[118:121]
	v_mfma_f32_16x16x32_bf16 v[114:117], v[154:157], v[162:165], v[114:117]
	v_mfma_f32_16x16x32_bf16 v[102:105], v[146:149], v[170:173], v[102:105]
	v_mfma_f32_16x16x32_bf16 v[98:101], v[154:157], v[170:173], v[98:101]
	v_mfma_f32_16x16x32_bf16 v[86:89], v[146:149], v[178:181], v[86:89]
	v_mfma_f32_16x16x32_bf16 v[82:85], v[154:157], v[178:181], v[82:85]
	v_mfma_f32_16x16x32_bf16 v[70:73], v[146:149], v[186:189], v[70:73]
	v_mfma_f32_16x16x32_bf16 v[66:69], v[154:157], v[186:189], v[66:69]
	v_mfma_f32_16x16x32_bf16 v[118:121], v[150:153], v[166:169], v[118:121]
	v_mfma_f32_16x16x32_bf16 v[114:117], v[158:161], v[166:169], v[114:117]
	v_mfma_f32_16x16x32_bf16 v[102:105], v[150:153], v[174:177], v[102:105]
	v_mfma_f32_16x16x32_bf16 v[98:101], v[158:161], v[174:177], v[98:101]
	v_mfma_f32_16x16x32_bf16 v[86:89], v[150:153], v[182:185], v[86:89]
	v_mfma_f32_16x16x32_bf16 v[82:85], v[158:161], v[182:185], v[82:85]
	v_mfma_f32_16x16x32_bf16 v[70:73], v[150:153], v[190:193], v[70:73]
	v_mfma_f32_16x16x32_bf16 v[66:69], v[158:161], v[190:193], v[66:69]
	s_setprio 0
	s_barrier
	s_add_i32 s14, s34, s90
	v_lshl_add_u64 v[194:195], v[232:233], 0, s[64:65]
	s_mov_b32 m0, s14
	ds_read_b128 v[162:165], v247 offset:49152
	ds_read_b128 v[166:169], v247 offset:50176
	ds_read_b128 v[170:173], v247 offset:51200
	ds_read_b128 v[174:177], v247 offset:52224
	ds_read_b128 v[178:181], v247 offset:53248
	ds_read_b128 v[182:185], v247 offset:54272
	ds_read_b128 v[186:189], v247 offset:55296
	ds_read_b128 v[190:193], v247 offset:56320
	global_load_lds_dwordx4 v[194:195], off
	s_add_i32 m0, s14, 0x2000
	s_add_u32 s12, s12, 0x40080
	v_lshl_add_u64 v[194:195], v[230:231], 0, s[64:65]
	s_addc_u32 s13, s13, 0
	s_add_i32 s14, s35, s90
	global_load_lds_dwordx4 v[194:195], off
	v_lshl_add_u64 v[194:195], s[12:13], 0, v[212:213]
	s_mov_b32 m0, s14
	s_nop 0
	global_load_lds_dwordx4 v[194:195], off
	v_lshl_add_u64 v[194:195], s[12:13], 0, v[216:217]
	s_add_i32 m0, s14, 0x2000
	s_nop 0
	global_load_lds_dwordx4 v[194:195], off
	v_lshl_add_u64 v[194:195], v[226:227], 0, s[64:65]
	s_mov_b32 m0, s63
	s_nop 0
	global_load_lds_dwordx4 v[194:195], off
	v_lshl_add_u64 v[194:195], v[228:229], 0, s[64:65]
	s_mov_b32 m0, s68
	s_nop 0
	global_load_lds_dwordx4 v[194:195], off
	s_waitcnt vmcnt(8)
	s_waitcnt lgkmcnt(0)
	s_setprio 1
	s_barrier
	v_mfma_f32_16x16x32_bf16 v[62:65], v[130:133], v[162:165], v[62:65]
	v_mfma_f32_16x16x32_bf16 v[58:61], v[138:141], v[162:165], v[58:61]
	v_mfma_f32_16x16x32_bf16 v[46:49], v[130:133], v[170:173], v[46:49]
	v_mfma_f32_16x16x32_bf16 v[42:45], v[138:141], v[170:173], v[42:45]
	v_mfma_f32_16x16x32_bf16 v[30:33], v[130:133], v[178:181], v[30:33]
	v_mfma_f32_16x16x32_bf16 v[26:29], v[138:141], v[178:181], v[26:29]
	v_mfma_f32_16x16x32_bf16 v[14:17], v[130:133], v[186:189], v[14:17]
	v_mfma_f32_16x16x32_bf16 v[10:13], v[138:141], v[186:189], v[10:13]
	v_mfma_f32_16x16x32_bf16 v[62:65], v[134:137], v[166:169], v[62:65]
	v_mfma_f32_16x16x32_bf16 v[58:61], v[142:145], v[166:169], v[58:61]
	v_mfma_f32_16x16x32_bf16 v[46:49], v[134:137], v[174:177], v[46:49]
	v_mfma_f32_16x16x32_bf16 v[42:45], v[142:145], v[174:177], v[42:45]
	v_mfma_f32_16x16x32_bf16 v[30:33], v[134:137], v[182:185], v[30:33]
	v_mfma_f32_16x16x32_bf16 v[26:29], v[142:145], v[182:185], v[26:29]
	v_mfma_f32_16x16x32_bf16 v[14:17], v[134:137], v[190:193], v[14:17]
	v_mfma_f32_16x16x32_bf16 v[10:13], v[142:145], v[190:193], v[10:13]
	s_setprio 0
	s_setprio 1
	v_mfma_f32_16x16x32_bf16 v[54:57], v[146:149], v[162:165], v[54:57]
	v_mfma_f32_16x16x32_bf16 v[50:53], v[154:157], v[162:165], v[50:53]
	v_mfma_f32_16x16x32_bf16 v[38:41], v[146:149], v[170:173], v[38:41]
	v_mfma_f32_16x16x32_bf16 v[34:37], v[154:157], v[170:173], v[34:37]
	v_mfma_f32_16x16x32_bf16 v[22:25], v[146:149], v[178:181], v[22:25]
	v_mfma_f32_16x16x32_bf16 v[18:21], v[154:157], v[178:181], v[18:21]
	v_mfma_f32_16x16x32_bf16 v[6:9], v[146:149], v[186:189], v[6:9]
	v_mfma_f32_16x16x32_bf16 v[2:5], v[154:157], v[186:189], v[2:5]
	v_mfma_f32_16x16x32_bf16 v[54:57], v[150:153], v[166:169], v[54:57]
	v_mfma_f32_16x16x32_bf16 v[50:53], v[158:161], v[166:169], v[50:53]
	v_mfma_f32_16x16x32_bf16 v[38:41], v[150:153], v[174:177], v[38:41]
	v_mfma_f32_16x16x32_bf16 v[34:37], v[158:161], v[174:177], v[34:37]
	v_mfma_f32_16x16x32_bf16 v[22:25], v[150:153], v[182:185], v[22:25]
	v_mfma_f32_16x16x32_bf16 v[18:21], v[158:161], v[182:185], v[18:21]
	v_mfma_f32_16x16x32_bf16 v[6:9], v[150:153], v[190:193], v[6:9]
	v_mfma_f32_16x16x32_bf16 v[2:5], v[158:161], v[190:193], v[2:5]
	s_setprio 0
	s_barrier
	s_add_i32 s40, s40, 2
	s_add_u32 s10, s10, 0x100
	s_addc_u32 s11, s11, 0
	s_cmp_gt_u32 s40, 13
	s_cbranch_scc1 .LBB0_425

; #define PG8_STAGE(bufoff, gbase, voff) do { _Pragma("unroll") for (int _i = 0; _i < 2; ++_i) \
;         __builtin_amdgcn_global_load_lds((const unsigned*)((const char*)(gbase) + (voff)[_i]), (PG8_LAS unsigned*)(lds + (bufoff) + ldsw + _i * 8192), 16, 0, 0); } while (0)
; #define PG8_LDA(dst, b, h) do { _Pragma("unroll") for (int m = 0; m < 4; ++m) _Pragma("unroll") for (int k = 0; k < 2; ++k) dst[m][k] = *(const PG8_LAS bf16x8*)(lds + PG8_SA(b, h) + aoff + m * 2048 + k * 1024); } while (0)
; #define PG8_LDB(dst, b, h) do { _Pragma("unroll") for (int n = 0; n < 2; ++n) _Pragma("unroll") for (int k = 0; k < 2; ++k) dst[n][k] = *(const PG8_LAS bf16x8*)(lds + PG8_SB(b, h) + boff + n * 2048 + k * 1024); } while (0)
; #define PG8_WAIT_V(n) asm volatile("s_waitcnt vmcnt(" #n ")" ::: "memory")
; #define PG8_WAIT_VN(n) asm volatile("s_waitcnt vmcnt(%0)" :: "n"(n) : "memory")
; #define PG8_WAIT_L(n) asm volatile("s_waitcnt lgkmcnt(" #n ")" ::: "memory")
; #define PG8_BAR __builtin_amdgcn_s_barrier()
; template <class Epi, class Sched, bool ALIGN_EPI = false, bool SP2 = false>
; __device__ __forceinline__ void gemm_phase(PG8_LAS unsigned char* lds, const Gemm g, const Sched& S, const Epi& E, const int wave_id) {
;     ...
;             const bool last = (t == nt - 2);
;             const char* a1 = cA + (size_t)(t + 1) * kstep;
;             const char* a2 = last ? nA : cA + (size_t)(t + 2) * kstep; const char* b2 = last ? nB : cB + (size_t)(t + 2) * kstep;
;             const char* a3 = a2 + kstep; const char* b3 = b2 + kstep;
;             if (last && has_next) S.a_ready(nxt);
;             if constexpr (SP2) {
;             int tz_ = __builtin_amdgcn_readfirstlane(t | (ui > 0 ? 0 : 1)); asm volatile("" : "+s"(tz_));
;             const bool strict = !(Epi::NS > 0 && tz_ == 0);
;             PG8_LDB(B0, 0, 0); PG8_LDB(B1, 0, 1); PG8_SCHED; PG8_LDA(At, 0, 0); PG8_STAGE(PG8_SA(1, 1), a1 + hstep, voffA);
;             PG8_WAIT_VN(8 + Epi::NS); if (strict) PG8_WAIT_V(8); PG8_WAIT_L(0); PG8_BAR; PG8_MMA(0, 0, At, B0); PG8_MMA(0, 1, At, B1); PG8_BAR; PG8_SCHED;
;             PG8_LDA(At, 0, 1); PG8_STAGE(PG8_SB(0, 0), b2, voffB); PG8_STAGE(PG8_SB(0, 1), b2 + hstep, voffB); PG8_STAGE(PG8_SA(0, 0), a2, voffA);
;             PG8_WAIT_VN(8 + Epi::NS); if (strict) PG8_WAIT_V(8); PG8_WAIT_L(0); PG8_BAR; PG8_MMA(1, 0, At, B0); PG8_MMA(1, 1, At, B1); PG8_BAR; PG8_SCHED;
.LBB0_423:
	s_add_u32 s12, s8, s10
	s_addc_u32 s13, s9, s11
	s_add_u32 s12, s12, 0x100
	s_addc_u32 s13, s13, 0
	s_add_u32 s41, s36, s10
	s_addc_u32 s42, s37, s11
	s_cmpk_eq_i32 s10, 0x700
	s_cselect_b32 s15, s23, s13
	s_cselect_b32 s14, s29, s12
	s_cselect_b32 s13, s21, s42
	s_cselect_b32 s12, s31, s41
	s_waitcnt lgkmcnt(0)
	s_setprio 1
	s_barrier
	v_mfma_f32_16x16x32_bf16 v[126:129], v[146:149], v[186:189], v[126:129]
	v_mfma_f32_16x16x32_bf16 v[122:125], v[154:157], v[186:189], v[122:125]
	v_mfma_f32_16x16x32_bf16 v[110:113], v[146:149], v[178:181], v[110:113]
	v_mfma_f32_16x16x32_bf16 v[106:109], v[154:157], v[178:181], v[106:109]
	v_mfma_f32_16x16x32_bf16 v[94:97], v[146:149], v[170:173], v[94:97]
	v_mfma_f32_16x16x32_bf16 v[90:93], v[154:157], v[170:173], v[90:93]
	v_mfma_f32_16x16x32_bf16 v[78:81], v[146:149], v[162:165], v[78:81]
	v_mfma_f32_16x16x32_bf16 v[74:77], v[154:157], v[162:165], v[74:77]
	v_mfma_f32_16x16x32_bf16 v[126:129], v[150:153], v[190:193], v[126:129]
	v_mfma_f32_16x16x32_bf16 v[122:125], v[158:161], v[190:193], v[122:125]
	v_mfma_f32_16x16x32_bf16 v[110:113], v[150:153], v[182:185], v[110:113]
	v_mfma_f32_16x16x32_bf16 v[106:109], v[158:161], v[182:185], v[106:109]
	v_mfma_f32_16x16x32_bf16 v[94:97], v[150:153], v[174:177], v[94:97]
	v_mfma_f32_16x16x32_bf16 v[90:93], v[158:161], v[174:177], v[90:93]
	v_mfma_f32_16x16x32_bf16 v[78:81], v[150:153], v[166:169], v[78:81]
	v_mfma_f32_16x16x32_bf16 v[74:77], v[158:161], v[166:169], v[74:77]
	s_setprio 0
	s_setprio 1
	v_mfma_f32_16x16x32_bf16 v[118:121], v[130:133], v[186:189], v[118:121]
	v_mfma_f32_16x16x32_bf16 v[114:117], v[138:141], v[186:189], v[114:117]
	v_mfma_f32_16x16x32_bf16 v[102:105], v[130:133], v[178:181], v[102:105]
	v_mfma_f32_16x16x32_bf16 v[98:101], v[138:141], v[178:181], v[98:101]
	v_mfma_f32_16x16x32_bf16 v[86:89], v[130:133], v[170:173], v[86:89]
	v_mfma_f32_16x16x32_bf16 v[82:85], v[138:141], v[170:173], v[82:85]
	v_mfma_f32_16x16x32_bf16 v[70:73], v[130:133], v[162:165], v[70:73]
	v_mfma_f32_16x16x32_bf16 v[66:69], v[138:141], v[162:165], v[66:69]
	v_mfma_f32_16x16x32_bf16 v[118:121], v[134:137], v[190:193], v[118:121]
	v_mfma_f32_16x16x32_bf16 v[114:117], v[142:145], v[190:193], v[114:117]
	v_mfma_f32_16x16x32_bf16 v[102:105], v[134:137], v[182:185], v[102:105]
	v_mfma_f32_16x16x32_bf16 v[98:101], v[142:145], v[182:185], v[98:101]
	v_mfma_f32_16x16x32_bf16 v[86:89], v[134:137], v[174:177], v[86:89]
	v_mfma_f32_16x16x32_bf16 v[82:85], v[142:145], v[174:177], v[82:85]
	v_mfma_f32_16x16x32_bf16 v[70:73], v[134:137], v[166:169], v[70:73]
	v_mfma_f32_16x16x32_bf16 v[66:69], v[142:145], v[166:169], v[66:69]
	s_setprio 0
	s_barrier
	s_mov_b32 m0, s94
	v_lshl_add_u64 v[232:233], s[12:13], 0, v[212:213]
	s_add_u32 s42, s12, 0x40000
	ds_read_b128 v[186:189], v247 offset:16384
	ds_read_b128 v[190:193], v247 offset:17408
	ds_read_b128 v[178:181], v247 offset:18432
	ds_read_b128 v[182:185], v247 offset:19456
	ds_read_b128 v[170:173], v247 offset:20480
	ds_read_b128 v[174:177], v247 offset:21504
	ds_read_b128 v[162:165], v247 offset:22528
	ds_read_b128 v[166:169], v247 offset:23552
	global_load_lds_dwordx4 v[232:233], off
	v_lshl_add_u64 v[230:231], s[12:13], 0, v[216:217]
	s_mov_b32 m0, s95
	s_addc_u32 s43, s13, 0
	global_load_lds_dwordx4 v[230:231], off
	v_lshl_add_u64 v[194:195], s[42:43], 0, v[212:213]
	s_mov_b32 m0, s38
	v_lshl_add_u64 v[226:227], s[14:15], 0, v[210:211]
	global_load_lds_dwordx4 v[194:195], off
	v_lshl_add_u64 v[194:195], s[42:43], 0, v[216:217]
	s_mov_b32 m0, s39
	v_lshl_add_u64 v[228:229], s[14:15], 0, v[214:215]
	global_load_lds_dwordx4 v[194:195], off
	s_mov_b32 m0, s91
	s_andn2_b64 vcc, exec, s[34:35]
	global_load_lds_dwordx4 v[226:227], off
	s_mov_b32 m0, s2
	s_nop 0
	global_load_lds_dwordx4 v[228:229], off
	s_waitcnt vmcnt(24)
	s_cbranch_vccnz .LBB0_420
	s_waitcnt vmcnt(8)
	s_branch .LBB0_420

; #define PG8_STAGE(bufoff, gbase, voff) do { _Pragma("unroll") for (int _i = 0; _i < 2; ++_i) \
;         __builtin_amdgcn_global_load_lds((const unsigned*)((const char*)(gbase) + (voff)[_i]), (PG8_LAS unsigned*)(lds + (bufoff) + ldsw + _i * 8192), 16, 0, 0); } while (0)
; #define PG8_LDA(dst, b, h) do { _Pragma("unroll") for (int m = 0; m < 4; ++m) _Pragma("unroll") for (int k = 0; k < 2; ++k) dst[m][k] = *(const PG8_LAS bf16x8*)(lds + PG8_SA(b, h) + aoff + m * 2048 + k * 1024); } while (0)
; #define PG8_LDB(dst, b, h) do { _Pragma("unroll") for (int n = 0; n < 2; ++n) _Pragma("unroll") for (int k = 0; k < 2; ++k) dst[n][k] = *(const PG8_LAS bf16x8*)(lds + PG8_SB(b, h) + boff + n * 2048 + k * 1024); } while (0)
; #define PG8_MMA(ai, bj, At, Bt) do { __builtin_amdgcn_s_setprio(1); _Pragma("unroll") for (int m = 0; m < 4; ++m) _Pragma("unroll") for (int n = 0; n < 2; ++n) _Pragma("unroll") for (int k = 0; k < 2; ++k) \
;         acc[ai][bj][m][n] = __builtin_amdgcn_mfma_f32_16x16x32_bf16(Bt[n][k], At[m][k], acc[ai][bj][m][n], 0, 0, 0); __builtin_amdgcn_s_setprio(0); } while (0)
; #define PG8_WAIT_V(n) asm volatile("s_waitcnt vmcnt(" #n ")" ::: "memory")
; #define PG8_WAIT_VN(n) asm volatile("s_waitcnt vmcnt(%0)" :: "n"(n) : "memory")
; #define PG8_WAIT_L(n) asm volatile("s_waitcnt lgkmcnt(" #n ")" ::: "memory")
; #define PG8_BAR __builtin_amdgcn_s_barrier()
; #define PG8_SCHED __builtin_amdgcn_sched_barrier(0)
; template <class Epi, class Sched, bool ALIGN_EPI = false, bool SP2 = false>
; __device__ __forceinline__ void gemm_phase(PG8_LAS unsigned char* lds, const Gemm g, const Sched& S, const Epi& E, const int wave_id) {
;     ...
;             PG8_WAIT_VN(8 + Epi::NS); if (strict) PG8_WAIT_V(8); PG8_WAIT_L(0); PG8_BAR; PG8_MMA(1, 0, At, B0); PG8_MMA(1, 1, At, B1); PG8_BAR; PG8_SCHED;
;             PG8_LDB(B0, 1, 0); PG8_LDB(B1, 1, 1); PG8_SCHED; PG8_LDA(At, 1, 0); PG8_STAGE(PG8_SA(0, 1), a2 + hstep, voffA);
;             PG8_WAIT_V(8); PG8_WAIT_L(0); PG8_BAR; PG8_MMA(0, 0, At, B0); PG8_MMA(0, 1, At, B1); PG8_BAR; PG8_SCHED;
.LBB0_1504:
	s_waitcnt lgkmcnt(0)
	s_setprio 1
	s_barrier
	v_mfma_f32_16x16x32_bf16 v[62:65], v[146:149], v[186:189], v[62:65]
	v_mfma_f32_16x16x32_bf16 v[58:61], v[154:157], v[186:189], v[58:61]
	v_mfma_f32_16x16x32_bf16 v[46:49], v[146:149], v[178:181], v[46:49]
	v_mfma_f32_16x16x32_bf16 v[42:45], v[154:157], v[178:181], v[42:45]
	v_mfma_f32_16x16x32_bf16 v[30:33], v[146:149], v[170:173], v[30:33]
	v_mfma_f32_16x16x32_bf16 v[26:29], v[154:157], v[170:173], v[26:29]
	v_mfma_f32_16x16x32_bf16 v[14:17], v[146:149], v[162:165], v[14:17]
	v_mfma_f32_16x16x32_bf16 v[10:13], v[154:157], v[162:165], v[10:13]
	v_mfma_f32_16x16x32_bf16 v[62:65], v[150:153], v[190:193], v[62:65]
	v_mfma_f32_16x16x32_bf16 v[58:61], v[158:161], v[190:193], v[58:61]
	v_mfma_f32_16x16x32_bf16 v[46:49], v[150:153], v[182:185], v[46:49]
	v_mfma_f32_16x16x32_bf16 v[42:45], v[158:161], v[182:185], v[42:45]
	v_mfma_f32_16x16x32_bf16 v[30:33], v[150:153], v[174:177], v[30:33]
	v_mfma_f32_16x16x32_bf16 v[26:29], v[158:161], v[174:177], v[26:29]
	v_mfma_f32_16x16x32_bf16 v[14:17], v[150:153], v[166:169], v[14:17]
	v_mfma_f32_16x16x32_bf16 v[10:13], v[158:161], v[166:169], v[10:13]
	s_setprio 0
	s_setprio 1
	v_mfma_f32_16x16x32_bf16 v[54:57], v[130:133], v[186:189], v[54:57]
	v_mfma_f32_16x16x32_bf16 v[50:53], v[138:141], v[186:189], v[50:53]
	v_mfma_f32_16x16x32_bf16 v[38:41], v[130:133], v[178:181], v[38:41]
	v_mfma_f32_16x16x32_bf16 v[34:37], v[138:141], v[178:181], v[34:37]
	v_mfma_f32_16x16x32_bf16 v[22:25], v[130:133], v[170:173], v[22:25]
	v_mfma_f32_16x16x32_bf16 v[18:21], v[138:141], v[170:173], v[18:21]
	v_mfma_f32_16x16x32_bf16 v[6:9], v[130:133], v[162:165], v[6:9]
	v_mfma_f32_16x16x32_bf16 v[2:5], v[138:141], v[162:165], v[2:5]
	v_mfma_f32_16x16x32_bf16 v[54:57], v[134:137], v[190:193], v[54:57]
	v_mfma_f32_16x16x32_bf16 v[50:53], v[142:145], v[190:193], v[50:53]
	v_mfma_f32_16x16x32_bf16 v[38:41], v[134:137], v[182:185], v[38:41]
	v_mfma_f32_16x16x32_bf16 v[34:37], v[142:145], v[182:185], v[34:37]
	v_mfma_f32_16x16x32_bf16 v[22:25], v[134:137], v[174:177], v[22:25]
	v_mfma_f32_16x16x32_bf16 v[18:21], v[142:145], v[174:177], v[18:21]
	v_mfma_f32_16x16x32_bf16 v[6:9], v[134:137], v[166:169], v[6:9]
	v_mfma_f32_16x16x32_bf16 v[2:5], v[142:145], v[166:169], v[2:5]
	s_setprio 0
	s_barrier
	s_add_i32 s20, 0, 0x18000
	s_add_i32 s21, 0, 0x1c000
	v_add_u32_e32 v142, s20, v1
	v_add_u32_e32 v158, s21, v1
	ds_read_b128 v[130:133], v142
	ds_read_b128 v[134:137], v142 offset:1024
	ds_read_b128 v[138:141], v142 offset:2048
	ds_read_b128 v[142:145], v142 offset:3072
	ds_read_b128 v[146:149], v158
	ds_read_b128 v[150:153], v158 offset:1024
	ds_read_b128 v[154:157], v158 offset:2048
	ds_read_b128 v[158:161], v158 offset:3072
	s_add_u32 s18, s18, 0x40000
	s_addc_u32 s19, s19, 0
	s_mov_b32 m0, s35
	v_lshl_add_u64 v[194:195], s[18:19], 0, v[216:217]
	ds_read_b128 v[162:165], v232 offset:32768
	ds_read_b128 v[166:169], v232 offset:33792
	ds_read_b128 v[170:173], v232 offset:34816
	ds_read_b128 v[174:177], v232 offset:35840
	ds_read_b128 v[178:181], v232 offset:36864
	ds_read_b128 v[182:185], v232 offset:37888
	ds_read_b128 v[186:189], v232 offset:38912
	ds_read_b128 v[190:193], v232 offset:39936
	global_load_lds_dwordx4 v[194:195], off
	v_lshl_add_u64 v[194:195], s[18:19], 0, v[212:213]
	s_mov_b32 m0, s36
	s_nop 0
	global_load_lds_dwordx4 v[194:195], off
	s_waitcnt vmcnt(8)
	s_waitcnt lgkmcnt(0)
	s_setprio 1
	s_barrier
	v_mfma_f32_16x16x32_bf16 v[126:129], v[130:133], v[162:165], v[126:129]
	v_mfma_f32_16x16x32_bf16 v[122:125], v[138:141], v[162:165], v[122:125]
	v_mfma_f32_16x16x32_bf16 v[110:113], v[130:133], v[170:173], v[110:113]
	v_mfma_f32_16x16x32_bf16 v[106:109], v[138:141], v[170:173], v[106:109]
	v_mfma_f32_16x16x32_bf16 v[94:97], v[130:133], v[178:181], v[94:97]
	v_mfma_f32_16x16x32_bf16 v[90:93], v[138:141], v[178:181], v[90:93]
	v_mfma_f32_16x16x32_bf16 v[78:81], v[130:133], v[186:189], v[78:81]
	v_mfma_f32_16x16x32_bf16 v[74:77], v[138:141], v[186:189], v[74:77]
	v_mfma_f32_16x16x32_bf16 v[126:129], v[134:137], v[166:169], v[126:129]
	v_mfma_f32_16x16x32_bf16 v[122:125], v[142:145], v[166:169], v[122:125]
	v_mfma_f32_16x16x32_bf16 v[110:113], v[134:137], v[174:177], v[110:113]
	v_mfma_f32_16x16x32_bf16 v[106:109], v[142:145], v[174:177], v[106:109]
	v_mfma_f32_16x16x32_bf16 v[94:97], v[134:137], v[182:185], v[94:97]
	v_mfma_f32_16x16x32_bf16 v[90:93], v[142:145], v[182:185], v[90:93]
	v_mfma_f32_16x16x32_bf16 v[78:81], v[134:137], v[190:193], v[78:81]
	v_mfma_f32_16x16x32_bf16 v[74:77], v[142:145], v[190:193], v[74:77]
	s_setprio 0
	s_setprio 1
	v_mfma_f32_16x16x32_bf16 v[118:121], v[146:149], v[162:165], v[118:121]
	v_mfma_f32_16x16x32_bf16 v[114:117], v[154:157], v[162:165], v[114:117]
	v_mfma_f32_16x16x32_bf16 v[102:105], v[146:149], v[170:173], v[102:105]
	v_mfma_f32_16x16x32_bf16 v[98:101], v[154:157], v[170:173], v[98:101]
	v_mfma_f32_16x16x32_bf16 v[86:89], v[146:149], v[178:181], v[86:89]
	v_mfma_f32_16x16x32_bf16 v[82:85], v[154:157], v[178:181], v[82:85]
	v_mfma_f32_16x16x32_bf16 v[70:73], v[146:149], v[186:189], v[70:73]
	v_mfma_f32_16x16x32_bf16 v[66:69], v[154:157], v[186:189], v[66:69]
	v_mfma_f32_16x16x32_bf16 v[118:121], v[150:153], v[166:169], v[118:121]
	v_mfma_f32_16x16x32_bf16 v[114:117], v[158:161], v[166:169], v[114:117]
	v_mfma_f32_16x16x32_bf16 v[102:105], v[150:153], v[174:177], v[102:105]
	v_mfma_f32_16x16x32_bf16 v[98:101], v[158:161], v[174:177], v[98:101]
	v_mfma_f32_16x16x32_bf16 v[86:89], v[150:153], v[182:185], v[86:89]
	v_mfma_f32_16x16x32_bf16 v[82:85], v[158:161], v[182:185], v[82:85]
	v_mfma_f32_16x16x32_bf16 v[70:73], v[150:153], v[190:193], v[70:73]
	v_mfma_f32_16x16x32_bf16 v[66:69], v[158:161], v[190:193], v[66:69]
	s_setprio 0
	s_barrier
; #define PG8_STAGE(bufoff, gbase, voff) do { _Pragma("unroll") for (int _i = 0; _i < 2; ++_i) \
;         __builtin_amdgcn_global_load_lds((const unsigned*)((const char*)(gbase) + (voff)[_i]), (PG8_LAS unsigned*)(lds + (bufoff) + ldsw + _i * 8192), 16, 0, 0); } while (0)
; #define PG8_LDA(dst, b, h) do { _Pragma("unroll") for (int m = 0; m < 4; ++m) _Pragma("unroll") for (int k = 0; k < 2; ++k) dst[m][k] = *(const PG8_LAS bf16x8*)(lds + PG8_SA(b, h) + aoff + m * 2048 + k * 1024); } while (0)
; #define PG8_MMA(ai, bj, At, Bt) do { __builtin_amdgcn_s_setprio(1); _Pragma("unroll") for (int m = 0; m < 4; ++m) _Pragma("unroll") for (int n = 0; n < 2; ++n) _Pragma("unroll") for (int k = 0; k < 2; ++k) \
;         acc[ai][bj][m][n] = __builtin_amdgcn_mfma_f32_16x16x32_bf16(Bt[n][k], At[m][k], acc[ai][bj][m][n], 0, 0, 0); __builtin_amdgcn_s_setprio(0); } while (0)
; #define PG8_WAIT_V(n) asm volatile("s_waitcnt vmcnt(" #n ")" ::: "memory")
; #define PG8_WAIT_L(n) asm volatile("s_waitcnt lgkmcnt(" #n ")" ::: "memory")
; #define PG8_BAR __builtin_amdgcn_s_barrier()
; #define PG8_SCHED __builtin_amdgcn_sched_barrier(0)
; template <class Epi, class Sched, bool ALIGN_EPI = false, bool SP2 = false>
; __device__ __forceinline__ void gemm_phase(PG8_LAS unsigned char* lds, const Gemm g, const Sched& S, const Epi& E, const int wave_id) {
;     ...
;             PG8_LDA(At, 1, 1); PG8_STAGE(PG8_SB(1, 0), b3, voffB); PG8_STAGE(PG8_SB(1, 1), b3 + hstep, voffB); PG8_STAGE(PG8_SA(1, 0), a3, voffA);
;             PG8_WAIT_V(8); PG8_WAIT_L(0); PG8_BAR; PG8_MMA(1, 0, At, B0); PG8_MMA(1, 1, At, B1); PG8_BAR; PG8_SCHED;
	s_add_i32 s18, s20, s24
	v_lshl_add_u64 v[194:195], v[228:229], 0, s[64:65]
	s_mov_b32 m0, s18
	ds_read_b128 v[162:165], v232 offset:49152
	ds_read_b128 v[166:169], v232 offset:50176
	ds_read_b128 v[170:173], v232 offset:51200
	ds_read_b128 v[174:177], v232 offset:52224
	ds_read_b128 v[178:181], v232 offset:53248
	ds_read_b128 v[182:185], v232 offset:54272
	ds_read_b128 v[186:189], v232 offset:55296
	ds_read_b128 v[190:193], v232 offset:56320
	global_load_lds_dwordx4 v[194:195], off
	s_add_i32 m0, s18, 0x2000
	s_add_u32 s16, s16, 0x40080
	v_lshl_add_u64 v[194:195], v[226:227], 0, s[64:65]
	s_addc_u32 s17, s17, 0
	s_add_i32 s18, s21, s24
	global_load_lds_dwordx4 v[194:195], off
	v_lshl_add_u64 v[194:195], s[16:17], 0, v[214:215]
	s_mov_b32 m0, s18
	s_nop 0
	global_load_lds_dwordx4 v[194:195], off
	v_lshl_add_u64 v[194:195], s[16:17], 0, v[210:211]
	s_add_i32 m0, s18, 0x2000
	s_nop 0
	global_load_lds_dwordx4 v[194:195], off
	v_lshl_add_u64 v[194:195], v[222:223], 0, s[64:65]
	s_mov_b32 m0, s37
	s_nop 0
	global_load_lds_dwordx4 v[194:195], off
	v_lshl_add_u64 v[194:195], v[224:225], 0, s[64:65]
	s_mov_b32 m0, s38
	s_nop 0
	global_load_lds_dwordx4 v[194:195], off
	s_waitcnt vmcnt(8)
	s_waitcnt lgkmcnt(0)
	s_setprio 1
	s_barrier
	v_mfma_f32_16x16x32_bf16 v[62:65], v[130:133], v[162:165], v[62:65]
	v_mfma_f32_16x16x32_bf16 v[58:61], v[138:141], v[162:165], v[58:61]
	v_mfma_f32_16x16x32_bf16 v[46:49], v[130:133], v[170:173], v[46:49]
	v_mfma_f32_16x16x32_bf16 v[42:45], v[138:141], v[170:173], v[42:45]
	v_mfma_f32_16x16x32_bf16 v[30:33], v[130:133], v[178:181], v[30:33]
	v_mfma_f32_16x16x32_bf16 v[26:29], v[138:141], v[178:181], v[26:29]
	v_mfma_f32_16x16x32_bf16 v[14:17], v[130:133], v[186:189], v[14:17]
	v_mfma_f32_16x16x32_bf16 v[10:13], v[138:141], v[186:189], v[10:13]
	v_mfma_f32_16x16x32_bf16 v[62:65], v[134:137], v[166:169], v[62:65]
	v_mfma_f32_16x16x32_bf16 v[58:61], v[142:145], v[166:169], v[58:61]
	v_mfma_f32_16x16x32_bf16 v[46:49], v[134:137], v[174:177], v[46:49]
	v_mfma_f32_16x16x32_bf16 v[42:45], v[142:145], v[174:177], v[42:45]
	v_mfma_f32_16x16x32_bf16 v[30:33], v[134:137], v[182:185], v[30:33]
	v_mfma_f32_16x16x32_bf16 v[26:29], v[142:145], v[182:185], v[26:29]
	v_mfma_f32_16x16x32_bf16 v[14:17], v[134:137], v[190:193], v[14:17]
	v_mfma_f32_16x16x32_bf16 v[10:13], v[142:145], v[190:193], v[10:13]
	s_setprio 0
	s_setprio 1
	v_mfma_f32_16x16x32_bf16 v[54:57], v[146:149], v[162:165], v[54:57]
	v_mfma_f32_16x16x32_bf16 v[50:53], v[154:157], v[162:165], v[50:53]
	v_mfma_f32_16x16x32_bf16 v[38:41], v[146:149], v[170:173], v[38:41]
	v_mfma_f32_16x16x32_bf16 v[34:37], v[154:157], v[170:173], v[34:37]
	v_mfma_f32_16x16x32_bf16 v[22:25], v[146:149], v[178:181], v[22:25]
	v_mfma_f32_16x16x32_bf16 v[18:21], v[154:157], v[178:181], v[18:21]
	v_mfma_f32_16x16x32_bf16 v[6:9], v[146:149], v[186:189], v[6:9]
	v_mfma_f32_16x16x32_bf16 v[2:5], v[154:157], v[186:189], v[2:5]
	v_mfma_f32_16x16x32_bf16 v[54:57], v[150:153], v[166:169], v[54:57]
	v_mfma_f32_16x16x32_bf16 v[50:53], v[158:161], v[166:169], v[50:53]
	v_mfma_f32_16x16x32_bf16 v[38:41], v[150:153], v[174:177], v[38:41]
	v_mfma_f32_16x16x32_bf16 v[34:37], v[158:161], v[174:177], v[34:37]
	v_mfma_f32_16x16x32_bf16 v[22:25], v[150:153], v[182:185], v[22:25]
	v_mfma_f32_16x16x32_bf16 v[18:21], v[158:161], v[182:185], v[18:21]
	v_mfma_f32_16x16x32_bf16 v[6:9], v[150:153], v[190:193], v[6:9]
	v_mfma_f32_16x16x32_bf16 v[2:5], v[158:161], v[190:193], v[2:5]
	s_setprio 0
	s_barrier
	s_add_u32 s12, s12, 0x100
	s_addc_u32 s13, s13, 0
	s_cmp_gt_u32 s43, 13
	s_cbranch_scc1 .LBB0_1526

; #define PG8_STAGE(bufoff, gbase, voff) do { _Pragma("unroll") for (int _i = 0; _i < 2; ++_i) \
;         __builtin_amdgcn_global_load_lds((const unsigned*)((const char*)(gbase) + (voff)[_i]), (PG8_LAS unsigned*)(lds + (bufoff) + ldsw + _i * 8192), 16, 0, 0); } while (0)
; #define PG8_LDA(dst, b, h) do { _Pragma("unroll") for (int m = 0; m < 4; ++m) _Pragma("unroll") for (int k = 0; k < 2; ++k) dst[m][k] = *(const PG8_LAS bf16x8*)(lds + PG8_SA(b, h) + aoff + m * 2048 + k * 1024); } while (0)
; #define PG8_LDB(dst, b, h) do { _Pragma("unroll") for (int n = 0; n < 2; ++n) _Pragma("unroll") for (int k = 0; k < 2; ++k) dst[n][k] = *(const PG8_LAS bf16x8*)(lds + PG8_SB(b, h) + boff + n * 2048 + k * 1024); } while (0)
; #define PG8_WAIT_V(n) asm volatile("s_waitcnt vmcnt(" #n ")" ::: "memory")
; #define PG8_WAIT_VN(n) asm volatile("s_waitcnt vmcnt(%0)" :: "n"(n) : "memory")
; #define PG8_WAIT_L(n) asm volatile("s_waitcnt lgkmcnt(" #n ")" ::: "memory")
; #define PG8_BAR __builtin_amdgcn_s_barrier()
; template <class Epi, class Sched, bool ALIGN_EPI = false, bool SP2 = false>
; __device__ __forceinline__ void gemm_phase(PG8_LAS unsigned char* lds, const Gemm g, const Sched& S, const Epi& E, const int wave_id) {
;     ...
;             const bool last = (t == nt - 2);
;             const char* a1 = cA + (size_t)(t + 1) * kstep;
;             const char* a2 = last ? nA : cA + (size_t)(t + 2) * kstep; const char* b2 = last ? nB : cB + (size_t)(t + 2) * kstep;
;             const char* a3 = a2 + kstep; const char* b3 = b2 + kstep;
;             if (last && has_next) S.a_ready(nxt);
;             if constexpr (SP2) {
;             int tz_ = __builtin_amdgcn_readfirstlane(t | (ui > 0 ? 0 : 1)); asm volatile("" : "+s"(tz_));
;             const bool strict = !(Epi::NS > 0 && tz_ == 0);
;             PG8_LDB(B0, 0, 0); PG8_LDB(B1, 0, 1); PG8_SCHED; PG8_LDA(At, 0, 0); PG8_STAGE(PG8_SA(1, 1), a1 + hstep, voffA);
;             PG8_WAIT_VN(8 + Epi::NS); if (strict) PG8_WAIT_V(8); PG8_WAIT_L(0); PG8_BAR; PG8_MMA(0, 0, At, B0); PG8_MMA(0, 1, At, B1); PG8_BAR; PG8_SCHED;
;             PG8_LDA(At, 0, 1); PG8_STAGE(PG8_SB(0, 0), b2, voffB); PG8_STAGE(PG8_SB(0, 1), b2 + hstep, voffB); PG8_STAGE(PG8_SA(0, 0), a2, voffA);
;             PG8_WAIT_VN(8 + Epi::NS); if (strict) PG8_WAIT_V(8); PG8_WAIT_L(0); PG8_BAR; PG8_MMA(1, 0, At, B0); PG8_MMA(1, 1, At, B1); PG8_BAR; PG8_SCHED;
.LBB0_1507:
	s_add_u32 s16, s41, s12
	s_addc_u32 s17, s42, s13
	s_add_u32 s16, s16, 0x8f2c0100
	s_addc_u32 s17, s17, 0
	s_add_u32 s49, s39, s12
	s_addc_u32 s50, s40, s13
	s_cmpk_eq_i32 s12, 0x700
	s_cselect_b32 s19, s11, s17
	s_cselect_b32 s18, s10, s16
	s_cselect_b32 s17, s9, s50
	s_cselect_b32 s16, s8, s49
	s_waitcnt lgkmcnt(0)
	s_setprio 1
	s_barrier
	v_mfma_f32_16x16x32_bf16 v[126:129], v[146:149], v[186:189], v[126:129]
	v_mfma_f32_16x16x32_bf16 v[122:125], v[154:157], v[186:189], v[122:125]
	v_mfma_f32_16x16x32_bf16 v[110:113], v[146:149], v[178:181], v[110:113]
	v_mfma_f32_16x16x32_bf16 v[106:109], v[154:157], v[178:181], v[106:109]
	v_mfma_f32_16x16x32_bf16 v[94:97], v[146:149], v[170:173], v[94:97]
	v_mfma_f32_16x16x32_bf16 v[90:93], v[154:157], v[170:173], v[90:93]
	v_mfma_f32_16x16x32_bf16 v[78:81], v[146:149], v[162:165], v[78:81]
	v_mfma_f32_16x16x32_bf16 v[74:77], v[154:157], v[162:165], v[74:77]
	v_mfma_f32_16x16x32_bf16 v[126:129], v[150:153], v[190:193], v[126:129]
	v_mfma_f32_16x16x32_bf16 v[122:125], v[158:161], v[190:193], v[122:125]
	v_mfma_f32_16x16x32_bf16 v[110:113], v[150:153], v[182:185], v[110:113]
	v_mfma_f32_16x16x32_bf16 v[106:109], v[158:161], v[182:185], v[106:109]
	v_mfma_f32_16x16x32_bf16 v[94:97], v[150:153], v[174:177], v[94:97]
	v_mfma_f32_16x16x32_bf16 v[90:93], v[158:161], v[174:177], v[90:93]
	v_mfma_f32_16x16x32_bf16 v[78:81], v[150:153], v[166:169], v[78:81]
	v_mfma_f32_16x16x32_bf16 v[74:77], v[158:161], v[166:169], v[74:77]
	s_setprio 0
	s_setprio 1
	v_mfma_f32_16x16x32_bf16 v[118:121], v[130:133], v[186:189], v[118:121]
	v_mfma_f32_16x16x32_bf16 v[114:117], v[138:141], v[186:189], v[114:117]
	v_mfma_f32_16x16x32_bf16 v[102:105], v[130:133], v[178:181], v[102:105]
	v_mfma_f32_16x16x32_bf16 v[98:101], v[138:141], v[178:181], v[98:101]
	v_mfma_f32_16x16x32_bf16 v[86:89], v[130:133], v[170:173], v[86:89]
	v_mfma_f32_16x16x32_bf16 v[82:85], v[138:141], v[170:173], v[82:85]
	v_mfma_f32_16x16x32_bf16 v[70:73], v[130:133], v[162:165], v[70:73]
	v_mfma_f32_16x16x32_bf16 v[66:69], v[138:141], v[162:165], v[66:69]
	v_mfma_f32_16x16x32_bf16 v[118:121], v[134:137], v[190:193], v[118:121]
	v_mfma_f32_16x16x32_bf16 v[114:117], v[142:145], v[190:193], v[114:117]
	v_mfma_f32_16x16x32_bf16 v[102:105], v[134:137], v[182:185], v[102:105]
	v_mfma_f32_16x16x32_bf16 v[98:101], v[142:145], v[182:185], v[98:101]
	v_mfma_f32_16x16x32_bf16 v[86:89], v[134:137], v[174:177], v[86:89]
	v_mfma_f32_16x16x32_bf16 v[82:85], v[142:145], v[174:177], v[82:85]
	v_mfma_f32_16x16x32_bf16 v[70:73], v[134:137], v[166:169], v[70:73]
	v_mfma_f32_16x16x32_bf16 v[66:69], v[142:145], v[166:169], v[66:69]
	s_setprio 0
	s_barrier
	s_mov_b32 m0, s26
	v_lshl_add_u64 v[228:229], s[16:17], 0, v[214:215]
	s_add_u32 s50, s16, 0x40000
	ds_read_b128 v[186:189], v232 offset:16384
	ds_read_b128 v[190:193], v232 offset:17408
	ds_read_b128 v[178:181], v232 offset:18432
	ds_read_b128 v[182:185], v232 offset:19456
	ds_read_b128 v[170:173], v232 offset:20480
	ds_read_b128 v[174:177], v232 offset:21504
	ds_read_b128 v[162:165], v232 offset:22528
	ds_read_b128 v[166:169], v232 offset:23552
	global_load_lds_dwordx4 v[228:229], off
	v_lshl_add_u64 v[226:227], s[16:17], 0, v[210:211]
	s_mov_b32 m0, s27
	s_addc_u32 s51, s17, 0
	global_load_lds_dwordx4 v[226:227], off
	v_lshl_add_u64 v[194:195], s[50:51], 0, v[214:215]
	s_mov_b32 m0, s29
	v_lshl_add_u64 v[222:223], s[18:19], 0, v[216:217]
	global_load_lds_dwordx4 v[194:195], off
	v_lshl_add_u64 v[194:195], s[50:51], 0, v[210:211]
	s_mov_b32 m0, s30
	v_lshl_add_u64 v[224:225], s[18:19], 0, v[212:213]
	global_load_lds_dwordx4 v[194:195], off
	s_mov_b32 m0, s25
	s_andn2_b64 vcc, exec, s[20:21]
	global_load_lds_dwordx4 v[222:223], off
	s_mov_b32 m0, s34
	s_nop 0
	global_load_lds_dwordx4 v[224:225], off
	s_waitcnt vmcnt(24)
	s_cbranch_vccnz .LBB0_1504
	s_waitcnt vmcnt(8)
	s_branch .LBB0_1504

; #define PG8_STAGE(bufoff, gbase, voff) do { _Pragma("unroll") for (int _i = 0; _i < 2; ++_i) \
;         __builtin_amdgcn_global_load_lds((const unsigned*)((const char*)(gbase) + (voff)[_i]), (PG8_LAS unsigned*)(lds + (bufoff) + ldsw + _i * 8192), 16, 0, 0); } while (0)
; #define PG8_LDA(dst, b, h) do { _Pragma("unroll") for (int m = 0; m < 4; ++m) _Pragma("unroll") for (int k = 0; k < 2; ++k) dst[m][k] = *(const PG8_LAS bf16x8*)(lds + PG8_SA(b, h) + aoff + m * 2048 + k * 1024); } while (0)
; #define PG8_LDB(dst, b, h) do { _Pragma("unroll") for (int n = 0; n < 2; ++n) _Pragma("unroll") for (int k = 0; k < 2; ++k) dst[n][k] = *(const PG8_LAS bf16x8*)(lds + PG8_SB(b, h) + boff + n * 2048 + k * 1024); } while (0)
; #define PG8_WAIT_V(n) asm volatile("s_waitcnt vmcnt(" #n ")" ::: "memory")
; #define PG8_WAIT_VN(n) asm volatile("s_waitcnt vmcnt(%0)" :: "n"(n) : "memory")
; #define PG8_WAIT_L(n) asm volatile("s_waitcnt lgkmcnt(" #n ")" ::: "memory")
; template <class Epi, class Sched, bool ALIGN_EPI = false, bool SP2 = false>
; __device__ __forceinline__ void gemm_phase(PG8_LAS unsigned char* lds, const Gemm g, const Sched& S, const Epi& E, const int wave_id) {
;     ...
;         for (int t = 0; t < nt; t += 2) {
;             const bool last = (t == nt - 2);
;             const char* a1 = cA + (size_t)(t + 1) * kstep;
;             const char* a2 = last ? nA : cA + (size_t)(t + 2) * kstep; const char* b2 = last ? nB : cB + (size_t)(t + 2) * kstep;
;             const char* a3 = a2 + kstep; const char* b3 = b2 + kstep;
;             if (last && has_next) S.a_ready(nxt);
;             if constexpr (SP2) {
;             int tz_ = __builtin_amdgcn_readfirstlane(t | (ui > 0 ? 0 : 1)); asm volatile("" : "+s"(tz_));
;             const bool strict = !(Epi::NS > 0 && tz_ == 0);
;             PG8_LDB(B0, 0, 0); PG8_LDB(B1, 0, 1); PG8_SCHED; PG8_LDA(At, 0, 0); PG8_STAGE(PG8_SA(1, 1), a1 + hstep, voffA);
;             PG8_WAIT_VN(8 + Epi::NS); if (strict) PG8_WAIT_V(8); PG8_WAIT_L(0); PG8_BAR; PG8_MMA(0, 0, At, B0); PG8_MMA(0, 1, At, B1); PG8_BAR; PG8_SCHED;
;             PG8_LDA(At, 0, 1); PG8_STAGE(PG8_SB(0, 0), b2, voffB); PG8_STAGE(PG8_SB(0, 1), b2 + hstep, voffB); PG8_STAGE(PG8_SA(0, 0), a2, voffA);
;             PG8_WAIT_VN(8 + Epi::NS); if (strict) PG8_WAIT_V(8); PG8_WAIT_L(0); PG8_BAR; PG8_MMA(1, 0, At, B0); PG8_MMA(1, 1, At, B1); PG8_BAR; PG8_SCHED;
.LBB0_1537:
	s_add_u32 s12, s8, s10
	s_addc_u32 s13, s9, s11
	s_add_u32 s12, s12, 0x100
	s_addc_u32 s13, s13, 0
	s_add_u32 s53, s67, s10
	s_addc_u32 s76, s68, s11
	s_add_i32 s69, s69, 2
	s_add_i32 s78, 0, 0x10000
	v_add_u32_e32 v147, s69, v146
	s_cmpk_eq_i32 s10, 0x700
	s_cselect_b32 s26, s57, s12
	v_readfirstlane_b32 s12, v147
	s_cselect_b32 s27, s56, s13
	v_add_u32_e32 v147, s78, v163
	s_cselect_b32 s13, s62, s76
	s_cselect_b32 s12, s63, s53
	s_add_i32 s53, 0, 0x14000
	ds_read_b128 v[148:151], v147
	ds_read_b128 v[152:155], v147 offset:1024
	ds_read_b128 v[156:159], v147 offset:2048
	ds_read_b128 v[166:169], v147 offset:3072
	v_add_u32_e32 v147, s53, v163
	ds_read_b128 v[170:173], v147
	ds_read_b128 v[174:177], v147 offset:1024
	ds_read_b128 v[178:181], v147 offset:2048
	ds_read_b128 v[182:185], v147 offset:3072
	v_lshl_add_u64 v[160:161], v[144:145], 0, s[10:11]
	s_add_i32 m0, s17, 0xc000
	ds_read_b128 v[186:189], v164
	ds_read_b128 v[190:193], v164 offset:1024
	ds_read_b128 v[194:197], v164 offset:2048
	ds_read_b128 v[198:201], v164 offset:3072
	ds_read_b128 v[202:205], v164 offset:4096
	ds_read_b128 v[206:209], v164 offset:5120
	ds_read_b128 v[210:213], v164 offset:6144
	ds_read_b128 v[214:217], v164 offset:7168
	global_load_lds_dwordx4 v[160:161], off
	v_lshl_add_u64 v[160:161], v[142:143], 0, s[10:11]
	s_add_i32 m0, s17, 0xe000
	s_nop 0
	global_load_lds_dwordx4 v[160:161], off
	s_waitcnt vmcnt(8)
	s_waitcnt vmcnt(8)
	s_waitcnt lgkmcnt(0)
	s_setprio 1
	s_barrier
	v_mfma_f32_16x16x32_bf16 v[126:129], v[148:151], v[186:189], v[126:129]
	v_mfma_f32_16x16x32_bf16 v[122:125], v[156:159], v[186:189], v[122:125]
	v_mfma_f32_16x16x32_bf16 v[118:121], v[148:151], v[194:197], v[118:121]
	v_mfma_f32_16x16x32_bf16 v[114:117], v[156:159], v[194:197], v[114:117]
	v_mfma_f32_16x16x32_bf16 v[110:113], v[148:151], v[202:205], v[110:113]
	v_mfma_f32_16x16x32_bf16 v[106:109], v[156:159], v[202:205], v[106:109]
	v_mfma_f32_16x16x32_bf16 v[102:105], v[148:151], v[210:213], v[102:105]
	v_mfma_f32_16x16x32_bf16 v[98:101], v[156:159], v[210:213], v[98:101]
	v_mfma_f32_16x16x32_bf16 v[126:129], v[152:155], v[190:193], v[126:129]
	v_mfma_f32_16x16x32_bf16 v[122:125], v[166:169], v[190:193], v[122:125]
	v_mfma_f32_16x16x32_bf16 v[118:121], v[152:155], v[198:201], v[118:121]
	v_mfma_f32_16x16x32_bf16 v[114:117], v[166:169], v[198:201], v[114:117]
	v_mfma_f32_16x16x32_bf16 v[110:113], v[152:155], v[206:209], v[110:113]
	v_mfma_f32_16x16x32_bf16 v[106:109], v[166:169], v[206:209], v[106:109]
	v_mfma_f32_16x16x32_bf16 v[102:105], v[152:155], v[214:217], v[102:105]
	v_mfma_f32_16x16x32_bf16 v[98:101], v[166:169], v[214:217], v[98:101]
	s_setprio 0
	s_setprio 1
	v_mfma_f32_16x16x32_bf16 v[94:97], v[170:173], v[186:189], v[94:97]
	v_mfma_f32_16x16x32_bf16 v[90:93], v[178:181], v[186:189], v[90:93]
	v_mfma_f32_16x16x32_bf16 v[86:89], v[170:173], v[194:197], v[86:89]
	v_mfma_f32_16x16x32_bf16 v[82:85], v[178:181], v[194:197], v[82:85]
	v_mfma_f32_16x16x32_bf16 v[78:81], v[170:173], v[202:205], v[78:81]
	v_mfma_f32_16x16x32_bf16 v[74:77], v[178:181], v[202:205], v[74:77]
	v_mfma_f32_16x16x32_bf16 v[70:73], v[170:173], v[210:213], v[70:73]
	v_mfma_f32_16x16x32_bf16 v[66:69], v[178:181], v[210:213], v[66:69]
	v_mfma_f32_16x16x32_bf16 v[94:97], v[174:177], v[190:193], v[94:97]
	v_mfma_f32_16x16x32_bf16 v[90:93], v[182:185], v[190:193], v[90:93]
	v_mfma_f32_16x16x32_bf16 v[86:89], v[174:177], v[198:201], v[86:89]
	v_mfma_f32_16x16x32_bf16 v[82:85], v[182:185], v[198:201], v[82:85]
	v_mfma_f32_16x16x32_bf16 v[78:81], v[174:177], v[206:209], v[78:81]
	v_mfma_f32_16x16x32_bf16 v[74:77], v[182:185], v[206:209], v[74:77]
	v_mfma_f32_16x16x32_bf16 v[70:73], v[174:177], v[214:217], v[70:73]
	v_mfma_f32_16x16x32_bf16 v[66:69], v[182:185], v[214:217], v[66:69]
	s_setprio 0
	s_barrier
	s_add_i32 s76, s78, s35
	v_lshl_add_u64 v[160:161], s[12:13], 0, v[132:133]
	s_mov_b32 m0, s76
	ds_read_b128 v[186:189], v164 offset:16384
	ds_read_b128 v[190:193], v164 offset:17408
	ds_read_b128 v[194:197], v164 offset:18432
	ds_read_b128 v[198:201], v164 offset:19456
	ds_read_b128 v[202:205], v164 offset:20480
	ds_read_b128 v[206:209], v164 offset:21504
	ds_read_b128 v[210:213], v164 offset:22528
	ds_read_b128 v[214:217], v164 offset:23552
	global_load_lds_dwordx4 v[160:161], off
	s_add_i32 m0, s76, 0x2000
	s_add_u32 s90, s12, 0x40000
	v_lshl_add_u64 v[218:219], s[12:13], 0, v[136:137]
	s_addc_u32 s91, s13, 0
	s_add_i32 s53, s53, s35
	global_load_lds_dwordx4 v[218:219], off
	v_lshl_add_u64 v[220:221], s[90:91], 0, v[132:133]
	s_mov_b32 m0, s53
	v_lshl_add_u64 v[222:223], s[26:27], 0, v[134:135]
	global_load_lds_dwordx4 v[220:221], off
	v_lshl_add_u64 v[220:221], s[90:91], 0, v[136:137]
	s_add_i32 m0, s53, 0x2000
	s_nop 0
	global_load_lds_dwordx4 v[220:221], off
	v_lshl_add_u64 v[220:221], s[26:27], 0, v[130:131]
	s_mov_b32 m0, s17
	s_nop 0
	global_load_lds_dwordx4 v[220:221], off
	s_mov_b32 m0, s37
	s_nop 0
	global_load_lds_dwordx4 v[222:223], off
	s_waitcnt vmcnt(8)
	s_waitcnt vmcnt(8)
	s_waitcnt lgkmcnt(0)
	s_setprio 1
	s_barrier
; #define PG8_STAGE(bufoff, gbase, voff) do { _Pragma("unroll") for (int _i = 0; _i < 2; ++_i) \
;         __builtin_amdgcn_global_load_lds((const unsigned*)((const char*)(gbase) + (voff)[_i]), (PG8_LAS unsigned*)(lds + (bufoff) + ldsw + _i * 8192), 16, 0, 0); } while (0)
; #define PG8_LDA(dst, b, h) do { _Pragma("unroll") for (int m = 0; m < 4; ++m) _Pragma("unroll") for (int k = 0; k < 2; ++k) dst[m][k] = *(const PG8_LAS bf16x8*)(lds + PG8_SA(b, h) + aoff + m * 2048 + k * 1024); } while (0)
; #define PG8_LDB(dst, b, h) do { _Pragma("unroll") for (int n = 0; n < 2; ++n) _Pragma("unroll") for (int k = 0; k < 2; ++k) dst[n][k] = *(const PG8_LAS bf16x8*)(lds + PG8_SB(b, h) + boff + n * 2048 + k * 1024); } while (0)
; #define PG8_MMA(ai, bj, At, Bt) do { __builtin_amdgcn_s_setprio(1); _Pragma("unroll") for (int m = 0; m < 4; ++m) _Pragma("unroll") for (int n = 0; n < 2; ++n) _Pragma("unroll") for (int k = 0; k < 2; ++k) \
;         acc[ai][bj][m][n] = __builtin_amdgcn_mfma_f32_16x16x32_bf16(Bt[n][k], At[m][k], acc[ai][bj][m][n], 0, 0, 0); __builtin_amdgcn_s_setprio(0); } while (0)
; #define PG8_WAIT_V(n) asm volatile("s_waitcnt vmcnt(" #n ")" ::: "memory")
; #define PG8_WAIT_VN(n) asm volatile("s_waitcnt vmcnt(%0)" :: "n"(n) : "memory")
; #define PG8_WAIT_L(n) asm volatile("s_waitcnt lgkmcnt(" #n ")" ::: "memory")
; #define PG8_BAR __builtin_amdgcn_s_barrier()
; #define PG8_SCHED __builtin_amdgcn_sched_barrier(0)
; template <class Epi, class Sched, bool ALIGN_EPI = false, bool SP2 = false>
; __device__ __forceinline__ void gemm_phase(PG8_LAS unsigned char* lds, const Gemm g, const Sched& S, const Epi& E, const int wave_id) {
;     ...
;             PG8_WAIT_VN(8 + Epi::NS); if (strict) PG8_WAIT_V(8); PG8_WAIT_L(0); PG8_BAR; PG8_MMA(1, 0, At, B0); PG8_MMA(1, 1, At, B1); PG8_BAR; PG8_SCHED;
;             PG8_LDB(B0, 1, 0); PG8_LDB(B1, 1, 1); PG8_SCHED; PG8_LDA(At, 1, 0); PG8_STAGE(PG8_SA(0, 1), a2 + hstep, voffA);
;             PG8_WAIT_V(8); PG8_WAIT_L(0); PG8_BAR; PG8_MMA(0, 0, At, B0); PG8_MMA(0, 1, At, B1); PG8_BAR; PG8_SCHED;
	v_mfma_f32_16x16x32_bf16 v[62:65], v[148:151], v[186:189], v[62:65]
	v_mfma_f32_16x16x32_bf16 v[58:61], v[156:159], v[186:189], v[58:61]
	v_mfma_f32_16x16x32_bf16 v[54:57], v[148:151], v[194:197], v[54:57]
	v_mfma_f32_16x16x32_bf16 v[50:53], v[156:159], v[194:197], v[50:53]
	v_mfma_f32_16x16x32_bf16 v[46:49], v[148:151], v[202:205], v[46:49]
	v_mfma_f32_16x16x32_bf16 v[42:45], v[156:159], v[202:205], v[42:45]
	v_mfma_f32_16x16x32_bf16 v[38:41], v[148:151], v[210:213], v[38:41]
	v_mfma_f32_16x16x32_bf16 v[34:37], v[156:159], v[210:213], v[34:37]
	v_mfma_f32_16x16x32_bf16 v[62:65], v[152:155], v[190:193], v[62:65]
	v_mfma_f32_16x16x32_bf16 v[58:61], v[166:169], v[190:193], v[58:61]
	v_mfma_f32_16x16x32_bf16 v[54:57], v[152:155], v[198:201], v[54:57]
	v_mfma_f32_16x16x32_bf16 v[50:53], v[166:169], v[198:201], v[50:53]
	v_mfma_f32_16x16x32_bf16 v[46:49], v[152:155], v[206:209], v[46:49]
	v_mfma_f32_16x16x32_bf16 v[42:45], v[166:169], v[206:209], v[42:45]
	v_mfma_f32_16x16x32_bf16 v[38:41], v[152:155], v[214:217], v[38:41]
	v_mfma_f32_16x16x32_bf16 v[34:37], v[166:169], v[214:217], v[34:37]
	s_setprio 0
	s_setprio 1
	v_mfma_f32_16x16x32_bf16 v[30:33], v[170:173], v[186:189], v[30:33]
	v_mfma_f32_16x16x32_bf16 v[26:29], v[178:181], v[186:189], v[26:29]
	v_mfma_f32_16x16x32_bf16 v[22:25], v[170:173], v[194:197], v[22:25]
	v_mfma_f32_16x16x32_bf16 v[18:21], v[178:181], v[194:197], v[18:21]
	v_mfma_f32_16x16x32_bf16 v[14:17], v[170:173], v[202:205], v[14:17]
	v_mfma_f32_16x16x32_bf16 v[10:13], v[178:181], v[202:205], v[10:13]
	v_mfma_f32_16x16x32_bf16 v[6:9], v[170:173], v[210:213], v[6:9]
	v_mfma_f32_16x16x32_bf16 v[2:5], v[178:181], v[210:213], v[2:5]
	v_mfma_f32_16x16x32_bf16 v[30:33], v[174:177], v[190:193], v[30:33]
	v_mfma_f32_16x16x32_bf16 v[26:29], v[182:185], v[190:193], v[26:29]
	v_mfma_f32_16x16x32_bf16 v[22:25], v[174:177], v[198:201], v[22:25]
	v_mfma_f32_16x16x32_bf16 v[18:21], v[182:185], v[198:201], v[18:21]
	v_mfma_f32_16x16x32_bf16 v[14:17], v[174:177], v[206:209], v[14:17]
	v_mfma_f32_16x16x32_bf16 v[10:13], v[182:185], v[206:209], v[10:13]
	v_mfma_f32_16x16x32_bf16 v[6:9], v[174:177], v[214:217], v[6:9]
	v_mfma_f32_16x16x32_bf16 v[2:5], v[182:185], v[214:217], v[2:5]
	s_setprio 0
	s_barrier
	s_add_i32 s53, 0, 0x18000
	v_add_u32_e32 v147, s53, v163
	s_add_i32 s76, 0, 0x1c000
	ds_read_b128 v[148:151], v147
	ds_read_b128 v[152:155], v147 offset:1024
	ds_read_b128 v[156:159], v147 offset:2048
	ds_read_b128 v[166:169], v147 offset:3072
	v_add_u32_e32 v147, s76, v163
	ds_read_b128 v[170:173], v147
	ds_read_b128 v[174:177], v147 offset:1024
	ds_read_b128 v[178:181], v147 offset:2048
	ds_read_b128 v[182:185], v147 offset:3072
	s_add_u32 s26, s26, 0x40000
	s_addc_u32 s27, s27, 0
	s_mov_b32 m0, s38
	v_lshl_add_u64 v[224:225], s[26:27], 0, v[130:131]
	ds_read_b128 v[186:189], v164 offset:32768
	ds_read_b128 v[190:193], v164 offset:33792
	ds_read_b128 v[194:197], v164 offset:34816
	ds_read_b128 v[198:201], v164 offset:35840
	ds_read_b128 v[202:205], v164 offset:36864
	ds_read_b128 v[206:209], v164 offset:37888
	ds_read_b128 v[210:213], v164 offset:38912
	ds_read_b128 v[214:217], v164 offset:39936
	global_load_lds_dwordx4 v[224:225], off
	v_lshl_add_u64 v[224:225], s[26:27], 0, v[134:135]
	s_mov_b32 m0, s39
	s_nop 0
	global_load_lds_dwordx4 v[224:225], off
	s_waitcnt vmcnt(8)
	s_waitcnt lgkmcnt(0)
	s_setprio 1
	s_barrier
	v_mfma_f32_16x16x32_bf16 v[126:129], v[148:151], v[186:189], v[126:129]
	v_mfma_f32_16x16x32_bf16 v[122:125], v[156:159], v[186:189], v[122:125]
	v_mfma_f32_16x16x32_bf16 v[118:121], v[148:151], v[194:197], v[118:121]
	v_mfma_f32_16x16x32_bf16 v[114:117], v[156:159], v[194:197], v[114:117]
	v_mfma_f32_16x16x32_bf16 v[110:113], v[148:151], v[202:205], v[110:113]
	v_mfma_f32_16x16x32_bf16 v[106:109], v[156:159], v[202:205], v[106:109]
	v_mfma_f32_16x16x32_bf16 v[102:105], v[148:151], v[210:213], v[102:105]
	v_mfma_f32_16x16x32_bf16 v[98:101], v[156:159], v[210:213], v[98:101]
	v_mfma_f32_16x16x32_bf16 v[126:129], v[152:155], v[190:193], v[126:129]
	v_mfma_f32_16x16x32_bf16 v[122:125], v[166:169], v[190:193], v[122:125]
	v_mfma_f32_16x16x32_bf16 v[118:121], v[152:155], v[198:201], v[118:121]
	v_mfma_f32_16x16x32_bf16 v[114:117], v[166:169], v[198:201], v[114:117]
	v_mfma_f32_16x16x32_bf16 v[110:113], v[152:155], v[206:209], v[110:113]
	v_mfma_f32_16x16x32_bf16 v[106:109], v[166:169], v[206:209], v[106:109]
	v_mfma_f32_16x16x32_bf16 v[102:105], v[152:155], v[214:217], v[102:105]
	v_mfma_f32_16x16x32_bf16 v[98:101], v[166:169], v[214:217], v[98:101]
	s_setprio 0
	s_setprio 1
	v_mfma_f32_16x16x32_bf16 v[94:97], v[170:173], v[186:189], v[94:97]
	v_mfma_f32_16x16x32_bf16 v[90:93], v[178:181], v[186:189], v[90:93]
	v_mfma_f32_16x16x32_bf16 v[86:89], v[170:173], v[194:197], v[86:89]
	v_mfma_f32_16x16x32_bf16 v[82:85], v[178:181], v[194:197], v[82:85]
	v_mfma_f32_16x16x32_bf16 v[78:81], v[170:173], v[202:205], v[78:81]
	v_mfma_f32_16x16x32_bf16 v[74:77], v[178:181], v[202:205], v[74:77]
	v_mfma_f32_16x16x32_bf16 v[70:73], v[170:173], v[210:213], v[70:73]
	v_mfma_f32_16x16x32_bf16 v[66:69], v[178:181], v[210:213], v[66:69]
	v_mfma_f32_16x16x32_bf16 v[94:97], v[174:177], v[190:193], v[94:97]
	v_mfma_f32_16x16x32_bf16 v[90:93], v[182:185], v[190:193], v[90:93]
	v_mfma_f32_16x16x32_bf16 v[86:89], v[174:177], v[198:201], v[86:89]
	v_mfma_f32_16x16x32_bf16 v[82:85], v[182:185], v[198:201], v[82:85]
	v_mfma_f32_16x16x32_bf16 v[78:81], v[174:177], v[206:209], v[78:81]
	v_mfma_f32_16x16x32_bf16 v[74:77], v[182:185], v[206:209], v[74:77]
	v_mfma_f32_16x16x32_bf16 v[70:73], v[174:177], v[214:217], v[70:73]
	v_mfma_f32_16x16x32_bf16 v[66:69], v[182:185], v[214:217], v[66:69]
	s_setprio 0
	s_barrier
; #define PG8_STAGE(bufoff, gbase, voff) do { _Pragma("unroll") for (int _i = 0; _i < 2; ++_i) \
;         __builtin_amdgcn_global_load_lds((const unsigned*)((const char*)(gbase) + (voff)[_i]), (PG8_LAS unsigned*)(lds + (bufoff) + ldsw + _i * 8192), 16, 0, 0); } while (0)
; #define PG8_LDA(dst, b, h) do { _Pragma("unroll") for (int m = 0; m < 4; ++m) _Pragma("unroll") for (int k = 0; k < 2; ++k) dst[m][k] = *(const PG8_LAS bf16x8*)(lds + PG8_SA(b, h) + aoff + m * 2048 + k * 1024); } while (0)
; #define PG8_MMA(ai, bj, At, Bt) do { __builtin_amdgcn_s_setprio(1); _Pragma("unroll") for (int m = 0; m < 4; ++m) _Pragma("unroll") for (int n = 0; n < 2; ++n) _Pragma("unroll") for (int k = 0; k < 2; ++k) \
;         acc[ai][bj][m][n] = __builtin_amdgcn_mfma_f32_16x16x32_bf16(Bt[n][k], At[m][k], acc[ai][bj][m][n], 0, 0, 0); __builtin_amdgcn_s_setprio(0); } while (0)
; #define PG8_WAIT_V(n) asm volatile("s_waitcnt vmcnt(" #n ")" ::: "memory")
; #define PG8_WAIT_L(n) asm volatile("s_waitcnt lgkmcnt(" #n ")" ::: "memory")
; #define PG8_BAR __builtin_amdgcn_s_barrier()
; #define PG8_SCHED __builtin_amdgcn_sched_barrier(0)
; template <class Epi, class Sched, bool ALIGN_EPI = false, bool SP2 = false>
; __device__ __forceinline__ void gemm_phase(PG8_LAS unsigned char* lds, const Gemm g, const Sched& S, const Epi& E, const int wave_id) {
;     ...
;             PG8_LDA(At, 1, 1); PG8_STAGE(PG8_SB(1, 0), b3, voffB); PG8_STAGE(PG8_SB(1, 1), b3 + hstep, voffB); PG8_STAGE(PG8_SA(1, 0), a3, voffA);
;             PG8_WAIT_V(8); PG8_WAIT_L(0); PG8_BAR; PG8_MMA(1, 0, At, B0); PG8_MMA(1, 1, At, B1); PG8_BAR; PG8_SCHED;
;     ...
;         if constexpr (ALIGN_EPI) { if (wr == 0) PG8_BAR; }
	s_add_i32 s26, s53, s35
	v_lshl_add_u64 v[160:161], v[160:161], 0, s[64:65]
	s_mov_b32 m0, s26
	ds_read_b128 v[186:189], v164 offset:49152
	ds_read_b128 v[190:193], v164 offset:50176
	ds_read_b128 v[194:197], v164 offset:51200
	ds_read_b128 v[198:201], v164 offset:52224
	ds_read_b128 v[202:205], v164 offset:53248
	ds_read_b128 v[206:209], v164 offset:54272
	ds_read_b128 v[210:213], v164 offset:55296
	ds_read_b128 v[214:217], v164 offset:56320
	global_load_lds_dwordx4 v[160:161], off
	s_add_i32 m0, s26, 0x2000
	s_add_u32 s12, s12, 0x40080
	v_lshl_add_u64 v[160:161], v[218:219], 0, s[64:65]
	s_addc_u32 s13, s13, 0
	s_add_i32 s26, s76, s35
	global_load_lds_dwordx4 v[160:161], off
	v_lshl_add_u64 v[160:161], s[12:13], 0, v[132:133]
	s_mov_b32 m0, s26
	s_nop 0
	global_load_lds_dwordx4 v[160:161], off
	v_lshl_add_u64 v[160:161], s[12:13], 0, v[136:137]
	s_add_i32 m0, s26, 0x2000
	s_nop 0
	global_load_lds_dwordx4 v[160:161], off
	v_lshl_add_u64 v[160:161], v[220:221], 0, s[64:65]
	s_mov_b32 m0, s41
	s_nop 0
	global_load_lds_dwordx4 v[160:161], off
	v_lshl_add_u64 v[160:161], v[222:223], 0, s[64:65]
	s_mov_b32 m0, s42
	s_nop 0
	global_load_lds_dwordx4 v[160:161], off
	s_waitcnt vmcnt(8)
	s_waitcnt lgkmcnt(0)
	s_setprio 1
	s_barrier
	v_mfma_f32_16x16x32_bf16 v[62:65], v[148:151], v[186:189], v[62:65]
	v_mfma_f32_16x16x32_bf16 v[58:61], v[156:159], v[186:189], v[58:61]
	v_mfma_f32_16x16x32_bf16 v[54:57], v[148:151], v[194:197], v[54:57]
	v_mfma_f32_16x16x32_bf16 v[50:53], v[156:159], v[194:197], v[50:53]
	v_mfma_f32_16x16x32_bf16 v[46:49], v[148:151], v[202:205], v[46:49]
	v_mfma_f32_16x16x32_bf16 v[42:45], v[156:159], v[202:205], v[42:45]
	v_mfma_f32_16x16x32_bf16 v[38:41], v[148:151], v[210:213], v[38:41]
	v_mfma_f32_16x16x32_bf16 v[34:37], v[156:159], v[210:213], v[34:37]
	v_mfma_f32_16x16x32_bf16 v[62:65], v[152:155], v[190:193], v[62:65]
	v_mfma_f32_16x16x32_bf16 v[58:61], v[166:169], v[190:193], v[58:61]
	v_mfma_f32_16x16x32_bf16 v[54:57], v[152:155], v[198:201], v[54:57]
	v_mfma_f32_16x16x32_bf16 v[50:53], v[166:169], v[198:201], v[50:53]
	v_mfma_f32_16x16x32_bf16 v[46:49], v[152:155], v[206:209], v[46:49]
	v_mfma_f32_16x16x32_bf16 v[42:45], v[166:169], v[206:209], v[42:45]
	v_mfma_f32_16x16x32_bf16 v[38:41], v[152:155], v[214:217], v[38:41]
	v_mfma_f32_16x16x32_bf16 v[34:37], v[166:169], v[214:217], v[34:37]
	s_setprio 0
	s_setprio 1
	v_mfma_f32_16x16x32_bf16 v[30:33], v[170:173], v[186:189], v[30:33]
	v_mfma_f32_16x16x32_bf16 v[26:29], v[178:181], v[186:189], v[26:29]
	v_mfma_f32_16x16x32_bf16 v[22:25], v[170:173], v[194:197], v[22:25]
	v_mfma_f32_16x16x32_bf16 v[18:21], v[178:181], v[194:197], v[18:21]
	v_mfma_f32_16x16x32_bf16 v[14:17], v[170:173], v[202:205], v[14:17]
	v_mfma_f32_16x16x32_bf16 v[10:13], v[178:181], v[202:205], v[10:13]
	v_mfma_f32_16x16x32_bf16 v[6:9], v[170:173], v[210:213], v[6:9]
	v_mfma_f32_16x16x32_bf16 v[2:5], v[178:181], v[210:213], v[2:5]
	v_mfma_f32_16x16x32_bf16 v[30:33], v[174:177], v[190:193], v[30:33]
	v_mfma_f32_16x16x32_bf16 v[26:29], v[182:185], v[190:193], v[26:29]
	v_mfma_f32_16x16x32_bf16 v[22:25], v[174:177], v[198:201], v[22:25]
	v_mfma_f32_16x16x32_bf16 v[18:21], v[182:185], v[198:201], v[18:21]
	v_mfma_f32_16x16x32_bf16 v[14:17], v[174:177], v[206:209], v[14:17]
	v_mfma_f32_16x16x32_bf16 v[10:13], v[182:185], v[206:209], v[10:13]
	v_mfma_f32_16x16x32_bf16 v[6:9], v[174:177], v[214:217], v[6:9]
	v_mfma_f32_16x16x32_bf16 v[2:5], v[182:185], v[214:217], v[2:5]
	s_setprio 0
	s_barrier
	s_add_u32 s10, s10, 0x100
	s_addc_u32 s11, s11, 0
	s_cmp_gt_u32 s69, 13
	s_cbranch_scc0 .LBB0_1537
	s_and_b64 vcc, exec, s[24:25]
	s_cbranch_vccz .LBB0_1540
	s_barrier

; #define PG8_STAGE(bufoff, gbase, voff) do { _Pragma("unroll") for (int _i = 0; _i < 2; ++_i) \
;         __builtin_amdgcn_global_load_lds((const unsigned*)((const char*)(gbase) + (voff)[_i]), (PG8_LAS unsigned*)(lds + (bufoff) + ldsw + _i * 8192), 16, 0, 0); } while (0)
; #define PG8_LDA(dst, b, h) do { _Pragma("unroll") for (int m = 0; m < 4; ++m) _Pragma("unroll") for (int k = 0; k < 2; ++k) dst[m][k] = *(const PG8_LAS bf16x8*)(lds + PG8_SA(b, h) + aoff + m * 2048 + k * 1024); } while (0)
; #define PG8_LDB(dst, b, h) do { _Pragma("unroll") for (int n = 0; n < 2; ++n) _Pragma("unroll") for (int k = 0; k < 2; ++k) dst[n][k] = *(const PG8_LAS bf16x8*)(lds + PG8_SB(b, h) + boff + n * 2048 + k * 1024); } while (0)
; #define PG8_WAIT_V(n) asm volatile("s_waitcnt vmcnt(" #n ")" ::: "memory")
; #define PG8_WAIT_VN(n) asm volatile("s_waitcnt vmcnt(%0)" :: "n"(n) : "memory")
; #define PG8_WAIT_L(n) asm volatile("s_waitcnt lgkmcnt(" #n ")" ::: "memory")
; template <class Epi, class Sched, bool ALIGN_EPI = false, bool SP2 = false>
; __device__ __forceinline__ void gemm_phase(PG8_LAS unsigned char* lds, const Gemm g, const Sched& S, const Epi& E, const int wave_id) {
;     ...
;         for (int t = 0; t < nt; t += 2) {
;             const bool last = (t == nt - 2);
;             const char* a1 = cA + (size_t)(t + 1) * kstep;
;             const char* a2 = last ? nA : cA + (size_t)(t + 2) * kstep; const char* b2 = last ? nB : cB + (size_t)(t + 2) * kstep;
;             const char* a3 = a2 + kstep; const char* b3 = b2 + kstep;
;             if (last && has_next) S.a_ready(nxt);
;             if constexpr (SP2) {
;             int tz_ = __builtin_amdgcn_readfirstlane(t | (ui > 0 ? 0 : 1)); asm volatile("" : "+s"(tz_));
;             const bool strict = !(Epi::NS > 0 && tz_ == 0);
;             PG8_LDB(B0, 0, 0); PG8_LDB(B1, 0, 1); PG8_SCHED; PG8_LDA(At, 0, 0); PG8_STAGE(PG8_SA(1, 1), a1 + hstep, voffA);
;             PG8_WAIT_VN(8 + Epi::NS); if (strict) PG8_WAIT_V(8); PG8_WAIT_L(0); PG8_BAR; PG8_MMA(0, 0, At, B0); PG8_MMA(0, 1, At, B1); PG8_BAR; PG8_SCHED;
;             PG8_LDA(At, 0, 1); PG8_STAGE(PG8_SB(0, 0), b2, voffB); PG8_STAGE(PG8_SB(0, 1), b2 + hstep, voffB); PG8_STAGE(PG8_SA(0, 0), a2, voffA);
;             PG8_WAIT_VN(8 + Epi::NS); if (strict) PG8_WAIT_V(8); PG8_WAIT_L(0); PG8_BAR; PG8_MMA(1, 0, At, B0); PG8_MMA(1, 1, At, B1); PG8_BAR; PG8_SCHED;
.LBB0_1685:
	s_add_u32 s24, s20, s22
	s_addc_u32 s25, s21, s23
	s_add_u32 s24, s24, 0x100
	s_addc_u32 s25, s25, 0
	s_add_u32 s53, s52, s22
	s_addc_u32 s57, s54, s23
	s_add_i32 s56, s56, 2
	s_add_i32 s62, 0, 0x10000
	v_add_u32_e32 v147, s56, v146
	s_cmpk_eq_i32 s22, 0x700
	s_cselect_b32 s26, s11, s24
	v_readfirstlane_b32 s24, v147
	s_cselect_b32 s27, s9, s25
	v_add_u32_e32 v147, s62, v163
	s_cselect_b32 s25, s13, s57
	s_cselect_b32 s24, s15, s53
	s_add_i32 s53, 0, 0x14000
	ds_read_b128 v[148:151], v147
	ds_read_b128 v[152:155], v147 offset:1024
	ds_read_b128 v[156:159], v147 offset:2048
	ds_read_b128 v[166:169], v147 offset:3072
	v_add_u32_e32 v147, s53, v163
	ds_read_b128 v[170:173], v147
	ds_read_b128 v[174:177], v147 offset:1024
	ds_read_b128 v[178:181], v147 offset:2048
	ds_read_b128 v[182:185], v147 offset:3072
	v_lshl_add_u64 v[160:161], v[144:145], 0, s[22:23]
	s_add_i32 m0, s38, 0xc000
	ds_read_b128 v[186:189], v164
	ds_read_b128 v[190:193], v164 offset:1024
	ds_read_b128 v[194:197], v164 offset:2048
	ds_read_b128 v[198:201], v164 offset:3072
	ds_read_b128 v[202:205], v164 offset:4096
	ds_read_b128 v[206:209], v164 offset:5120
	ds_read_b128 v[210:213], v164 offset:6144
	ds_read_b128 v[214:217], v164 offset:7168
	global_load_lds_dwordx4 v[160:161], off
	v_lshl_add_u64 v[160:161], v[142:143], 0, s[22:23]
	s_add_i32 m0, s38, 0xe000
	s_nop 0
	global_load_lds_dwordx4 v[160:161], off
	s_waitcnt vmcnt(8)
	s_waitcnt vmcnt(8)
	s_waitcnt lgkmcnt(0)
	s_setprio 1
	s_barrier
	v_mfma_f32_16x16x32_bf16 v[126:129], v[148:151], v[186:189], v[126:129]
	v_mfma_f32_16x16x32_bf16 v[122:125], v[156:159], v[186:189], v[122:125]
	v_mfma_f32_16x16x32_bf16 v[118:121], v[148:151], v[194:197], v[118:121]
	v_mfma_f32_16x16x32_bf16 v[114:117], v[156:159], v[194:197], v[114:117]
	v_mfma_f32_16x16x32_bf16 v[110:113], v[148:151], v[202:205], v[110:113]
	v_mfma_f32_16x16x32_bf16 v[106:109], v[156:159], v[202:205], v[106:109]
	v_mfma_f32_16x16x32_bf16 v[102:105], v[148:151], v[210:213], v[102:105]
	v_mfma_f32_16x16x32_bf16 v[98:101], v[156:159], v[210:213], v[98:101]
	v_mfma_f32_16x16x32_bf16 v[126:129], v[152:155], v[190:193], v[126:129]
	v_mfma_f32_16x16x32_bf16 v[122:125], v[166:169], v[190:193], v[122:125]
	v_mfma_f32_16x16x32_bf16 v[118:121], v[152:155], v[198:201], v[118:121]
	v_mfma_f32_16x16x32_bf16 v[114:117], v[166:169], v[198:201], v[114:117]
	v_mfma_f32_16x16x32_bf16 v[110:113], v[152:155], v[206:209], v[110:113]
	v_mfma_f32_16x16x32_bf16 v[106:109], v[166:169], v[206:209], v[106:109]
	v_mfma_f32_16x16x32_bf16 v[102:105], v[152:155], v[214:217], v[102:105]
	v_mfma_f32_16x16x32_bf16 v[98:101], v[166:169], v[214:217], v[98:101]
	s_setprio 0
	s_setprio 1
	v_mfma_f32_16x16x32_bf16 v[94:97], v[170:173], v[186:189], v[94:97]
	v_mfma_f32_16x16x32_bf16 v[90:93], v[178:181], v[186:189], v[90:93]
	v_mfma_f32_16x16x32_bf16 v[86:89], v[170:173], v[194:197], v[86:89]
	v_mfma_f32_16x16x32_bf16 v[82:85], v[178:181], v[194:197], v[82:85]
	v_mfma_f32_16x16x32_bf16 v[78:81], v[170:173], v[202:205], v[78:81]
	v_mfma_f32_16x16x32_bf16 v[74:77], v[178:181], v[202:205], v[74:77]
	v_mfma_f32_16x16x32_bf16 v[70:73], v[170:173], v[210:213], v[70:73]
	v_mfma_f32_16x16x32_bf16 v[66:69], v[178:181], v[210:213], v[66:69]
	v_mfma_f32_16x16x32_bf16 v[94:97], v[174:177], v[190:193], v[94:97]
	v_mfma_f32_16x16x32_bf16 v[90:93], v[182:185], v[190:193], v[90:93]
	v_mfma_f32_16x16x32_bf16 v[86:89], v[174:177], v[198:201], v[86:89]
	v_mfma_f32_16x16x32_bf16 v[82:85], v[182:185], v[198:201], v[82:85]
	v_mfma_f32_16x16x32_bf16 v[78:81], v[174:177], v[206:209], v[78:81]
	v_mfma_f32_16x16x32_bf16 v[74:77], v[182:185], v[206:209], v[74:77]
	v_mfma_f32_16x16x32_bf16 v[70:73], v[174:177], v[214:217], v[70:73]
	v_mfma_f32_16x16x32_bf16 v[66:69], v[182:185], v[214:217], v[66:69]
	s_setprio 0
	s_barrier
	s_add_i32 s57, s62, s37
	v_lshl_add_u64 v[160:161], s[24:25], 0, v[132:133]
	s_mov_b32 m0, s57
	ds_read_b128 v[186:189], v164 offset:16384
	ds_read_b128 v[190:193], v164 offset:17408
	ds_read_b128 v[194:197], v164 offset:18432
	ds_read_b128 v[198:201], v164 offset:19456
	ds_read_b128 v[202:205], v164 offset:20480
	ds_read_b128 v[206:209], v164 offset:21504
	ds_read_b128 v[210:213], v164 offset:22528
	ds_read_b128 v[214:217], v164 offset:23552
	global_load_lds_dwordx4 v[160:161], off
	s_add_i32 m0, s57, 0x2000
	s_add_u32 s62, s24, 0x40000
	v_lshl_add_u64 v[218:219], s[24:25], 0, v[136:137]
	s_addc_u32 s63, s25, 0
	s_add_i32 s53, s53, s37
	global_load_lds_dwordx4 v[218:219], off
	v_lshl_add_u64 v[220:221], s[62:63], 0, v[132:133]
	s_mov_b32 m0, s53
	v_lshl_add_u64 v[222:223], s[26:27], 0, v[134:135]
	global_load_lds_dwordx4 v[220:221], off
	v_lshl_add_u64 v[220:221], s[62:63], 0, v[136:137]
	s_add_i32 m0, s53, 0x2000
	s_nop 0
	global_load_lds_dwordx4 v[220:221], off
	v_lshl_add_u64 v[220:221], s[26:27], 0, v[130:131]
	s_mov_b32 m0, s38
	s_nop 0
	global_load_lds_dwordx4 v[220:221], off
	s_mov_b32 m0, s39
	s_nop 0
	global_load_lds_dwordx4 v[222:223], off
	s_waitcnt vmcnt(8)
	s_waitcnt vmcnt(8)
	s_waitcnt lgkmcnt(0)
	s_setprio 1
	s_barrier
; #define PG8_STAGE(bufoff, gbase, voff) do { _Pragma("unroll") for (int _i = 0; _i < 2; ++_i) \
;         __builtin_amdgcn_global_load_lds((const unsigned*)((const char*)(gbase) + (voff)[_i]), (PG8_LAS unsigned*)(lds + (bufoff) + ldsw + _i * 8192), 16, 0, 0); } while (0)
; #define PG8_LDA(dst, b, h) do { _Pragma("unroll") for (int m = 0; m < 4; ++m) _Pragma("unroll") for (int k = 0; k < 2; ++k) dst[m][k] = *(const PG8_LAS bf16x8*)(lds + PG8_SA(b, h) + aoff + m * 2048 + k * 1024); } while (0)
; #define PG8_LDB(dst, b, h) do { _Pragma("unroll") for (int n = 0; n < 2; ++n) _Pragma("unroll") for (int k = 0; k < 2; ++k) dst[n][k] = *(const PG8_LAS bf16x8*)(lds + PG8_SB(b, h) + boff + n * 2048 + k * 1024); } while (0)
; #define PG8_MMA(ai, bj, At, Bt) do { __builtin_amdgcn_s_setprio(1); _Pragma("unroll") for (int m = 0; m < 4; ++m) _Pragma("unroll") for (int n = 0; n < 2; ++n) _Pragma("unroll") for (int k = 0; k < 2; ++k) \
;         acc[ai][bj][m][n] = __builtin_amdgcn_mfma_f32_16x16x32_bf16(Bt[n][k], At[m][k], acc[ai][bj][m][n], 0, 0, 0); __builtin_amdgcn_s_setprio(0); } while (0)
; #define PG8_WAIT_V(n) asm volatile("s_waitcnt vmcnt(" #n ")" ::: "memory")
; #define PG8_WAIT_VN(n) asm volatile("s_waitcnt vmcnt(%0)" :: "n"(n) : "memory")
; #define PG8_WAIT_L(n) asm volatile("s_waitcnt lgkmcnt(" #n ")" ::: "memory")
; #define PG8_BAR __builtin_amdgcn_s_barrier()
; #define PG8_SCHED __builtin_amdgcn_sched_barrier(0)
; template <class Epi, class Sched, bool ALIGN_EPI = false, bool SP2 = false>
; __device__ __forceinline__ void gemm_phase(PG8_LAS unsigned char* lds, const Gemm g, const Sched& S, const Epi& E, const int wave_id) {
;     ...
;             PG8_WAIT_VN(8 + Epi::NS); if (strict) PG8_WAIT_V(8); PG8_WAIT_L(0); PG8_BAR; PG8_MMA(1, 0, At, B0); PG8_MMA(1, 1, At, B1); PG8_BAR; PG8_SCHED;
;             PG8_LDB(B0, 1, 0); PG8_LDB(B1, 1, 1); PG8_SCHED; PG8_LDA(At, 1, 0); PG8_STAGE(PG8_SA(0, 1), a2 + hstep, voffA);
;             PG8_WAIT_V(8); PG8_WAIT_L(0); PG8_BAR; PG8_MMA(0, 0, At, B0); PG8_MMA(0, 1, At, B1); PG8_BAR; PG8_SCHED;
	v_mfma_f32_16x16x32_bf16 v[62:65], v[148:151], v[186:189], v[62:65]
	v_mfma_f32_16x16x32_bf16 v[58:61], v[156:159], v[186:189], v[58:61]
	v_mfma_f32_16x16x32_bf16 v[54:57], v[148:151], v[194:197], v[54:57]
	v_mfma_f32_16x16x32_bf16 v[50:53], v[156:159], v[194:197], v[50:53]
	v_mfma_f32_16x16x32_bf16 v[46:49], v[148:151], v[202:205], v[46:49]
	v_mfma_f32_16x16x32_bf16 v[42:45], v[156:159], v[202:205], v[42:45]
	v_mfma_f32_16x16x32_bf16 v[38:41], v[148:151], v[210:213], v[38:41]
	v_mfma_f32_16x16x32_bf16 v[34:37], v[156:159], v[210:213], v[34:37]
	v_mfma_f32_16x16x32_bf16 v[62:65], v[152:155], v[190:193], v[62:65]
	v_mfma_f32_16x16x32_bf16 v[58:61], v[166:169], v[190:193], v[58:61]
	v_mfma_f32_16x16x32_bf16 v[54:57], v[152:155], v[198:201], v[54:57]
	v_mfma_f32_16x16x32_bf16 v[50:53], v[166:169], v[198:201], v[50:53]
	v_mfma_f32_16x16x32_bf16 v[46:49], v[152:155], v[206:209], v[46:49]
	v_mfma_f32_16x16x32_bf16 v[42:45], v[166:169], v[206:209], v[42:45]
	v_mfma_f32_16x16x32_bf16 v[38:41], v[152:155], v[214:217], v[38:41]
	v_mfma_f32_16x16x32_bf16 v[34:37], v[166:169], v[214:217], v[34:37]
	s_setprio 0
	s_setprio 1
	v_mfma_f32_16x16x32_bf16 v[30:33], v[170:173], v[186:189], v[30:33]
	v_mfma_f32_16x16x32_bf16 v[26:29], v[178:181], v[186:189], v[26:29]
	v_mfma_f32_16x16x32_bf16 v[22:25], v[170:173], v[194:197], v[22:25]
	v_mfma_f32_16x16x32_bf16 v[18:21], v[178:181], v[194:197], v[18:21]
	v_mfma_f32_16x16x32_bf16 v[14:17], v[170:173], v[202:205], v[14:17]
	v_mfma_f32_16x16x32_bf16 v[10:13], v[178:181], v[202:205], v[10:13]
	v_mfma_f32_16x16x32_bf16 v[6:9], v[170:173], v[210:213], v[6:9]
	v_mfma_f32_16x16x32_bf16 v[2:5], v[178:181], v[210:213], v[2:5]
	v_mfma_f32_16x16x32_bf16 v[30:33], v[174:177], v[190:193], v[30:33]
	v_mfma_f32_16x16x32_bf16 v[26:29], v[182:185], v[190:193], v[26:29]
	v_mfma_f32_16x16x32_bf16 v[22:25], v[174:177], v[198:201], v[22:25]
	v_mfma_f32_16x16x32_bf16 v[18:21], v[182:185], v[198:201], v[18:21]
	v_mfma_f32_16x16x32_bf16 v[14:17], v[174:177], v[206:209], v[14:17]
	v_mfma_f32_16x16x32_bf16 v[10:13], v[182:185], v[206:209], v[10:13]
	v_mfma_f32_16x16x32_bf16 v[6:9], v[174:177], v[214:217], v[6:9]
	v_mfma_f32_16x16x32_bf16 v[2:5], v[182:185], v[214:217], v[2:5]
	s_setprio 0
	s_barrier
	s_add_i32 s53, 0, 0x18000
	v_add_u32_e32 v147, s53, v163
	s_add_i32 s57, 0, 0x1c000
	ds_read_b128 v[148:151], v147
	ds_read_b128 v[152:155], v147 offset:1024
	ds_read_b128 v[156:159], v147 offset:2048
	ds_read_b128 v[166:169], v147 offset:3072
	v_add_u32_e32 v147, s57, v163
	ds_read_b128 v[170:173], v147
	ds_read_b128 v[174:177], v147 offset:1024
	ds_read_b128 v[178:181], v147 offset:2048
	ds_read_b128 v[182:185], v147 offset:3072
	s_add_u32 s26, s26, 0x40000
	s_addc_u32 s27, s27, 0
	s_mov_b32 m0, s40
	v_lshl_add_u64 v[224:225], s[26:27], 0, v[130:131]
	ds_read_b128 v[186:189], v164 offset:32768
	ds_read_b128 v[190:193], v164 offset:33792
	ds_read_b128 v[194:197], v164 offset:34816
	ds_read_b128 v[198:201], v164 offset:35840
	ds_read_b128 v[202:205], v164 offset:36864
	ds_read_b128 v[206:209], v164 offset:37888
	ds_read_b128 v[210:213], v164 offset:38912
	ds_read_b128 v[214:217], v164 offset:39936
	global_load_lds_dwordx4 v[224:225], off
	v_lshl_add_u64 v[224:225], s[26:27], 0, v[134:135]
	s_mov_b32 m0, s41
	s_nop 0
	global_load_lds_dwordx4 v[224:225], off
	s_waitcnt vmcnt(8)
	s_waitcnt lgkmcnt(0)
	s_setprio 1
	s_barrier
	v_mfma_f32_16x16x32_bf16 v[126:129], v[148:151], v[186:189], v[126:129]
	v_mfma_f32_16x16x32_bf16 v[122:125], v[156:159], v[186:189], v[122:125]
	v_mfma_f32_16x16x32_bf16 v[118:121], v[148:151], v[194:197], v[118:121]
	v_mfma_f32_16x16x32_bf16 v[114:117], v[156:159], v[194:197], v[114:117]
	v_mfma_f32_16x16x32_bf16 v[110:113], v[148:151], v[202:205], v[110:113]
	v_mfma_f32_16x16x32_bf16 v[106:109], v[156:159], v[202:205], v[106:109]
	v_mfma_f32_16x16x32_bf16 v[102:105], v[148:151], v[210:213], v[102:105]
	v_mfma_f32_16x16x32_bf16 v[98:101], v[156:159], v[210:213], v[98:101]
	v_mfma_f32_16x16x32_bf16 v[126:129], v[152:155], v[190:193], v[126:129]
	v_mfma_f32_16x16x32_bf16 v[122:125], v[166:169], v[190:193], v[122:125]
	v_mfma_f32_16x16x32_bf16 v[118:121], v[152:155], v[198:201], v[118:121]
	v_mfma_f32_16x16x32_bf16 v[114:117], v[166:169], v[198:201], v[114:117]
	v_mfma_f32_16x16x32_bf16 v[110:113], v[152:155], v[206:209], v[110:113]
	v_mfma_f32_16x16x32_bf16 v[106:109], v[166:169], v[206:209], v[106:109]
	v_mfma_f32_16x16x32_bf16 v[102:105], v[152:155], v[214:217], v[102:105]
	v_mfma_f32_16x16x32_bf16 v[98:101], v[166:169], v[214:217], v[98:101]
	s_setprio 0
	s_setprio 1
	v_mfma_f32_16x16x32_bf16 v[94:97], v[170:173], v[186:189], v[94:97]
	v_mfma_f32_16x16x32_bf16 v[90:93], v[178:181], v[186:189], v[90:93]
	v_mfma_f32_16x16x32_bf16 v[86:89], v[170:173], v[194:197], v[86:89]
	v_mfma_f32_16x16x32_bf16 v[82:85], v[178:181], v[194:197], v[82:85]
	v_mfma_f32_16x16x32_bf16 v[78:81], v[170:173], v[202:205], v[78:81]
	v_mfma_f32_16x16x32_bf16 v[74:77], v[178:181], v[202:205], v[74:77]
	v_mfma_f32_16x16x32_bf16 v[70:73], v[170:173], v[210:213], v[70:73]
	v_mfma_f32_16x16x32_bf16 v[66:69], v[178:181], v[210:213], v[66:69]
	v_mfma_f32_16x16x32_bf16 v[94:97], v[174:177], v[190:193], v[94:97]
	v_mfma_f32_16x16x32_bf16 v[90:93], v[182:185], v[190:193], v[90:93]
	v_mfma_f32_16x16x32_bf16 v[86:89], v[174:177], v[198:201], v[86:89]
	v_mfma_f32_16x16x32_bf16 v[82:85], v[182:185], v[198:201], v[82:85]
	v_mfma_f32_16x16x32_bf16 v[78:81], v[174:177], v[206:209], v[78:81]
	v_mfma_f32_16x16x32_bf16 v[74:77], v[182:185], v[206:209], v[74:77]
	v_mfma_f32_16x16x32_bf16 v[70:73], v[174:177], v[214:217], v[70:73]
	v_mfma_f32_16x16x32_bf16 v[66:69], v[182:185], v[214:217], v[66:69]
	s_setprio 0
	s_barrier
; #define PG8_STAGE(bufoff, gbase, voff) do { _Pragma("unroll") for (int _i = 0; _i < 2; ++_i) \
;         __builtin_amdgcn_global_load_lds((const unsigned*)((const char*)(gbase) + (voff)[_i]), (PG8_LAS unsigned*)(lds + (bufoff) + ldsw + _i * 8192), 16, 0, 0); } while (0)
; #define PG8_LDA(dst, b, h) do { _Pragma("unroll") for (int m = 0; m < 4; ++m) _Pragma("unroll") for (int k = 0; k < 2; ++k) dst[m][k] = *(const PG8_LAS bf16x8*)(lds + PG8_SA(b, h) + aoff + m * 2048 + k * 1024); } while (0)
; #define PG8_MMA(ai, bj, At, Bt) do { __builtin_amdgcn_s_setprio(1); _Pragma("unroll") for (int m = 0; m < 4; ++m) _Pragma("unroll") for (int n = 0; n < 2; ++n) _Pragma("unroll") for (int k = 0; k < 2; ++k) \
;         acc[ai][bj][m][n] = __builtin_amdgcn_mfma_f32_16x16x32_bf16(Bt[n][k], At[m][k], acc[ai][bj][m][n], 0, 0, 0); __builtin_amdgcn_s_setprio(0); } while (0)
; #define PG8_WAIT_V(n) asm volatile("s_waitcnt vmcnt(" #n ")" ::: "memory")
; #define PG8_WAIT_L(n) asm volatile("s_waitcnt lgkmcnt(" #n ")" ::: "memory")
; #define PG8_BAR __builtin_amdgcn_s_barrier()
; #define PG8_SCHED __builtin_amdgcn_sched_barrier(0)
; template <class Epi, class Sched, bool ALIGN_EPI = false, bool SP2 = false>
; __device__ __forceinline__ void gemm_phase(PG8_LAS unsigned char* lds, const Gemm g, const Sched& S, const Epi& E, const int wave_id) {
;     ...
;             PG8_LDA(At, 1, 1); PG8_STAGE(PG8_SB(1, 0), b3, voffB); PG8_STAGE(PG8_SB(1, 1), b3 + hstep, voffB); PG8_STAGE(PG8_SA(1, 0), a3, voffA);
;             PG8_WAIT_V(8); PG8_WAIT_L(0); PG8_BAR; PG8_MMA(1, 0, At, B0); PG8_MMA(1, 1, At, B1); PG8_BAR; PG8_SCHED;
;     ...
;         if constexpr (ALIGN_EPI) { if (wr == 0) PG8_BAR; }
	s_add_i32 s26, s53, s37
	v_lshl_add_u64 v[160:161], v[160:161], 0, s[64:65]
	s_mov_b32 m0, s26
	ds_read_b128 v[186:189], v164 offset:49152
	ds_read_b128 v[190:193], v164 offset:50176
	ds_read_b128 v[194:197], v164 offset:51200
	ds_read_b128 v[198:201], v164 offset:52224
	ds_read_b128 v[202:205], v164 offset:53248
	ds_read_b128 v[206:209], v164 offset:54272
	ds_read_b128 v[210:213], v164 offset:55296
	ds_read_b128 v[214:217], v164 offset:56320
	global_load_lds_dwordx4 v[160:161], off
	s_add_i32 m0, s26, 0x2000
	s_add_u32 s24, s24, 0x40080
	v_lshl_add_u64 v[160:161], v[218:219], 0, s[64:65]
	s_addc_u32 s25, s25, 0
	s_add_i32 s26, s57, s37
	global_load_lds_dwordx4 v[160:161], off
	v_lshl_add_u64 v[160:161], s[24:25], 0, v[132:133]
	s_mov_b32 m0, s26
	s_nop 0
	global_load_lds_dwordx4 v[160:161], off
	v_lshl_add_u64 v[160:161], s[24:25], 0, v[136:137]
	s_add_i32 m0, s26, 0x2000
	s_nop 0
	global_load_lds_dwordx4 v[160:161], off
	v_lshl_add_u64 v[160:161], v[220:221], 0, s[64:65]
	s_mov_b32 m0, s43
	s_nop 0
	global_load_lds_dwordx4 v[160:161], off
	v_lshl_add_u64 v[160:161], v[222:223], 0, s[64:65]
	s_mov_b32 m0, s49
	s_nop 0
	global_load_lds_dwordx4 v[160:161], off
	s_waitcnt vmcnt(8)
	s_waitcnt lgkmcnt(0)
	s_setprio 1
	s_barrier
	v_mfma_f32_16x16x32_bf16 v[62:65], v[148:151], v[186:189], v[62:65]
	v_mfma_f32_16x16x32_bf16 v[58:61], v[156:159], v[186:189], v[58:61]
	v_mfma_f32_16x16x32_bf16 v[54:57], v[148:151], v[194:197], v[54:57]
	v_mfma_f32_16x16x32_bf16 v[50:53], v[156:159], v[194:197], v[50:53]
	v_mfma_f32_16x16x32_bf16 v[46:49], v[148:151], v[202:205], v[46:49]
	v_mfma_f32_16x16x32_bf16 v[42:45], v[156:159], v[202:205], v[42:45]
	v_mfma_f32_16x16x32_bf16 v[38:41], v[148:151], v[210:213], v[38:41]
	v_mfma_f32_16x16x32_bf16 v[34:37], v[156:159], v[210:213], v[34:37]
	v_mfma_f32_16x16x32_bf16 v[62:65], v[152:155], v[190:193], v[62:65]
	v_mfma_f32_16x16x32_bf16 v[58:61], v[166:169], v[190:193], v[58:61]
	v_mfma_f32_16x16x32_bf16 v[54:57], v[152:155], v[198:201], v[54:57]
	v_mfma_f32_16x16x32_bf16 v[50:53], v[166:169], v[198:201], v[50:53]
	v_mfma_f32_16x16x32_bf16 v[46:49], v[152:155], v[206:209], v[46:49]
	v_mfma_f32_16x16x32_bf16 v[42:45], v[166:169], v[206:209], v[42:45]
	v_mfma_f32_16x16x32_bf16 v[38:41], v[152:155], v[214:217], v[38:41]
	v_mfma_f32_16x16x32_bf16 v[34:37], v[166:169], v[214:217], v[34:37]
	s_setprio 0
	s_setprio 1
	v_mfma_f32_16x16x32_bf16 v[30:33], v[170:173], v[186:189], v[30:33]
	v_mfma_f32_16x16x32_bf16 v[26:29], v[178:181], v[186:189], v[26:29]
	v_mfma_f32_16x16x32_bf16 v[22:25], v[170:173], v[194:197], v[22:25]
	v_mfma_f32_16x16x32_bf16 v[18:21], v[178:181], v[194:197], v[18:21]
	v_mfma_f32_16x16x32_bf16 v[14:17], v[170:173], v[202:205], v[14:17]
	v_mfma_f32_16x16x32_bf16 v[10:13], v[178:181], v[202:205], v[10:13]
	v_mfma_f32_16x16x32_bf16 v[6:9], v[170:173], v[210:213], v[6:9]
	v_mfma_f32_16x16x32_bf16 v[2:5], v[178:181], v[210:213], v[2:5]
	v_mfma_f32_16x16x32_bf16 v[30:33], v[174:177], v[190:193], v[30:33]
	v_mfma_f32_16x16x32_bf16 v[26:29], v[182:185], v[190:193], v[26:29]
	v_mfma_f32_16x16x32_bf16 v[22:25], v[174:177], v[198:201], v[22:25]
	v_mfma_f32_16x16x32_bf16 v[18:21], v[182:185], v[198:201], v[18:21]
	v_mfma_f32_16x16x32_bf16 v[14:17], v[174:177], v[206:209], v[14:17]
	v_mfma_f32_16x16x32_bf16 v[10:13], v[182:185], v[206:209], v[10:13]
	v_mfma_f32_16x16x32_bf16 v[6:9], v[174:177], v[214:217], v[6:9]
	v_mfma_f32_16x16x32_bf16 v[2:5], v[182:185], v[214:217], v[2:5]
	s_setprio 0
	s_barrier
	s_add_u32 s22, s22, 0x100
	s_addc_u32 s23, s23, 0
	s_cmp_gt_u32 s56, 13
	s_cbranch_scc0 .LBB0_1685
	s_and_b64 vcc, exec, s[4:5]
	s_cbranch_vccz .LBB0_1688
	s_barrier

; #define PG8_STAGE(bufoff, gbase, voff) do { _Pragma("unroll") for (int _i = 0; _i < 2; ++_i) \
;         __builtin_amdgcn_global_load_lds((const unsigned*)((const char*)(gbase) + (voff)[_i]), (PG8_LAS unsigned*)(lds + (bufoff) + ldsw + _i * 8192), 16, 0, 0); } while (0)
; #define PG8_LDA(dst, b, h) do { _Pragma("unroll") for (int m = 0; m < 4; ++m) _Pragma("unroll") for (int k = 0; k < 2; ++k) dst[m][k] = *(const PG8_LAS bf16x8*)(lds + PG8_SA(b, h) + aoff + m * 2048 + k * 1024); } while (0)
; #define PG8_LDB(dst, b, h) do { _Pragma("unroll") for (int n = 0; n < 2; ++n) _Pragma("unroll") for (int k = 0; k < 2; ++k) dst[n][k] = *(const PG8_LAS bf16x8*)(lds + PG8_SB(b, h) + boff + n * 2048 + k * 1024); } while (0)
; #define PG8_MMA(ai, bj, At, Bt) do { __builtin_amdgcn_s_setprio(1); _Pragma("unroll") for (int m = 0; m < 4; ++m) _Pragma("unroll") for (int n = 0; n < 2; ++n) _Pragma("unroll") for (int k = 0; k < 2; ++k) \
;         acc[ai][bj][m][n] = __builtin_amdgcn_mfma_f32_16x16x32_bf16(Bt[n][k], At[m][k], acc[ai][bj][m][n], 0, 0, 0); __builtin_amdgcn_s_setprio(0); } while (0)
; #define PG8_WAIT_V(n) asm volatile("s_waitcnt vmcnt(" #n ")" ::: "memory")
; #define PG8_WAIT_VN(n) asm volatile("s_waitcnt vmcnt(%0)" :: "n"(n) : "memory")
; #define PG8_WAIT_L(n) asm volatile("s_waitcnt lgkmcnt(" #n ")" ::: "memory")
; #define PG8_BAR __builtin_amdgcn_s_barrier()
; #define PG8_SCHED __builtin_amdgcn_sched_barrier(0)
; template <class Epi, class Sched, bool ALIGN_EPI = false, bool SP2 = false>
; __device__ __forceinline__ void gemm_phase(PG8_LAS unsigned char* lds, const Gemm g, const Sched& S, const Epi& E, const int wave_id) {
;     ...
;             PG8_WAIT_VN(8 + Epi::NS); if (strict) PG8_WAIT_V(8); PG8_WAIT_L(0); PG8_BAR; PG8_MMA(1, 0, At, B0); PG8_MMA(1, 1, At, B1); PG8_BAR; PG8_SCHED;
;             PG8_LDB(B0, 1, 0); PG8_LDB(B1, 1, 1); PG8_SCHED; PG8_LDA(At, 1, 0); PG8_STAGE(PG8_SA(0, 1), a2 + hstep, voffA);
;             PG8_WAIT_V(8); PG8_WAIT_L(0); PG8_BAR; PG8_MMA(0, 0, At, B0); PG8_MMA(0, 1, At, B1); PG8_BAR; PG8_SCHED;
.LBB0_1821:
	s_waitcnt lgkmcnt(0)
	s_setprio 1
	s_barrier
	v_mfma_f32_16x16x32_bf16 v[62:65], v[146:149], v[186:189], v[62:65]
	v_mfma_f32_16x16x32_bf16 v[58:61], v[154:157], v[186:189], v[58:61]
	v_mfma_f32_16x16x32_bf16 v[46:49], v[146:149], v[178:181], v[46:49]
	v_mfma_f32_16x16x32_bf16 v[42:45], v[154:157], v[178:181], v[42:45]
	v_mfma_f32_16x16x32_bf16 v[30:33], v[146:149], v[170:173], v[30:33]
	v_mfma_f32_16x16x32_bf16 v[26:29], v[154:157], v[170:173], v[26:29]
	v_mfma_f32_16x16x32_bf16 v[14:17], v[146:149], v[162:165], v[14:17]
	v_mfma_f32_16x16x32_bf16 v[10:13], v[154:157], v[162:165], v[10:13]
	v_mfma_f32_16x16x32_bf16 v[62:65], v[150:153], v[190:193], v[62:65]
	v_mfma_f32_16x16x32_bf16 v[58:61], v[158:161], v[190:193], v[58:61]
	v_mfma_f32_16x16x32_bf16 v[46:49], v[150:153], v[182:185], v[46:49]
	v_mfma_f32_16x16x32_bf16 v[42:45], v[158:161], v[182:185], v[42:45]
	v_mfma_f32_16x16x32_bf16 v[30:33], v[150:153], v[174:177], v[30:33]
	v_mfma_f32_16x16x32_bf16 v[26:29], v[158:161], v[174:177], v[26:29]
	v_mfma_f32_16x16x32_bf16 v[14:17], v[150:153], v[166:169], v[14:17]
	v_mfma_f32_16x16x32_bf16 v[10:13], v[158:161], v[166:169], v[10:13]
	s_setprio 0
	s_setprio 1
	v_mfma_f32_16x16x32_bf16 v[54:57], v[130:133], v[186:189], v[54:57]
	v_mfma_f32_16x16x32_bf16 v[50:53], v[138:141], v[186:189], v[50:53]
	v_mfma_f32_16x16x32_bf16 v[38:41], v[130:133], v[178:181], v[38:41]
	v_mfma_f32_16x16x32_bf16 v[34:37], v[138:141], v[178:181], v[34:37]
	v_mfma_f32_16x16x32_bf16 v[22:25], v[130:133], v[170:173], v[22:25]
	v_mfma_f32_16x16x32_bf16 v[18:21], v[138:141], v[170:173], v[18:21]
	v_mfma_f32_16x16x32_bf16 v[6:9], v[130:133], v[162:165], v[6:9]
	v_mfma_f32_16x16x32_bf16 v[2:5], v[138:141], v[162:165], v[2:5]
	v_mfma_f32_16x16x32_bf16 v[54:57], v[134:137], v[190:193], v[54:57]
	v_mfma_f32_16x16x32_bf16 v[50:53], v[142:145], v[190:193], v[50:53]
	v_mfma_f32_16x16x32_bf16 v[38:41], v[134:137], v[182:185], v[38:41]
	v_mfma_f32_16x16x32_bf16 v[34:37], v[142:145], v[182:185], v[34:37]
	v_mfma_f32_16x16x32_bf16 v[22:25], v[134:137], v[174:177], v[22:25]
	v_mfma_f32_16x16x32_bf16 v[18:21], v[142:145], v[174:177], v[18:21]
	v_mfma_f32_16x16x32_bf16 v[6:9], v[134:137], v[166:169], v[6:9]
	v_mfma_f32_16x16x32_bf16 v[2:5], v[142:145], v[166:169], v[2:5]
	s_setprio 0
	s_barrier
	s_add_i32 s26, 0, 0x18000
	s_add_i32 s27, 0, 0x1c000
	v_add_u32_e32 v142, s26, v246
	v_add_u32_e32 v158, s27, v246
	ds_read_b128 v[130:133], v142
	ds_read_b128 v[134:137], v142 offset:1024
	ds_read_b128 v[138:141], v142 offset:2048
	ds_read_b128 v[142:145], v142 offset:3072
	ds_read_b128 v[146:149], v158
	ds_read_b128 v[150:153], v158 offset:1024
	ds_read_b128 v[154:157], v158 offset:2048
	ds_read_b128 v[158:161], v158 offset:3072
	s_add_u32 s24, s24, 0x40000
	s_addc_u32 s25, s25, 0
	s_mov_b32 m0, s50
	v_lshl_add_u64 v[194:195], s[24:25], 0, v[210:211]
	ds_read_b128 v[162:165], v247 offset:32768
	ds_read_b128 v[166:169], v247 offset:33792
	ds_read_b128 v[170:173], v247 offset:34816
	ds_read_b128 v[174:177], v247 offset:35840
	ds_read_b128 v[178:181], v247 offset:36864
	ds_read_b128 v[182:185], v247 offset:37888
	ds_read_b128 v[186:189], v247 offset:38912
	ds_read_b128 v[190:193], v247 offset:39936
	global_load_lds_dwordx4 v[194:195], off
	v_lshl_add_u64 v[194:195], s[24:25], 0, v[214:215]
	s_mov_b32 m0, s51
	s_nop 0
	global_load_lds_dwordx4 v[194:195], off
	s_waitcnt vmcnt(26)
	s_cmp_eq_u32 s100, 0
	s_cbranch_scc1 .Lthird_wait_relaxed_3
	s_waitcnt vmcnt(8)
; #define PG8_STAGE(bufoff, gbase, voff) do { _Pragma("unroll") for (int _i = 0; _i < 2; ++_i) \
;         __builtin_amdgcn_global_load_lds((const unsigned*)((const char*)(gbase) + (voff)[_i]), (PG8_LAS unsigned*)(lds + (bufoff) + ldsw + _i * 8192), 16, 0, 0); } while (0)
; #define PG8_LDA(dst, b, h) do { _Pragma("unroll") for (int m = 0; m < 4; ++m) _Pragma("unroll") for (int k = 0; k < 2; ++k) dst[m][k] = *(const PG8_LAS bf16x8*)(lds + PG8_SA(b, h) + aoff + m * 2048 + k * 1024); } while (0)
; #define PG8_MMA(ai, bj, At, Bt) do { __builtin_amdgcn_s_setprio(1); _Pragma("unroll") for (int m = 0; m < 4; ++m) _Pragma("unroll") for (int n = 0; n < 2; ++n) _Pragma("unroll") for (int k = 0; k < 2; ++k) \
;         acc[ai][bj][m][n] = __builtin_amdgcn_mfma_f32_16x16x32_bf16(Bt[n][k], At[m][k], acc[ai][bj][m][n], 0, 0, 0); __builtin_amdgcn_s_setprio(0); } while (0)
; #define PG8_WAIT_V(n) asm volatile("s_waitcnt vmcnt(" #n ")" ::: "memory")
; #define PG8_WAIT_L(n) asm volatile("s_waitcnt lgkmcnt(" #n ")" ::: "memory")
; #define PG8_BAR __builtin_amdgcn_s_barrier()
; #define PG8_SCHED __builtin_amdgcn_sched_barrier(0)
; template <class Epi, class Sched, bool ALIGN_EPI = false, bool SP2 = false>
; __device__ __forceinline__ void gemm_phase(PG8_LAS unsigned char* lds, const Gemm g, const Sched& S, const Epi& E, const int wave_id) {
;     ...
;             PG8_WAIT_V(8); PG8_WAIT_L(0); PG8_BAR; PG8_MMA(0, 0, At, B0); PG8_MMA(0, 1, At, B1); PG8_BAR; PG8_SCHED;
;             PG8_LDA(At, 1, 1); PG8_STAGE(PG8_SB(1, 0), b3, voffB); PG8_STAGE(PG8_SB(1, 1), b3 + hstep, voffB); PG8_STAGE(PG8_SA(1, 0), a3, voffA);
;             PG8_WAIT_V(8); PG8_WAIT_L(0); PG8_BAR; PG8_MMA(1, 0, At, B0); PG8_MMA(1, 1, At, B1); PG8_BAR; PG8_SCHED;
.Lthird_wait_relaxed_3:
	s_waitcnt lgkmcnt(0)
	s_setprio 1
	s_barrier
	v_mfma_f32_16x16x32_bf16 v[126:129], v[130:133], v[162:165], v[126:129]
	v_mfma_f32_16x16x32_bf16 v[122:125], v[138:141], v[162:165], v[122:125]
	v_mfma_f32_16x16x32_bf16 v[110:113], v[130:133], v[170:173], v[110:113]
	v_mfma_f32_16x16x32_bf16 v[106:109], v[138:141], v[170:173], v[106:109]
	v_mfma_f32_16x16x32_bf16 v[94:97], v[130:133], v[178:181], v[94:97]
	v_mfma_f32_16x16x32_bf16 v[90:93], v[138:141], v[178:181], v[90:93]
	v_mfma_f32_16x16x32_bf16 v[78:81], v[130:133], v[186:189], v[78:81]
	v_mfma_f32_16x16x32_bf16 v[74:77], v[138:141], v[186:189], v[74:77]
	v_mfma_f32_16x16x32_bf16 v[126:129], v[134:137], v[166:169], v[126:129]
	v_mfma_f32_16x16x32_bf16 v[122:125], v[142:145], v[166:169], v[122:125]
	v_mfma_f32_16x16x32_bf16 v[110:113], v[134:137], v[174:177], v[110:113]
	v_mfma_f32_16x16x32_bf16 v[106:109], v[142:145], v[174:177], v[106:109]
	v_mfma_f32_16x16x32_bf16 v[94:97], v[134:137], v[182:185], v[94:97]
	v_mfma_f32_16x16x32_bf16 v[90:93], v[142:145], v[182:185], v[90:93]
	v_mfma_f32_16x16x32_bf16 v[78:81], v[134:137], v[190:193], v[78:81]
	v_mfma_f32_16x16x32_bf16 v[74:77], v[142:145], v[190:193], v[74:77]
	s_setprio 0
	s_setprio 1
	v_mfma_f32_16x16x32_bf16 v[118:121], v[146:149], v[162:165], v[118:121]
	v_mfma_f32_16x16x32_bf16 v[114:117], v[154:157], v[162:165], v[114:117]
	v_mfma_f32_16x16x32_bf16 v[102:105], v[146:149], v[170:173], v[102:105]
	v_mfma_f32_16x16x32_bf16 v[98:101], v[154:157], v[170:173], v[98:101]
	v_mfma_f32_16x16x32_bf16 v[86:89], v[146:149], v[178:181], v[86:89]
	v_mfma_f32_16x16x32_bf16 v[82:85], v[154:157], v[178:181], v[82:85]
	v_mfma_f32_16x16x32_bf16 v[70:73], v[146:149], v[186:189], v[70:73]
	v_mfma_f32_16x16x32_bf16 v[66:69], v[154:157], v[186:189], v[66:69]
	v_mfma_f32_16x16x32_bf16 v[118:121], v[150:153], v[166:169], v[118:121]
	v_mfma_f32_16x16x32_bf16 v[114:117], v[158:161], v[166:169], v[114:117]
	v_mfma_f32_16x16x32_bf16 v[102:105], v[150:153], v[174:177], v[102:105]
	v_mfma_f32_16x16x32_bf16 v[98:101], v[158:161], v[174:177], v[98:101]
	v_mfma_f32_16x16x32_bf16 v[86:89], v[150:153], v[182:185], v[86:89]
	v_mfma_f32_16x16x32_bf16 v[82:85], v[158:161], v[182:185], v[82:85]
	v_mfma_f32_16x16x32_bf16 v[70:73], v[150:153], v[190:193], v[70:73]
	v_mfma_f32_16x16x32_bf16 v[66:69], v[158:161], v[190:193], v[66:69]
	s_setprio 0
	s_barrier
	s_add_i32 s24, s26, s38
	v_lshl_add_u64 v[194:195], v[232:233], 0, s[64:65]
	s_mov_b32 m0, s24
	ds_read_b128 v[162:165], v247 offset:49152
	ds_read_b128 v[166:169], v247 offset:50176
	ds_read_b128 v[170:173], v247 offset:51200
	ds_read_b128 v[174:177], v247 offset:52224
	ds_read_b128 v[178:181], v247 offset:53248
	ds_read_b128 v[182:185], v247 offset:54272
	ds_read_b128 v[186:189], v247 offset:55296
	ds_read_b128 v[190:193], v247 offset:56320
	global_load_lds_dwordx4 v[194:195], off
	s_add_i32 m0, s24, 0x2000
	s_add_u32 s22, s22, 0x40080
	v_lshl_add_u64 v[194:195], v[230:231], 0, s[64:65]
	s_addc_u32 s23, s23, 0
	s_add_i32 s24, s27, s38
	global_load_lds_dwordx4 v[194:195], off
	v_lshl_add_u64 v[194:195], s[22:23], 0, v[212:213]
	s_mov_b32 m0, s24
	s_nop 0
	global_load_lds_dwordx4 v[194:195], off
	v_lshl_add_u64 v[194:195], s[22:23], 0, v[216:217]
	s_add_i32 m0, s24, 0x2000
	s_nop 0
	global_load_lds_dwordx4 v[194:195], off
	v_lshl_add_u64 v[194:195], v[226:227], 0, s[64:65]
	s_mov_b32 m0, s54
	s_nop 0
	global_load_lds_dwordx4 v[194:195], off
	v_lshl_add_u64 v[194:195], v[228:229], 0, s[64:65]
	s_mov_b32 m0, s56
	s_nop 0
	global_load_lds_dwordx4 v[194:195], off
	s_waitcnt vmcnt(8)
	s_waitcnt lgkmcnt(0)
	s_setprio 1
	s_barrier
	v_mfma_f32_16x16x32_bf16 v[62:65], v[130:133], v[162:165], v[62:65]
	v_mfma_f32_16x16x32_bf16 v[58:61], v[138:141], v[162:165], v[58:61]
	v_mfma_f32_16x16x32_bf16 v[46:49], v[130:133], v[170:173], v[46:49]
	v_mfma_f32_16x16x32_bf16 v[42:45], v[138:141], v[170:173], v[42:45]
	v_mfma_f32_16x16x32_bf16 v[30:33], v[130:133], v[178:181], v[30:33]
	v_mfma_f32_16x16x32_bf16 v[26:29], v[138:141], v[178:181], v[26:29]
	v_mfma_f32_16x16x32_bf16 v[14:17], v[130:133], v[186:189], v[14:17]
	v_mfma_f32_16x16x32_bf16 v[10:13], v[138:141], v[186:189], v[10:13]
	v_mfma_f32_16x16x32_bf16 v[62:65], v[134:137], v[166:169], v[62:65]
	v_mfma_f32_16x16x32_bf16 v[58:61], v[142:145], v[166:169], v[58:61]
	v_mfma_f32_16x16x32_bf16 v[46:49], v[134:137], v[174:177], v[46:49]
	v_mfma_f32_16x16x32_bf16 v[42:45], v[142:145], v[174:177], v[42:45]
	v_mfma_f32_16x16x32_bf16 v[30:33], v[134:137], v[182:185], v[30:33]
	v_mfma_f32_16x16x32_bf16 v[26:29], v[142:145], v[182:185], v[26:29]
	v_mfma_f32_16x16x32_bf16 v[14:17], v[134:137], v[190:193], v[14:17]
	v_mfma_f32_16x16x32_bf16 v[10:13], v[142:145], v[190:193], v[10:13]
	s_setprio 0
	s_setprio 1
	v_mfma_f32_16x16x32_bf16 v[54:57], v[146:149], v[162:165], v[54:57]
	v_mfma_f32_16x16x32_bf16 v[50:53], v[154:157], v[162:165], v[50:53]
	v_mfma_f32_16x16x32_bf16 v[38:41], v[146:149], v[170:173], v[38:41]
	v_mfma_f32_16x16x32_bf16 v[34:37], v[154:157], v[170:173], v[34:37]
	v_mfma_f32_16x16x32_bf16 v[22:25], v[146:149], v[178:181], v[22:25]
	v_mfma_f32_16x16x32_bf16 v[18:21], v[154:157], v[178:181], v[18:21]
	v_mfma_f32_16x16x32_bf16 v[6:9], v[146:149], v[186:189], v[6:9]
	v_mfma_f32_16x16x32_bf16 v[2:5], v[154:157], v[186:189], v[2:5]
	v_mfma_f32_16x16x32_bf16 v[54:57], v[150:153], v[166:169], v[54:57]
	v_mfma_f32_16x16x32_bf16 v[50:53], v[158:161], v[166:169], v[50:53]
	v_mfma_f32_16x16x32_bf16 v[38:41], v[150:153], v[174:177], v[38:41]
	v_mfma_f32_16x16x32_bf16 v[34:37], v[158:161], v[174:177], v[34:37]
	v_mfma_f32_16x16x32_bf16 v[22:25], v[150:153], v[182:185], v[22:25]
	v_mfma_f32_16x16x32_bf16 v[18:21], v[158:161], v[182:185], v[18:21]
	v_mfma_f32_16x16x32_bf16 v[6:9], v[150:153], v[190:193], v[6:9]
	v_mfma_f32_16x16x32_bf16 v[2:5], v[158:161], v[190:193], v[2:5]
	s_setprio 0
	s_barrier
	s_add_i32 s74, s74, 2
	s_add_u32 s20, s20, 0x100
	s_addc_u32 s21, s21, 0
	s_cmp_gt_u32 s74, 13
	s_cbranch_scc1 .LBB0_1826

; #define PG8_STAGE(bufoff, gbase, voff) do { _Pragma("unroll") for (int _i = 0; _i < 2; ++_i) \
;         __builtin_amdgcn_global_load_lds((const unsigned*)((const char*)(gbase) + (voff)[_i]), (PG8_LAS unsigned*)(lds + (bufoff) + ldsw + _i * 8192), 16, 0, 0); } while (0)
; #define PG8_LDA(dst, b, h) do { _Pragma("unroll") for (int m = 0; m < 4; ++m) _Pragma("unroll") for (int k = 0; k < 2; ++k) dst[m][k] = *(const PG8_LAS bf16x8*)(lds + PG8_SA(b, h) + aoff + m * 2048 + k * 1024); } while (0)
; #define PG8_LDB(dst, b, h) do { _Pragma("unroll") for (int n = 0; n < 2; ++n) _Pragma("unroll") for (int k = 0; k < 2; ++k) dst[n][k] = *(const PG8_LAS bf16x8*)(lds + PG8_SB(b, h) + boff + n * 2048 + k * 1024); } while (0)
; #define PG8_WAIT_V(n) asm volatile("s_waitcnt vmcnt(" #n ")" ::: "memory")
; #define PG8_WAIT_VN(n) asm volatile("s_waitcnt vmcnt(%0)" :: "n"(n) : "memory")
; #define PG8_WAIT_L(n) asm volatile("s_waitcnt lgkmcnt(" #n ")" ::: "memory")
; #define PG8_BAR __builtin_amdgcn_s_barrier()
; template <class Epi, class Sched, bool ALIGN_EPI = false, bool SP2 = false>
; __device__ __forceinline__ void gemm_phase(PG8_LAS unsigned char* lds, const Gemm g, const Sched& S, const Epi& E, const int wave_id) {
;     ...
;             const bool last = (t == nt - 2);
;             const char* a1 = cA + (size_t)(t + 1) * kstep;
;             const char* a2 = last ? nA : cA + (size_t)(t + 2) * kstep; const char* b2 = last ? nB : cB + (size_t)(t + 2) * kstep;
;             const char* a3 = a2 + kstep; const char* b3 = b2 + kstep;
;             if (last && has_next) S.a_ready(nxt);
;             if constexpr (SP2) {
;             int tz_ = __builtin_amdgcn_readfirstlane(t | (ui > 0 ? 0 : 1)); asm volatile("" : "+s"(tz_));
;             const bool strict = !(Epi::NS > 0 && tz_ == 0);
;             PG8_LDB(B0, 0, 0); PG8_LDB(B1, 0, 1); PG8_SCHED; PG8_LDA(At, 0, 0); PG8_STAGE(PG8_SA(1, 1), a1 + hstep, voffA);
;             PG8_WAIT_VN(8 + Epi::NS); if (strict) PG8_WAIT_V(8); PG8_WAIT_L(0); PG8_BAR; PG8_MMA(0, 0, At, B0); PG8_MMA(0, 1, At, B1); PG8_BAR; PG8_SCHED;
;             PG8_LDA(At, 0, 1); PG8_STAGE(PG8_SB(0, 0), b2, voffB); PG8_STAGE(PG8_SB(0, 1), b2 + hstep, voffB); PG8_STAGE(PG8_SA(0, 0), a2, voffA);
;             PG8_WAIT_VN(8 + Epi::NS); if (strict) PG8_WAIT_V(8); PG8_WAIT_L(0); PG8_BAR; PG8_MMA(1, 0, At, B0); PG8_MMA(1, 1, At, B1); PG8_BAR; PG8_SCHED;
.LBB0_1824:
	s_add_u32 s22, s18, s20
	s_addc_u32 s23, s19, s21
	s_add_u32 s22, s22, 0x100
	s_addc_u32 s23, s23, 0
	s_add_u32 s53, s68, s20
	s_addc_u32 s75, s69, s21
	s_cmpk_eq_i32 s20, 0x700
	s_cselect_b32 s25, s11, s23
	s_cselect_b32 s24, s63, s22
	s_cselect_b32 s23, s9, s75
	s_cselect_b32 s22, s67, s53
	s_waitcnt lgkmcnt(0)
	s_setprio 1
	s_barrier
	v_mfma_f32_16x16x32_bf16 v[126:129], v[146:149], v[186:189], v[126:129]
	v_mfma_f32_16x16x32_bf16 v[122:125], v[154:157], v[186:189], v[122:125]
	v_mfma_f32_16x16x32_bf16 v[110:113], v[146:149], v[178:181], v[110:113]
	v_mfma_f32_16x16x32_bf16 v[106:109], v[154:157], v[178:181], v[106:109]
	v_mfma_f32_16x16x32_bf16 v[94:97], v[146:149], v[170:173], v[94:97]
	v_mfma_f32_16x16x32_bf16 v[90:93], v[154:157], v[170:173], v[90:93]
	v_mfma_f32_16x16x32_bf16 v[78:81], v[146:149], v[162:165], v[78:81]
	v_mfma_f32_16x16x32_bf16 v[74:77], v[154:157], v[162:165], v[74:77]
	v_mfma_f32_16x16x32_bf16 v[126:129], v[150:153], v[190:193], v[126:129]
	v_mfma_f32_16x16x32_bf16 v[122:125], v[158:161], v[190:193], v[122:125]
	v_mfma_f32_16x16x32_bf16 v[110:113], v[150:153], v[182:185], v[110:113]
	v_mfma_f32_16x16x32_bf16 v[106:109], v[158:161], v[182:185], v[106:109]
	v_mfma_f32_16x16x32_bf16 v[94:97], v[150:153], v[174:177], v[94:97]
	v_mfma_f32_16x16x32_bf16 v[90:93], v[158:161], v[174:177], v[90:93]
	v_mfma_f32_16x16x32_bf16 v[78:81], v[150:153], v[166:169], v[78:81]
	v_mfma_f32_16x16x32_bf16 v[74:77], v[158:161], v[166:169], v[74:77]
	s_setprio 0
	s_setprio 1
	v_mfma_f32_16x16x32_bf16 v[118:121], v[130:133], v[186:189], v[118:121]
	v_mfma_f32_16x16x32_bf16 v[114:117], v[138:141], v[186:189], v[114:117]
	v_mfma_f32_16x16x32_bf16 v[102:105], v[130:133], v[178:181], v[102:105]
	v_mfma_f32_16x16x32_bf16 v[98:101], v[138:141], v[178:181], v[98:101]
	v_mfma_f32_16x16x32_bf16 v[86:89], v[130:133], v[170:173], v[86:89]
	v_mfma_f32_16x16x32_bf16 v[82:85], v[138:141], v[170:173], v[82:85]
	v_mfma_f32_16x16x32_bf16 v[70:73], v[130:133], v[162:165], v[70:73]
	v_mfma_f32_16x16x32_bf16 v[66:69], v[138:141], v[162:165], v[66:69]
	v_mfma_f32_16x16x32_bf16 v[118:121], v[134:137], v[190:193], v[118:121]
	v_mfma_f32_16x16x32_bf16 v[114:117], v[142:145], v[190:193], v[114:117]
	v_mfma_f32_16x16x32_bf16 v[102:105], v[134:137], v[182:185], v[102:105]
	v_mfma_f32_16x16x32_bf16 v[98:101], v[142:145], v[182:185], v[98:101]
	v_mfma_f32_16x16x32_bf16 v[86:89], v[134:137], v[174:177], v[86:89]
	v_mfma_f32_16x16x32_bf16 v[82:85], v[142:145], v[174:177], v[82:85]
	v_mfma_f32_16x16x32_bf16 v[70:73], v[134:137], v[166:169], v[70:73]
	v_mfma_f32_16x16x32_bf16 v[66:69], v[142:145], v[166:169], v[66:69]
	s_setprio 0
	s_barrier
	s_mov_b32 m0, s40
	v_lshl_add_u64 v[232:233], s[22:23], 0, v[212:213]
	s_add_u32 s90, s22, 0x40000
	ds_read_b128 v[186:189], v247 offset:16384
	ds_read_b128 v[190:193], v247 offset:17408
	ds_read_b128 v[178:181], v247 offset:18432
	ds_read_b128 v[182:185], v247 offset:19456
	ds_read_b128 v[170:173], v247 offset:20480
	ds_read_b128 v[174:177], v247 offset:21504
	ds_read_b128 v[162:165], v247 offset:22528
	ds_read_b128 v[166:169], v247 offset:23552
	global_load_lds_dwordx4 v[232:233], off
	v_lshl_add_u64 v[230:231], s[22:23], 0, v[216:217]
	s_mov_b32 m0, s41
	s_addc_u32 s91, s23, 0
	global_load_lds_dwordx4 v[230:231], off
	v_lshl_add_u64 v[194:195], s[90:91], 0, v[212:213]
	s_mov_b32 m0, s42
	v_lshl_add_u64 v[226:227], s[24:25], 0, v[210:211]
	global_load_lds_dwordx4 v[194:195], off
	v_lshl_add_u64 v[194:195], s[90:91], 0, v[216:217]
	s_mov_b32 m0, s43
	v_lshl_add_u64 v[228:229], s[24:25], 0, v[214:215]
	global_load_lds_dwordx4 v[194:195], off
	s_mov_b32 m0, s39
	s_andn2_b64 vcc, exec, s[26:27]
	global_load_lds_dwordx4 v[226:227], off
	s_mov_b32 m0, s49
	s_nop 0
	global_load_lds_dwordx4 v[228:229], off
	s_waitcnt vmcnt(24)
	s_cbranch_vccnz .LBB0_1821
	s_waitcnt vmcnt(8)
	s_branch .LBB0_1821

; #define PG8_STAGE(bufoff, gbase, voff) do { _Pragma("unroll") for (int _i = 0; _i < 2; ++_i) \
;         __builtin_amdgcn_global_load_lds((const unsigned*)((const char*)(gbase) + (voff)[_i]), (PG8_LAS unsigned*)(lds + (bufoff) + ldsw + _i * 8192), 16, 0, 0); } while (0)
; #define PG8_LDA(dst, b, h) do { _Pragma("unroll") for (int m = 0; m < 4; ++m) _Pragma("unroll") for (int k = 0; k < 2; ++k) dst[m][k] = *(const PG8_LAS bf16x8*)(lds + PG8_SA(b, h) + aoff + m * 2048 + k * 1024); } while (0)
; #define PG8_LDB(dst, b, h) do { _Pragma("unroll") for (int n = 0; n < 2; ++n) _Pragma("unroll") for (int k = 0; k < 2; ++k) dst[n][k] = *(const PG8_LAS bf16x8*)(lds + PG8_SB(b, h) + boff + n * 2048 + k * 1024); } while (0)
; #define PG8_MMA(ai, bj, At, Bt) do { __builtin_amdgcn_s_setprio(1); _Pragma("unroll") for (int m = 0; m < 4; ++m) _Pragma("unroll") for (int n = 0; n < 2; ++n) _Pragma("unroll") for (int k = 0; k < 2; ++k) \
;         acc[ai][bj][m][n] = __builtin_amdgcn_mfma_f32_16x16x32_bf16(Bt[n][k], At[m][k], acc[ai][bj][m][n], 0, 0, 0); __builtin_amdgcn_s_setprio(0); } while (0)
; #define PG8_WAIT_V(n) asm volatile("s_waitcnt vmcnt(" #n ")" ::: "memory")
; #define PG8_WAIT_VN(n) asm volatile("s_waitcnt vmcnt(%0)" :: "n"(n) : "memory")
; #define PG8_WAIT_L(n) asm volatile("s_waitcnt lgkmcnt(" #n ")" ::: "memory")
; #define PG8_BAR __builtin_amdgcn_s_barrier()
; #define PG8_SCHED __builtin_amdgcn_sched_barrier(0)
; template <class Epi, class Sched, bool ALIGN_EPI = false, bool SP2 = false>
; __device__ __forceinline__ void gemm_phase(PG8_LAS unsigned char* lds, const Gemm g, const Sched& S, const Epi& E, const int wave_id) {
;     ...
;             PG8_WAIT_VN(8 + Epi::NS); if (strict) PG8_WAIT_V(8); PG8_WAIT_L(0); PG8_BAR; PG8_MMA(1, 0, At, B0); PG8_MMA(1, 1, At, B1); PG8_BAR; PG8_SCHED;
;             PG8_LDB(B0, 1, 0); PG8_LDB(B1, 1, 1); PG8_SCHED; PG8_LDA(At, 1, 0); PG8_STAGE(PG8_SA(0, 1), a2 + hstep, voffA);
;             PG8_WAIT_V(8); PG8_WAIT_L(0); PG8_BAR; PG8_MMA(0, 0, At, B0); PG8_MMA(0, 1, At, B1); PG8_BAR; PG8_SCHED;
.LBB0_1889:
	s_waitcnt lgkmcnt(0)
	s_setprio 1
	s_barrier
	v_mfma_f32_16x16x32_bf16 v[62:65], v[146:149], v[186:189], v[62:65]
	v_mfma_f32_16x16x32_bf16 v[58:61], v[154:157], v[186:189], v[58:61]
	v_mfma_f32_16x16x32_bf16 v[54:57], v[146:149], v[178:181], v[54:57]
	v_mfma_f32_16x16x32_bf16 v[50:53], v[154:157], v[178:181], v[50:53]
	v_mfma_f32_16x16x32_bf16 v[30:33], v[146:149], v[170:173], v[30:33]
	v_mfma_f32_16x16x32_bf16 v[26:29], v[154:157], v[170:173], v[26:29]
	v_mfma_f32_16x16x32_bf16 v[22:25], v[146:149], v[162:165], v[22:25]
	v_mfma_f32_16x16x32_bf16 v[18:21], v[154:157], v[162:165], v[18:21]
	v_mfma_f32_16x16x32_bf16 v[62:65], v[150:153], v[190:193], v[62:65]
	v_mfma_f32_16x16x32_bf16 v[58:61], v[158:161], v[190:193], v[58:61]
	v_mfma_f32_16x16x32_bf16 v[54:57], v[150:153], v[182:185], v[54:57]
	v_mfma_f32_16x16x32_bf16 v[50:53], v[158:161], v[182:185], v[50:53]
	v_mfma_f32_16x16x32_bf16 v[30:33], v[150:153], v[174:177], v[30:33]
	v_mfma_f32_16x16x32_bf16 v[26:29], v[158:161], v[174:177], v[26:29]
	v_mfma_f32_16x16x32_bf16 v[22:25], v[150:153], v[166:169], v[22:25]
	v_mfma_f32_16x16x32_bf16 v[18:21], v[158:161], v[166:169], v[18:21]
	s_setprio 0
	s_setprio 1
	v_mfma_f32_16x16x32_bf16 v[46:49], v[130:133], v[186:189], v[46:49]
	v_mfma_f32_16x16x32_bf16 v[42:45], v[138:141], v[186:189], v[42:45]
	v_mfma_f32_16x16x32_bf16 v[38:41], v[130:133], v[178:181], v[38:41]
	v_mfma_f32_16x16x32_bf16 v[34:37], v[138:141], v[178:181], v[34:37]
	v_mfma_f32_16x16x32_bf16 v[14:17], v[130:133], v[170:173], v[14:17]
	v_mfma_f32_16x16x32_bf16 v[10:13], v[138:141], v[170:173], v[10:13]
	v_mfma_f32_16x16x32_bf16 v[6:9], v[130:133], v[162:165], v[6:9]
	v_mfma_f32_16x16x32_bf16 v[2:5], v[138:141], v[162:165], v[2:5]
	v_mfma_f32_16x16x32_bf16 v[46:49], v[134:137], v[190:193], v[46:49]
	v_mfma_f32_16x16x32_bf16 v[42:45], v[142:145], v[190:193], v[42:45]
	v_mfma_f32_16x16x32_bf16 v[38:41], v[134:137], v[182:185], v[38:41]
	v_mfma_f32_16x16x32_bf16 v[34:37], v[142:145], v[182:185], v[34:37]
	v_mfma_f32_16x16x32_bf16 v[14:17], v[134:137], v[174:177], v[14:17]
	v_mfma_f32_16x16x32_bf16 v[10:13], v[142:145], v[174:177], v[10:13]
	v_mfma_f32_16x16x32_bf16 v[6:9], v[134:137], v[166:169], v[6:9]
	v_mfma_f32_16x16x32_bf16 v[2:5], v[142:145], v[166:169], v[2:5]
	s_setprio 0
	s_barrier
	s_add_i32 s16, 0, 0x18000
	s_add_i32 s17, 0, 0x1c000
	v_add_u32_e32 v142, s16, v231
	v_add_u32_e32 v158, s17, v231
	ds_read_b128 v[130:133], v142
	ds_read_b128 v[134:137], v142 offset:1024
	ds_read_b128 v[138:141], v142 offset:2048
	ds_read_b128 v[142:145], v142 offset:3072
	ds_read_b128 v[146:149], v158
	ds_read_b128 v[150:153], v158 offset:1024
	ds_read_b128 v[154:157], v158 offset:2048
	ds_read_b128 v[158:161], v158 offset:3072
	s_add_u32 s14, s14, 0x40000
	s_addc_u32 s15, s15, 0
	s_mov_b32 m0, s28
	v_lshl_add_u64 v[194:195], s[14:15], 0, v[210:211]
	ds_read_b128 v[162:165], v232 offset:32768
	ds_read_b128 v[166:169], v232 offset:33792
	ds_read_b128 v[170:173], v232 offset:34816
	ds_read_b128 v[174:177], v232 offset:35840
	ds_read_b128 v[178:181], v232 offset:36864
	ds_read_b128 v[182:185], v232 offset:37888
	ds_read_b128 v[186:189], v232 offset:38912
	ds_read_b128 v[190:193], v232 offset:39936
	global_load_lds_dwordx4 v[194:195], off
	v_lshl_add_u64 v[194:195], s[14:15], 0, v[214:215]
	s_mov_b32 m0, s29
	s_nop 0
	global_load_lds_dwordx4 v[194:195], off
	s_waitcnt vmcnt(8)
	s_waitcnt lgkmcnt(0)
	s_setprio 1
	s_barrier
	v_mfma_f32_16x16x32_bf16 v[126:129], v[130:133], v[162:165], v[126:129]
	v_mfma_f32_16x16x32_bf16 v[122:125], v[138:141], v[162:165], v[122:125]
	v_mfma_f32_16x16x32_bf16 v[118:121], v[130:133], v[170:173], v[118:121]
	v_mfma_f32_16x16x32_bf16 v[114:117], v[138:141], v[170:173], v[114:117]
	v_mfma_f32_16x16x32_bf16 v[94:97], v[130:133], v[178:181], v[94:97]
	v_mfma_f32_16x16x32_bf16 v[90:93], v[138:141], v[178:181], v[90:93]
	v_mfma_f32_16x16x32_bf16 v[86:89], v[130:133], v[186:189], v[86:89]
	v_mfma_f32_16x16x32_bf16 v[82:85], v[138:141], v[186:189], v[82:85]
	v_mfma_f32_16x16x32_bf16 v[126:129], v[134:137], v[166:169], v[126:129]
	v_mfma_f32_16x16x32_bf16 v[122:125], v[142:145], v[166:169], v[122:125]
	v_mfma_f32_16x16x32_bf16 v[118:121], v[134:137], v[174:177], v[118:121]
	v_mfma_f32_16x16x32_bf16 v[114:117], v[142:145], v[174:177], v[114:117]
	v_mfma_f32_16x16x32_bf16 v[94:97], v[134:137], v[182:185], v[94:97]
	v_mfma_f32_16x16x32_bf16 v[90:93], v[142:145], v[182:185], v[90:93]
	v_mfma_f32_16x16x32_bf16 v[86:89], v[134:137], v[190:193], v[86:89]
	v_mfma_f32_16x16x32_bf16 v[82:85], v[142:145], v[190:193], v[82:85]
	s_setprio 0
	s_setprio 1
	v_mfma_f32_16x16x32_bf16 v[110:113], v[146:149], v[162:165], v[110:113]
	v_mfma_f32_16x16x32_bf16 v[106:109], v[154:157], v[162:165], v[106:109]
	v_mfma_f32_16x16x32_bf16 v[102:105], v[146:149], v[170:173], v[102:105]
	v_mfma_f32_16x16x32_bf16 v[98:101], v[154:157], v[170:173], v[98:101]
	v_mfma_f32_16x16x32_bf16 v[78:81], v[146:149], v[178:181], v[78:81]
	v_mfma_f32_16x16x32_bf16 v[74:77], v[154:157], v[178:181], v[74:77]
	v_mfma_f32_16x16x32_bf16 v[70:73], v[146:149], v[186:189], v[70:73]
	v_mfma_f32_16x16x32_bf16 v[66:69], v[154:157], v[186:189], v[66:69]
	v_mfma_f32_16x16x32_bf16 v[110:113], v[150:153], v[166:169], v[110:113]
	v_mfma_f32_16x16x32_bf16 v[106:109], v[158:161], v[166:169], v[106:109]
	v_mfma_f32_16x16x32_bf16 v[102:105], v[150:153], v[174:177], v[102:105]
	v_mfma_f32_16x16x32_bf16 v[98:101], v[158:161], v[174:177], v[98:101]
	v_mfma_f32_16x16x32_bf16 v[78:81], v[150:153], v[182:185], v[78:81]
	v_mfma_f32_16x16x32_bf16 v[74:77], v[158:161], v[182:185], v[74:77]
	v_mfma_f32_16x16x32_bf16 v[70:73], v[150:153], v[190:193], v[70:73]
	v_mfma_f32_16x16x32_bf16 v[66:69], v[158:161], v[190:193], v[66:69]
	s_setprio 0
	s_barrier
; #define PG8_STAGE(bufoff, gbase, voff) do { _Pragma("unroll") for (int _i = 0; _i < 2; ++_i) \
;         __builtin_amdgcn_global_load_lds((const unsigned*)((const char*)(gbase) + (voff)[_i]), (PG8_LAS unsigned*)(lds + (bufoff) + ldsw + _i * 8192), 16, 0, 0); } while (0)
; #define PG8_LDA(dst, b, h) do { _Pragma("unroll") for (int m = 0; m < 4; ++m) _Pragma("unroll") for (int k = 0; k < 2; ++k) dst[m][k] = *(const PG8_LAS bf16x8*)(lds + PG8_SA(b, h) + aoff + m * 2048 + k * 1024); } while (0)
; #define PG8_MMA(ai, bj, At, Bt) do { __builtin_amdgcn_s_setprio(1); _Pragma("unroll") for (int m = 0; m < 4; ++m) _Pragma("unroll") for (int n = 0; n < 2; ++n) _Pragma("unroll") for (int k = 0; k < 2; ++k) \
;         acc[ai][bj][m][n] = __builtin_amdgcn_mfma_f32_16x16x32_bf16(Bt[n][k], At[m][k], acc[ai][bj][m][n], 0, 0, 0); __builtin_amdgcn_s_setprio(0); } while (0)
; #define PG8_WAIT_V(n) asm volatile("s_waitcnt vmcnt(" #n ")" ::: "memory")
; #define PG8_WAIT_L(n) asm volatile("s_waitcnt lgkmcnt(" #n ")" ::: "memory")
; #define PG8_BAR __builtin_amdgcn_s_barrier()
; #define PG8_SCHED __builtin_amdgcn_sched_barrier(0)
; template <class Epi, class Sched, bool ALIGN_EPI = false, bool SP2 = false>
; __device__ __forceinline__ void gemm_phase(PG8_LAS unsigned char* lds, const Gemm g, const Sched& S, const Epi& E, const int wave_id) {
;     ...
;             PG8_LDA(At, 1, 1); PG8_STAGE(PG8_SB(1, 0), b3, voffB); PG8_STAGE(PG8_SB(1, 1), b3 + hstep, voffB); PG8_STAGE(PG8_SA(1, 0), a3, voffA);
;             PG8_WAIT_V(8); PG8_WAIT_L(0); PG8_BAR; PG8_MMA(1, 0, At, B0); PG8_MMA(1, 1, At, B1); PG8_BAR; PG8_SCHED;
	s_add_i32 s14, s16, s21
	v_lshl_add_u64 v[194:195], v[228:229], 0, s[64:65]
	s_mov_b32 m0, s14
	ds_read_b128 v[162:165], v232 offset:49152
	ds_read_b128 v[166:169], v232 offset:50176
	ds_read_b128 v[170:173], v232 offset:51200
	ds_read_b128 v[174:177], v232 offset:52224
	ds_read_b128 v[178:181], v232 offset:53248
	ds_read_b128 v[182:185], v232 offset:54272
	ds_read_b128 v[186:189], v232 offset:55296
	ds_read_b128 v[190:193], v232 offset:56320
	global_load_lds_dwordx4 v[194:195], off
	s_add_i32 m0, s14, 0x2000
	s_add_u32 s12, s12, 0x40080
	v_lshl_add_u64 v[194:195], v[226:227], 0, s[64:65]
	s_addc_u32 s13, s13, 0
	s_add_i32 s14, s17, s21
	global_load_lds_dwordx4 v[194:195], off
	v_lshl_add_u64 v[194:195], s[12:13], 0, v[212:213]
	s_mov_b32 m0, s14
	s_nop 0
	global_load_lds_dwordx4 v[194:195], off
	v_lshl_add_u64 v[194:195], s[12:13], 0, v[216:217]
	s_add_i32 m0, s14, 0x2000
	s_nop 0
	global_load_lds_dwordx4 v[194:195], off
	v_lshl_add_u64 v[194:195], v[222:223], 0, s[64:65]
	s_mov_b32 m0, s30
	s_nop 0
	global_load_lds_dwordx4 v[194:195], off
	v_lshl_add_u64 v[194:195], v[224:225], 0, s[64:65]
	s_mov_b32 m0, s31
	s_nop 0
	global_load_lds_dwordx4 v[194:195], off
	s_waitcnt vmcnt(8)
	s_waitcnt lgkmcnt(0)
	s_setprio 1
	s_barrier
	v_mfma_f32_16x16x32_bf16 v[62:65], v[130:133], v[162:165], v[62:65]
	v_mfma_f32_16x16x32_bf16 v[58:61], v[138:141], v[162:165], v[58:61]
	v_mfma_f32_16x16x32_bf16 v[54:57], v[130:133], v[170:173], v[54:57]
	v_mfma_f32_16x16x32_bf16 v[50:53], v[138:141], v[170:173], v[50:53]
	v_mfma_f32_16x16x32_bf16 v[30:33], v[130:133], v[178:181], v[30:33]
	v_mfma_f32_16x16x32_bf16 v[26:29], v[138:141], v[178:181], v[26:29]
	v_mfma_f32_16x16x32_bf16 v[22:25], v[130:133], v[186:189], v[22:25]
	v_mfma_f32_16x16x32_bf16 v[18:21], v[138:141], v[186:189], v[18:21]
	v_mfma_f32_16x16x32_bf16 v[62:65], v[134:137], v[166:169], v[62:65]
	v_mfma_f32_16x16x32_bf16 v[58:61], v[142:145], v[166:169], v[58:61]
	v_mfma_f32_16x16x32_bf16 v[54:57], v[134:137], v[174:177], v[54:57]
	v_mfma_f32_16x16x32_bf16 v[50:53], v[142:145], v[174:177], v[50:53]
	v_mfma_f32_16x16x32_bf16 v[30:33], v[134:137], v[182:185], v[30:33]
	v_mfma_f32_16x16x32_bf16 v[26:29], v[142:145], v[182:185], v[26:29]
	v_mfma_f32_16x16x32_bf16 v[22:25], v[134:137], v[190:193], v[22:25]
	v_mfma_f32_16x16x32_bf16 v[18:21], v[142:145], v[190:193], v[18:21]
	s_setprio 0
	s_setprio 1
	v_mfma_f32_16x16x32_bf16 v[46:49], v[146:149], v[162:165], v[46:49]
	v_mfma_f32_16x16x32_bf16 v[42:45], v[154:157], v[162:165], v[42:45]
	v_mfma_f32_16x16x32_bf16 v[38:41], v[146:149], v[170:173], v[38:41]
	v_mfma_f32_16x16x32_bf16 v[34:37], v[154:157], v[170:173], v[34:37]
	v_mfma_f32_16x16x32_bf16 v[14:17], v[146:149], v[178:181], v[14:17]
	v_mfma_f32_16x16x32_bf16 v[10:13], v[154:157], v[178:181], v[10:13]
	v_mfma_f32_16x16x32_bf16 v[6:9], v[146:149], v[186:189], v[6:9]
	v_mfma_f32_16x16x32_bf16 v[2:5], v[154:157], v[186:189], v[2:5]
	v_mfma_f32_16x16x32_bf16 v[46:49], v[150:153], v[166:169], v[46:49]
	v_mfma_f32_16x16x32_bf16 v[42:45], v[158:161], v[166:169], v[42:45]
	v_mfma_f32_16x16x32_bf16 v[38:41], v[150:153], v[174:177], v[38:41]
	v_mfma_f32_16x16x32_bf16 v[34:37], v[158:161], v[174:177], v[34:37]
	v_mfma_f32_16x16x32_bf16 v[14:17], v[150:153], v[182:185], v[14:17]
	v_mfma_f32_16x16x32_bf16 v[10:13], v[158:161], v[182:185], v[10:13]
	v_mfma_f32_16x16x32_bf16 v[6:9], v[150:153], v[190:193], v[6:9]
	v_mfma_f32_16x16x32_bf16 v[2:5], v[158:161], v[190:193], v[2:5]
	s_setprio 0
	s_barrier
	s_add_u32 s10, s10, 0x100
	s_addc_u32 s11, s11, 0
	s_cmp_gt_u32 s38, 13
	v_readlane_b32 s40, v254, 55
	s_cbranch_scc1 .LBB0_1894

; #define PG8_STAGE(bufoff, gbase, voff) do { _Pragma("unroll") for (int _i = 0; _i < 2; ++_i) \
;         __builtin_amdgcn_global_load_lds((const unsigned*)((const char*)(gbase) + (voff)[_i]), (PG8_LAS unsigned*)(lds + (bufoff) + ldsw + _i * 8192), 16, 0, 0); } while (0)
; #define PG8_LDA(dst, b, h) do { _Pragma("unroll") for (int m = 0; m < 4; ++m) _Pragma("unroll") for (int k = 0; k < 2; ++k) dst[m][k] = *(const PG8_LAS bf16x8*)(lds + PG8_SA(b, h) + aoff + m * 2048 + k * 1024); } while (0)
; #define PG8_LDB(dst, b, h) do { _Pragma("unroll") for (int n = 0; n < 2; ++n) _Pragma("unroll") for (int k = 0; k < 2; ++k) dst[n][k] = *(const PG8_LAS bf16x8*)(lds + PG8_SB(b, h) + boff + n * 2048 + k * 1024); } while (0)
; #define PG8_WAIT_V(n) asm volatile("s_waitcnt vmcnt(" #n ")" ::: "memory")
; #define PG8_WAIT_VN(n) asm volatile("s_waitcnt vmcnt(%0)" :: "n"(n) : "memory")
; #define PG8_WAIT_L(n) asm volatile("s_waitcnt lgkmcnt(" #n ")" ::: "memory")
; #define PG8_BAR __builtin_amdgcn_s_barrier()
; template <class Epi, class Sched, bool ALIGN_EPI = false, bool SP2 = false>
; __device__ __forceinline__ void gemm_phase(PG8_LAS unsigned char* lds, const Gemm g, const Sched& S, const Epi& E, const int wave_id) {
;     ...
;             const bool last = (t == nt - 2);
;             const char* a1 = cA + (size_t)(t + 1) * kstep;
;             const char* a2 = last ? nA : cA + (size_t)(t + 2) * kstep; const char* b2 = last ? nB : cB + (size_t)(t + 2) * kstep;
;             const char* a3 = a2 + kstep; const char* b3 = b2 + kstep;
;             if (last && has_next) S.a_ready(nxt);
;             if constexpr (SP2) {
;             int tz_ = __builtin_amdgcn_readfirstlane(t | (ui > 0 ? 0 : 1)); asm volatile("" : "+s"(tz_));
;             const bool strict = !(Epi::NS > 0 && tz_ == 0);
;             PG8_LDB(B0, 0, 0); PG8_LDB(B1, 0, 1); PG8_SCHED; PG8_LDA(At, 0, 0); PG8_STAGE(PG8_SA(1, 1), a1 + hstep, voffA);
;             PG8_WAIT_VN(8 + Epi::NS); if (strict) PG8_WAIT_V(8); PG8_WAIT_L(0); PG8_BAR; PG8_MMA(0, 0, At, B0); PG8_MMA(0, 1, At, B1); PG8_BAR; PG8_SCHED;
;             PG8_LDA(At, 0, 1); PG8_STAGE(PG8_SB(0, 0), b2, voffB); PG8_STAGE(PG8_SB(0, 1), b2 + hstep, voffB); PG8_STAGE(PG8_SA(0, 0), a2, voffA);
;             PG8_WAIT_VN(8 + Epi::NS); if (strict) PG8_WAIT_V(8); PG8_WAIT_L(0); PG8_BAR; PG8_MMA(1, 0, At, B0); PG8_MMA(1, 1, At, B1); PG8_BAR; PG8_SCHED;
.LBB0_1892:
	s_add_u32 s12, s36, s10
	s_addc_u32 s13, s37, s11
	s_add_u32 s12, s12, 0x8200100
	s_addc_u32 s13, s13, 0
	s_add_u32 s39, s34, s10
	s_addc_u32 s40, s35, s11
	s_cmpk_eq_i32 s10, 0x700
	s_cselect_b32 s15, s9, s13
	s_cselect_b32 s14, s8, s12
	s_cselect_b32 s13, s7, s40
	s_cselect_b32 s12, s6, s39
	s_waitcnt lgkmcnt(0)
	s_setprio 1
	s_barrier
	v_mfma_f32_16x16x32_bf16 v[126:129], v[146:149], v[186:189], v[126:129]
	v_mfma_f32_16x16x32_bf16 v[122:125], v[154:157], v[186:189], v[122:125]
	v_mfma_f32_16x16x32_bf16 v[118:121], v[146:149], v[178:181], v[118:121]
	v_mfma_f32_16x16x32_bf16 v[114:117], v[154:157], v[178:181], v[114:117]
	v_mfma_f32_16x16x32_bf16 v[94:97], v[146:149], v[170:173], v[94:97]
	v_mfma_f32_16x16x32_bf16 v[90:93], v[154:157], v[170:173], v[90:93]
	v_mfma_f32_16x16x32_bf16 v[86:89], v[146:149], v[162:165], v[86:89]
	v_mfma_f32_16x16x32_bf16 v[82:85], v[154:157], v[162:165], v[82:85]
	v_mfma_f32_16x16x32_bf16 v[126:129], v[150:153], v[190:193], v[126:129]
	v_mfma_f32_16x16x32_bf16 v[122:125], v[158:161], v[190:193], v[122:125]
	v_mfma_f32_16x16x32_bf16 v[118:121], v[150:153], v[182:185], v[118:121]
	v_mfma_f32_16x16x32_bf16 v[114:117], v[158:161], v[182:185], v[114:117]
	v_mfma_f32_16x16x32_bf16 v[94:97], v[150:153], v[174:177], v[94:97]
	v_mfma_f32_16x16x32_bf16 v[90:93], v[158:161], v[174:177], v[90:93]
	v_mfma_f32_16x16x32_bf16 v[86:89], v[150:153], v[166:169], v[86:89]
	v_mfma_f32_16x16x32_bf16 v[82:85], v[158:161], v[166:169], v[82:85]
	s_setprio 0
	s_setprio 1
	v_mfma_f32_16x16x32_bf16 v[110:113], v[130:133], v[186:189], v[110:113]
	v_mfma_f32_16x16x32_bf16 v[106:109], v[138:141], v[186:189], v[106:109]
	v_mfma_f32_16x16x32_bf16 v[102:105], v[130:133], v[178:181], v[102:105]
	v_mfma_f32_16x16x32_bf16 v[98:101], v[138:141], v[178:181], v[98:101]
	v_mfma_f32_16x16x32_bf16 v[78:81], v[130:133], v[170:173], v[78:81]
	v_mfma_f32_16x16x32_bf16 v[74:77], v[138:141], v[170:173], v[74:77]
	v_mfma_f32_16x16x32_bf16 v[70:73], v[130:133], v[162:165], v[70:73]
	v_mfma_f32_16x16x32_bf16 v[66:69], v[138:141], v[162:165], v[66:69]
	v_mfma_f32_16x16x32_bf16 v[110:113], v[134:137], v[190:193], v[110:113]
	v_mfma_f32_16x16x32_bf16 v[106:109], v[142:145], v[190:193], v[106:109]
	v_mfma_f32_16x16x32_bf16 v[102:105], v[134:137], v[182:185], v[102:105]
	v_mfma_f32_16x16x32_bf16 v[98:101], v[142:145], v[182:185], v[98:101]
	v_mfma_f32_16x16x32_bf16 v[78:81], v[134:137], v[174:177], v[78:81]
	v_mfma_f32_16x16x32_bf16 v[74:77], v[142:145], v[174:177], v[74:77]
	v_mfma_f32_16x16x32_bf16 v[70:73], v[134:137], v[166:169], v[70:73]
	v_mfma_f32_16x16x32_bf16 v[66:69], v[142:145], v[166:169], v[66:69]
	s_setprio 0
	s_barrier
	s_mov_b32 m0, s22
	v_lshl_add_u64 v[228:229], s[12:13], 0, v[212:213]
	s_add_u32 s40, s12, 0x40000
	ds_read_b128 v[186:189], v232 offset:16384
	ds_read_b128 v[190:193], v232 offset:17408
	ds_read_b128 v[178:181], v232 offset:18432
	ds_read_b128 v[182:185], v232 offset:19456
	ds_read_b128 v[170:173], v232 offset:20480
	ds_read_b128 v[174:177], v232 offset:21504
	ds_read_b128 v[162:165], v232 offset:22528
	ds_read_b128 v[166:169], v232 offset:23552
	global_load_lds_dwordx4 v[228:229], off
	v_lshl_add_u64 v[226:227], s[12:13], 0, v[216:217]
	s_mov_b32 m0, s23
	s_addc_u32 s41, s13, 0
	global_load_lds_dwordx4 v[226:227], off
	v_lshl_add_u64 v[194:195], s[40:41], 0, v[212:213]
	s_mov_b32 m0, s24
	v_lshl_add_u64 v[222:223], s[14:15], 0, v[210:211]
	global_load_lds_dwordx4 v[194:195], off
	v_lshl_add_u64 v[194:195], s[40:41], 0, v[216:217]
	s_mov_b32 m0, s25
	v_lshl_add_u64 v[224:225], s[14:15], 0, v[214:215]
	global_load_lds_dwordx4 v[194:195], off
	s_mov_b32 m0, s5
	s_andn2_b64 vcc, exec, s[16:17]
	global_load_lds_dwordx4 v[222:223], off
	s_mov_b32 m0, s26
	s_nop 0
	global_load_lds_dwordx4 v[224:225], off
	s_waitcnt vmcnt(16)
	s_cbranch_vccnz .LBB0_1889
	s_waitcnt vmcnt(8)
	s_branch .LBB0_1889

; #define PG8_STAGE(bufoff, gbase, voff) do { _Pragma("unroll") for (int _i = 0; _i < 2; ++_i) \
;         __builtin_amdgcn_global_load_lds((const unsigned*)((const char*)(gbase) + (voff)[_i]), (PG8_LAS unsigned*)(lds + (bufoff) + ldsw + _i * 8192), 16, 0, 0); } while (0)
; #define PG8_LDA(dst, b, h) do { _Pragma("unroll") for (int m = 0; m < 4; ++m) _Pragma("unroll") for (int k = 0; k < 2; ++k) dst[m][k] = *(const PG8_LAS bf16x8*)(lds + PG8_SA(b, h) + aoff + m * 2048 + k * 1024); } while (0)
; #define PG8_LDB(dst, b, h) do { _Pragma("unroll") for (int n = 0; n < 2; ++n) _Pragma("unroll") for (int k = 0; k < 2; ++k) dst[n][k] = *(const PG8_LAS bf16x8*)(lds + PG8_SB(b, h) + boff + n * 2048 + k * 1024); } while (0)
; #define PG8_MMA(ai, bj, At, Bt) do { __builtin_amdgcn_s_setprio(1); _Pragma("unroll") for (int m = 0; m < 4; ++m) _Pragma("unroll") for (int n = 0; n < 2; ++n) _Pragma("unroll") for (int k = 0; k < 2; ++k) \
;         acc[ai][bj][m][n] = __builtin_amdgcn_mfma_f32_16x16x32_bf16(Bt[n][k], At[m][k], acc[ai][bj][m][n], 0, 0, 0); __builtin_amdgcn_s_setprio(0); } while (0)
; #define PG8_WAIT_V(n) asm volatile("s_waitcnt vmcnt(" #n ")" ::: "memory")
; #define PG8_WAIT_VN(n) asm volatile("s_waitcnt vmcnt(%0)" :: "n"(n) : "memory")
; #define PG8_WAIT_L(n) asm volatile("s_waitcnt lgkmcnt(" #n ")" ::: "memory")
; #define PG8_BAR __builtin_amdgcn_s_barrier()
; #define PG8_SCHED __builtin_amdgcn_sched_barrier(0)
; template <class Epi, class Sched, bool ALIGN_EPI = false, bool SP2 = false>
; __device__ __forceinline__ void gemm_phase(PG8_LAS unsigned char* lds, const Gemm g, const Sched& S, const Epi& E, const int wave_id) {
;     ...
;             PG8_WAIT_VN(8 + Epi::NS); if (strict) PG8_WAIT_V(8); PG8_WAIT_L(0); PG8_BAR; PG8_MMA(1, 0, At, B0); PG8_MMA(1, 1, At, B1); PG8_BAR; PG8_SCHED;
;             PG8_LDB(B0, 1, 0); PG8_LDB(B1, 1, 1); PG8_SCHED; PG8_LDA(At, 1, 0); PG8_STAGE(PG8_SA(0, 1), a2 + hstep, voffA);
;             PG8_WAIT_V(8); PG8_WAIT_L(0); PG8_BAR; PG8_MMA(0, 0, At, B0); PG8_MMA(0, 1, At, B1); PG8_BAR; PG8_SCHED;
.LBB0_1952:
	s_waitcnt lgkmcnt(0)
	s_setprio 1
	s_barrier
	v_mfma_f32_16x16x32_bf16 v[62:65], v[146:149], v[186:189], v[62:65]
	v_mfma_f32_16x16x32_bf16 v[58:61], v[154:157], v[186:189], v[58:61]
	v_mfma_f32_16x16x32_bf16 v[54:57], v[146:149], v[178:181], v[54:57]
	v_mfma_f32_16x16x32_bf16 v[50:53], v[154:157], v[178:181], v[50:53]
	v_mfma_f32_16x16x32_bf16 v[30:33], v[146:149], v[170:173], v[30:33]
	v_mfma_f32_16x16x32_bf16 v[26:29], v[154:157], v[170:173], v[26:29]
	v_mfma_f32_16x16x32_bf16 v[22:25], v[146:149], v[162:165], v[22:25]
	v_mfma_f32_16x16x32_bf16 v[18:21], v[154:157], v[162:165], v[18:21]
	v_mfma_f32_16x16x32_bf16 v[62:65], v[150:153], v[190:193], v[62:65]
	v_mfma_f32_16x16x32_bf16 v[58:61], v[158:161], v[190:193], v[58:61]
	v_mfma_f32_16x16x32_bf16 v[54:57], v[150:153], v[182:185], v[54:57]
	v_mfma_f32_16x16x32_bf16 v[50:53], v[158:161], v[182:185], v[50:53]
	v_mfma_f32_16x16x32_bf16 v[30:33], v[150:153], v[174:177], v[30:33]
	v_mfma_f32_16x16x32_bf16 v[26:29], v[158:161], v[174:177], v[26:29]
	v_mfma_f32_16x16x32_bf16 v[22:25], v[150:153], v[166:169], v[22:25]
	v_mfma_f32_16x16x32_bf16 v[18:21], v[158:161], v[166:169], v[18:21]
	s_setprio 0
	s_setprio 1
	v_mfma_f32_16x16x32_bf16 v[46:49], v[130:133], v[186:189], v[46:49]
	v_mfma_f32_16x16x32_bf16 v[42:45], v[138:141], v[186:189], v[42:45]
	v_mfma_f32_16x16x32_bf16 v[38:41], v[130:133], v[178:181], v[38:41]
	v_mfma_f32_16x16x32_bf16 v[34:37], v[138:141], v[178:181], v[34:37]
	v_mfma_f32_16x16x32_bf16 v[14:17], v[130:133], v[170:173], v[14:17]
	v_mfma_f32_16x16x32_bf16 v[10:13], v[138:141], v[170:173], v[10:13]
	v_mfma_f32_16x16x32_bf16 v[6:9], v[130:133], v[162:165], v[6:9]
	v_mfma_f32_16x16x32_bf16 v[2:5], v[138:141], v[162:165], v[2:5]
	v_mfma_f32_16x16x32_bf16 v[46:49], v[134:137], v[190:193], v[46:49]
	v_mfma_f32_16x16x32_bf16 v[42:45], v[142:145], v[190:193], v[42:45]
	v_mfma_f32_16x16x32_bf16 v[38:41], v[134:137], v[182:185], v[38:41]
	v_mfma_f32_16x16x32_bf16 v[34:37], v[142:145], v[182:185], v[34:37]
	v_mfma_f32_16x16x32_bf16 v[14:17], v[134:137], v[174:177], v[14:17]
	v_mfma_f32_16x16x32_bf16 v[10:13], v[142:145], v[174:177], v[10:13]
	v_mfma_f32_16x16x32_bf16 v[6:9], v[134:137], v[166:169], v[6:9]
	v_mfma_f32_16x16x32_bf16 v[2:5], v[142:145], v[166:169], v[2:5]
	s_setprio 0
	s_barrier
	s_add_i32 s28, 0, 0x18000
	s_add_i32 s29, 0, 0x1c000
	v_add_u32_e32 v142, s28, v246
	v_add_u32_e32 v158, s29, v246
	ds_read_b128 v[130:133], v142
	ds_read_b128 v[134:137], v142 offset:1024
	ds_read_b128 v[138:141], v142 offset:2048
	ds_read_b128 v[142:145], v142 offset:3072
	ds_read_b128 v[146:149], v158
	ds_read_b128 v[150:153], v158 offset:1024
	ds_read_b128 v[154:157], v158 offset:2048
	ds_read_b128 v[158:161], v158 offset:3072
	s_add_u32 s26, s26, 0x40000
	s_addc_u32 s27, s27, 0
	s_mov_b32 m0, s52
	v_lshl_add_u64 v[194:195], s[26:27], 0, v[216:217]
	ds_read_b128 v[162:165], v247 offset:32768
	ds_read_b128 v[166:169], v247 offset:33792
	ds_read_b128 v[170:173], v247 offset:34816
	ds_read_b128 v[174:177], v247 offset:35840
	ds_read_b128 v[178:181], v247 offset:36864
	ds_read_b128 v[182:185], v247 offset:37888
	ds_read_b128 v[186:189], v247 offset:38912
	ds_read_b128 v[190:193], v247 offset:39936
	global_load_lds_dwordx4 v[194:195], off
	v_lshl_add_u64 v[194:195], s[26:27], 0, v[212:213]
	s_mov_b32 m0, s54
	s_nop 0
	global_load_lds_dwordx4 v[194:195], off
	s_waitcnt vmcnt(18)
	s_cmp_eq_u32 s100, 0
	s_cbranch_scc1 .Lthird_wait_relaxed_2
	s_waitcnt vmcnt(8)
; #define PG8_STAGE(bufoff, gbase, voff) do { _Pragma("unroll") for (int _i = 0; _i < 2; ++_i) \
;         __builtin_amdgcn_global_load_lds((const unsigned*)((const char*)(gbase) + (voff)[_i]), (PG8_LAS unsigned*)(lds + (bufoff) + ldsw + _i * 8192), 16, 0, 0); } while (0)
; #define PG8_LDA(dst, b, h) do { _Pragma("unroll") for (int m = 0; m < 4; ++m) _Pragma("unroll") for (int k = 0; k < 2; ++k) dst[m][k] = *(const PG8_LAS bf16x8*)(lds + PG8_SA(b, h) + aoff + m * 2048 + k * 1024); } while (0)
; #define PG8_MMA(ai, bj, At, Bt) do { __builtin_amdgcn_s_setprio(1); _Pragma("unroll") for (int m = 0; m < 4; ++m) _Pragma("unroll") for (int n = 0; n < 2; ++n) _Pragma("unroll") for (int k = 0; k < 2; ++k) \
;         acc[ai][bj][m][n] = __builtin_amdgcn_mfma_f32_16x16x32_bf16(Bt[n][k], At[m][k], acc[ai][bj][m][n], 0, 0, 0); __builtin_amdgcn_s_setprio(0); } while (0)
; #define PG8_WAIT_V(n) asm volatile("s_waitcnt vmcnt(" #n ")" ::: "memory")
; #define PG8_WAIT_L(n) asm volatile("s_waitcnt lgkmcnt(" #n ")" ::: "memory")
; #define PG8_BAR __builtin_amdgcn_s_barrier()
; #define PG8_SCHED __builtin_amdgcn_sched_barrier(0)
; template <class Epi, class Sched, bool ALIGN_EPI = false, bool SP2 = false>
; __device__ __forceinline__ void gemm_phase(PG8_LAS unsigned char* lds, const Gemm g, const Sched& S, const Epi& E, const int wave_id) {
;     ...
;             PG8_WAIT_V(8); PG8_WAIT_L(0); PG8_BAR; PG8_MMA(0, 0, At, B0); PG8_MMA(0, 1, At, B1); PG8_BAR; PG8_SCHED;
;             PG8_LDA(At, 1, 1); PG8_STAGE(PG8_SB(1, 0), b3, voffB); PG8_STAGE(PG8_SB(1, 1), b3 + hstep, voffB); PG8_STAGE(PG8_SA(1, 0), a3, voffA);
;             PG8_WAIT_V(8); PG8_WAIT_L(0); PG8_BAR; PG8_MMA(1, 0, At, B0); PG8_MMA(1, 1, At, B1); PG8_BAR; PG8_SCHED;
.Lthird_wait_relaxed_2:
	s_waitcnt lgkmcnt(0)
	s_setprio 1
	s_barrier
	v_mfma_f32_16x16x32_bf16 v[126:129], v[130:133], v[162:165], v[126:129]
	v_mfma_f32_16x16x32_bf16 v[122:125], v[138:141], v[162:165], v[122:125]
	v_mfma_f32_16x16x32_bf16 v[118:121], v[130:133], v[170:173], v[118:121]
	v_mfma_f32_16x16x32_bf16 v[114:117], v[138:141], v[170:173], v[114:117]
	v_mfma_f32_16x16x32_bf16 v[94:97], v[130:133], v[178:181], v[94:97]
	v_mfma_f32_16x16x32_bf16 v[90:93], v[138:141], v[178:181], v[90:93]
	v_mfma_f32_16x16x32_bf16 v[86:89], v[130:133], v[186:189], v[86:89]
	v_mfma_f32_16x16x32_bf16 v[82:85], v[138:141], v[186:189], v[82:85]
	v_mfma_f32_16x16x32_bf16 v[126:129], v[134:137], v[166:169], v[126:129]
	v_mfma_f32_16x16x32_bf16 v[122:125], v[142:145], v[166:169], v[122:125]
	v_mfma_f32_16x16x32_bf16 v[118:121], v[134:137], v[174:177], v[118:121]
	v_mfma_f32_16x16x32_bf16 v[114:117], v[142:145], v[174:177], v[114:117]
	v_mfma_f32_16x16x32_bf16 v[94:97], v[134:137], v[182:185], v[94:97]
	v_mfma_f32_16x16x32_bf16 v[90:93], v[142:145], v[182:185], v[90:93]
	v_mfma_f32_16x16x32_bf16 v[86:89], v[134:137], v[190:193], v[86:89]
	v_mfma_f32_16x16x32_bf16 v[82:85], v[142:145], v[190:193], v[82:85]
	s_setprio 0
	s_setprio 1
	v_mfma_f32_16x16x32_bf16 v[110:113], v[146:149], v[162:165], v[110:113]
	v_mfma_f32_16x16x32_bf16 v[106:109], v[154:157], v[162:165], v[106:109]
	v_mfma_f32_16x16x32_bf16 v[102:105], v[146:149], v[170:173], v[102:105]
	v_mfma_f32_16x16x32_bf16 v[98:101], v[154:157], v[170:173], v[98:101]
	v_mfma_f32_16x16x32_bf16 v[78:81], v[146:149], v[178:181], v[78:81]
	v_mfma_f32_16x16x32_bf16 v[74:77], v[154:157], v[178:181], v[74:77]
	v_mfma_f32_16x16x32_bf16 v[70:73], v[146:149], v[186:189], v[70:73]
	v_mfma_f32_16x16x32_bf16 v[66:69], v[154:157], v[186:189], v[66:69]
	v_mfma_f32_16x16x32_bf16 v[110:113], v[150:153], v[166:169], v[110:113]
	v_mfma_f32_16x16x32_bf16 v[106:109], v[158:161], v[166:169], v[106:109]
	v_mfma_f32_16x16x32_bf16 v[102:105], v[150:153], v[174:177], v[102:105]
	v_mfma_f32_16x16x32_bf16 v[98:101], v[158:161], v[174:177], v[98:101]
	v_mfma_f32_16x16x32_bf16 v[78:81], v[150:153], v[182:185], v[78:81]
	v_mfma_f32_16x16x32_bf16 v[74:77], v[158:161], v[182:185], v[74:77]
	v_mfma_f32_16x16x32_bf16 v[70:73], v[150:153], v[190:193], v[70:73]
	v_mfma_f32_16x16x32_bf16 v[66:69], v[158:161], v[190:193], v[66:69]
	s_setprio 0
	s_barrier
	s_add_i32 s26, s28, s39
	v_lshl_add_u64 v[194:195], v[232:233], 0, s[64:65]
	s_mov_b32 m0, s26
	ds_read_b128 v[162:165], v247 offset:49152
	ds_read_b128 v[166:169], v247 offset:50176
	ds_read_b128 v[170:173], v247 offset:51200
	ds_read_b128 v[174:177], v247 offset:52224
	ds_read_b128 v[178:181], v247 offset:53248
	ds_read_b128 v[182:185], v247 offset:54272
	ds_read_b128 v[186:189], v247 offset:55296
	ds_read_b128 v[190:193], v247 offset:56320
	global_load_lds_dwordx4 v[194:195], off
	s_add_i32 m0, s26, 0x2000
	s_add_u32 s24, s24, 0x40080
	v_lshl_add_u64 v[194:195], v[230:231], 0, s[64:65]
	s_addc_u32 s25, s25, 0
	s_add_i32 s26, s29, s39
	global_load_lds_dwordx4 v[194:195], off
	v_lshl_add_u64 v[194:195], s[24:25], 0, v[214:215]
	s_mov_b32 m0, s26
	s_nop 0
	global_load_lds_dwordx4 v[194:195], off
	v_lshl_add_u64 v[194:195], s[24:25], 0, v[210:211]
	s_add_i32 m0, s26, 0x2000
	s_nop 0
	global_load_lds_dwordx4 v[194:195], off
	v_lshl_add_u64 v[194:195], v[226:227], 0, s[64:65]
	s_mov_b32 m0, s57
	s_nop 0
	global_load_lds_dwordx4 v[194:195], off
	v_lshl_add_u64 v[194:195], v[228:229], 0, s[64:65]
	s_mov_b32 m0, s62
	s_nop 0
	global_load_lds_dwordx4 v[194:195], off
	s_waitcnt vmcnt(8)
	s_waitcnt lgkmcnt(0)
	s_setprio 1
	s_barrier
	v_mfma_f32_16x16x32_bf16 v[62:65], v[130:133], v[162:165], v[62:65]
	v_mfma_f32_16x16x32_bf16 v[58:61], v[138:141], v[162:165], v[58:61]
	v_mfma_f32_16x16x32_bf16 v[54:57], v[130:133], v[170:173], v[54:57]
	v_mfma_f32_16x16x32_bf16 v[50:53], v[138:141], v[170:173], v[50:53]
	v_mfma_f32_16x16x32_bf16 v[30:33], v[130:133], v[178:181], v[30:33]
	v_mfma_f32_16x16x32_bf16 v[26:29], v[138:141], v[178:181], v[26:29]
	v_mfma_f32_16x16x32_bf16 v[22:25], v[130:133], v[186:189], v[22:25]
	v_mfma_f32_16x16x32_bf16 v[18:21], v[138:141], v[186:189], v[18:21]
	v_mfma_f32_16x16x32_bf16 v[62:65], v[134:137], v[166:169], v[62:65]
	v_mfma_f32_16x16x32_bf16 v[58:61], v[142:145], v[166:169], v[58:61]
	v_mfma_f32_16x16x32_bf16 v[54:57], v[134:137], v[174:177], v[54:57]
	v_mfma_f32_16x16x32_bf16 v[50:53], v[142:145], v[174:177], v[50:53]
	v_mfma_f32_16x16x32_bf16 v[30:33], v[134:137], v[182:185], v[30:33]
	v_mfma_f32_16x16x32_bf16 v[26:29], v[142:145], v[182:185], v[26:29]
	v_mfma_f32_16x16x32_bf16 v[22:25], v[134:137], v[190:193], v[22:25]
	v_mfma_f32_16x16x32_bf16 v[18:21], v[142:145], v[190:193], v[18:21]
	s_setprio 0
	s_setprio 1
	v_mfma_f32_16x16x32_bf16 v[46:49], v[146:149], v[162:165], v[46:49]
	v_mfma_f32_16x16x32_bf16 v[42:45], v[154:157], v[162:165], v[42:45]
	v_mfma_f32_16x16x32_bf16 v[38:41], v[146:149], v[170:173], v[38:41]
	v_mfma_f32_16x16x32_bf16 v[34:37], v[154:157], v[170:173], v[34:37]
	v_mfma_f32_16x16x32_bf16 v[14:17], v[146:149], v[178:181], v[14:17]
	v_mfma_f32_16x16x32_bf16 v[10:13], v[154:157], v[178:181], v[10:13]
	v_mfma_f32_16x16x32_bf16 v[6:9], v[146:149], v[186:189], v[6:9]
	v_mfma_f32_16x16x32_bf16 v[2:5], v[154:157], v[186:189], v[2:5]
	v_mfma_f32_16x16x32_bf16 v[46:49], v[150:153], v[166:169], v[46:49]
	v_mfma_f32_16x16x32_bf16 v[42:45], v[158:161], v[166:169], v[42:45]
	v_mfma_f32_16x16x32_bf16 v[38:41], v[150:153], v[174:177], v[38:41]
	v_mfma_f32_16x16x32_bf16 v[34:37], v[158:161], v[174:177], v[34:37]
	v_mfma_f32_16x16x32_bf16 v[14:17], v[150:153], v[182:185], v[14:17]
	v_mfma_f32_16x16x32_bf16 v[10:13], v[158:161], v[182:185], v[10:13]
	v_mfma_f32_16x16x32_bf16 v[6:9], v[150:153], v[190:193], v[6:9]
	v_mfma_f32_16x16x32_bf16 v[2:5], v[158:161], v[190:193], v[2:5]
	s_setprio 0
	s_barrier
	s_add_i32 s76, s76, 2
	s_add_u32 s22, s22, 0x100
	s_addc_u32 s23, s23, 0
	s_cmp_gt_u32 s76, 13
	s_cbranch_scc1 .LBB0_1957

; #define PG8_STAGE(bufoff, gbase, voff) do { _Pragma("unroll") for (int _i = 0; _i < 2; ++_i) \
;         __builtin_amdgcn_global_load_lds((const unsigned*)((const char*)(gbase) + (voff)[_i]), (PG8_LAS unsigned*)(lds + (bufoff) + ldsw + _i * 8192), 16, 0, 0); } while (0)
; #define PG8_LDA(dst, b, h) do { _Pragma("unroll") for (int m = 0; m < 4; ++m) _Pragma("unroll") for (int k = 0; k < 2; ++k) dst[m][k] = *(const PG8_LAS bf16x8*)(lds + PG8_SA(b, h) + aoff + m * 2048 + k * 1024); } while (0)
; #define PG8_LDB(dst, b, h) do { _Pragma("unroll") for (int n = 0; n < 2; ++n) _Pragma("unroll") for (int k = 0; k < 2; ++k) dst[n][k] = *(const PG8_LAS bf16x8*)(lds + PG8_SB(b, h) + boff + n * 2048 + k * 1024); } while (0)
; #define PG8_WAIT_V(n) asm volatile("s_waitcnt vmcnt(" #n ")" ::: "memory")
; #define PG8_WAIT_VN(n) asm volatile("s_waitcnt vmcnt(%0)" :: "n"(n) : "memory")
; #define PG8_WAIT_L(n) asm volatile("s_waitcnt lgkmcnt(" #n ")" ::: "memory")
; #define PG8_BAR __builtin_amdgcn_s_barrier()
; template <class Epi, class Sched, bool ALIGN_EPI = false, bool SP2 = false>
; __device__ __forceinline__ void gemm_phase(PG8_LAS unsigned char* lds, const Gemm g, const Sched& S, const Epi& E, const int wave_id) {
;     ...
;             const bool last = (t == nt - 2);
;             const char* a1 = cA + (size_t)(t + 1) * kstep;
;             const char* a2 = last ? nA : cA + (size_t)(t + 2) * kstep; const char* b2 = last ? nB : cB + (size_t)(t + 2) * kstep;
;             const char* a3 = a2 + kstep; const char* b3 = b2 + kstep;
;             if (last && has_next) S.a_ready(nxt);
;             if constexpr (SP2) {
;             int tz_ = __builtin_amdgcn_readfirstlane(t | (ui > 0 ? 0 : 1)); asm volatile("" : "+s"(tz_));
;             const bool strict = !(Epi::NS > 0 && tz_ == 0);
;             PG8_LDB(B0, 0, 0); PG8_LDB(B1, 0, 1); PG8_SCHED; PG8_LDA(At, 0, 0); PG8_STAGE(PG8_SA(1, 1), a1 + hstep, voffA);
;             PG8_WAIT_VN(8 + Epi::NS); if (strict) PG8_WAIT_V(8); PG8_WAIT_L(0); PG8_BAR; PG8_MMA(0, 0, At, B0); PG8_MMA(0, 1, At, B1); PG8_BAR; PG8_SCHED;
;             PG8_LDA(At, 0, 1); PG8_STAGE(PG8_SB(0, 0), b2, voffB); PG8_STAGE(PG8_SB(0, 1), b2 + hstep, voffB); PG8_STAGE(PG8_SA(0, 0), a2, voffA);
;             PG8_WAIT_VN(8 + Epi::NS); if (strict) PG8_WAIT_V(8); PG8_WAIT_L(0); PG8_BAR; PG8_MMA(1, 0, At, B0); PG8_MMA(1, 1, At, B1); PG8_BAR; PG8_SCHED;
.LBB0_1955:
	s_add_u32 s24, s20, s22
	s_addc_u32 s25, s21, s23
	s_add_u32 s24, s24, 0x100
	s_addc_u32 s25, s25, 0
	s_add_u32 s53, s74, s22
	s_addc_u32 s78, s75, s23
	s_cmpk_eq_i32 s22, 0x700
	s_cselect_b32 s27, s13, s25
	s_cselect_b32 s26, s68, s24
	s_cselect_b32 s25, s11, s78
	s_cselect_b32 s24, s69, s53
	s_waitcnt lgkmcnt(0)
	s_setprio 1
	s_barrier
	v_mfma_f32_16x16x32_bf16 v[126:129], v[146:149], v[186:189], v[126:129]
	v_mfma_f32_16x16x32_bf16 v[122:125], v[154:157], v[186:189], v[122:125]
	v_mfma_f32_16x16x32_bf16 v[118:121], v[146:149], v[178:181], v[118:121]
	v_mfma_f32_16x16x32_bf16 v[114:117], v[154:157], v[178:181], v[114:117]
	v_mfma_f32_16x16x32_bf16 v[94:97], v[146:149], v[170:173], v[94:97]
	v_mfma_f32_16x16x32_bf16 v[90:93], v[154:157], v[170:173], v[90:93]
	v_mfma_f32_16x16x32_bf16 v[86:89], v[146:149], v[162:165], v[86:89]
	v_mfma_f32_16x16x32_bf16 v[82:85], v[154:157], v[162:165], v[82:85]
	v_mfma_f32_16x16x32_bf16 v[126:129], v[150:153], v[190:193], v[126:129]
	v_mfma_f32_16x16x32_bf16 v[122:125], v[158:161], v[190:193], v[122:125]
	v_mfma_f32_16x16x32_bf16 v[118:121], v[150:153], v[182:185], v[118:121]
	v_mfma_f32_16x16x32_bf16 v[114:117], v[158:161], v[182:185], v[114:117]
	v_mfma_f32_16x16x32_bf16 v[94:97], v[150:153], v[174:177], v[94:97]
	v_mfma_f32_16x16x32_bf16 v[90:93], v[158:161], v[174:177], v[90:93]
	v_mfma_f32_16x16x32_bf16 v[86:89], v[150:153], v[166:169], v[86:89]
	v_mfma_f32_16x16x32_bf16 v[82:85], v[158:161], v[166:169], v[82:85]
	s_setprio 0
	s_setprio 1
	v_mfma_f32_16x16x32_bf16 v[110:113], v[130:133], v[186:189], v[110:113]
	v_mfma_f32_16x16x32_bf16 v[106:109], v[138:141], v[186:189], v[106:109]
	v_mfma_f32_16x16x32_bf16 v[102:105], v[130:133], v[178:181], v[102:105]
	v_mfma_f32_16x16x32_bf16 v[98:101], v[138:141], v[178:181], v[98:101]
	v_mfma_f32_16x16x32_bf16 v[78:81], v[130:133], v[170:173], v[78:81]
	v_mfma_f32_16x16x32_bf16 v[74:77], v[138:141], v[170:173], v[74:77]
	v_mfma_f32_16x16x32_bf16 v[70:73], v[130:133], v[162:165], v[70:73]
	v_mfma_f32_16x16x32_bf16 v[66:69], v[138:141], v[162:165], v[66:69]
	v_mfma_f32_16x16x32_bf16 v[110:113], v[134:137], v[190:193], v[110:113]
	v_mfma_f32_16x16x32_bf16 v[106:109], v[142:145], v[190:193], v[106:109]
	v_mfma_f32_16x16x32_bf16 v[102:105], v[134:137], v[182:185], v[102:105]
	v_mfma_f32_16x16x32_bf16 v[98:101], v[142:145], v[182:185], v[98:101]
	v_mfma_f32_16x16x32_bf16 v[78:81], v[134:137], v[174:177], v[78:81]
	v_mfma_f32_16x16x32_bf16 v[74:77], v[142:145], v[174:177], v[74:77]
	v_mfma_f32_16x16x32_bf16 v[70:73], v[134:137], v[166:169], v[70:73]
	v_mfma_f32_16x16x32_bf16 v[66:69], v[142:145], v[166:169], v[66:69]
	s_setprio 0
	s_barrier
	s_mov_b32 m0, s42
	v_lshl_add_u64 v[232:233], s[24:25], 0, v[214:215]
	s_add_u32 s90, s24, 0x40000
	ds_read_b128 v[186:189], v247 offset:16384
	ds_read_b128 v[190:193], v247 offset:17408
	ds_read_b128 v[178:181], v247 offset:18432
	ds_read_b128 v[182:185], v247 offset:19456
	ds_read_b128 v[170:173], v247 offset:20480
	ds_read_b128 v[174:177], v247 offset:21504
	ds_read_b128 v[162:165], v247 offset:22528
	ds_read_b128 v[166:169], v247 offset:23552
	global_load_lds_dwordx4 v[232:233], off
	v_lshl_add_u64 v[230:231], s[24:25], 0, v[210:211]
	s_mov_b32 m0, s43
	s_addc_u32 s91, s25, 0
	global_load_lds_dwordx4 v[230:231], off
	v_lshl_add_u64 v[194:195], s[90:91], 0, v[214:215]
	s_mov_b32 m0, s49
	v_lshl_add_u64 v[226:227], s[26:27], 0, v[216:217]
	global_load_lds_dwordx4 v[194:195], off
	v_lshl_add_u64 v[194:195], s[90:91], 0, v[210:211]
	s_mov_b32 m0, s50
	v_lshl_add_u64 v[228:229], s[26:27], 0, v[212:213]
	global_load_lds_dwordx4 v[194:195], off
	s_mov_b32 m0, s41
	s_andn2_b64 vcc, exec, s[28:29]
	global_load_lds_dwordx4 v[226:227], off
	s_mov_b32 m0, s51
	s_nop 0
	global_load_lds_dwordx4 v[228:229], off
	s_waitcnt vmcnt(16)
	s_cbranch_vccnz .LBB0_1952
	s_waitcnt vmcnt(8)
	s_branch .LBB0_1952

; #define PG8_STAGE(bufoff, gbase, voff) do { _Pragma("unroll") for (int _i = 0; _i < 2; ++_i) \
;         __builtin_amdgcn_global_load_lds((const unsigned*)((const char*)(gbase) + (voff)[_i]), (PG8_LAS unsigned*)(lds + (bufoff) + ldsw + _i * 8192), 16, 0, 0); } while (0)
; #define PG8_LDA(dst, b, h) do { _Pragma("unroll") for (int m = 0; m < 4; ++m) _Pragma("unroll") for (int k = 0; k < 2; ++k) dst[m][k] = *(const PG8_LAS bf16x8*)(lds + PG8_SA(b, h) + aoff + m * 2048 + k * 1024); } while (0)
; #define PG8_LDB(dst, b, h) do { _Pragma("unroll") for (int n = 0; n < 2; ++n) _Pragma("unroll") for (int k = 0; k < 2; ++k) dst[n][k] = *(const PG8_LAS bf16x8*)(lds + PG8_SB(b, h) + boff + n * 2048 + k * 1024); } while (0)
; #define PG8_WAIT_V(n) asm volatile("s_waitcnt vmcnt(" #n ")" ::: "memory")
; #define PG8_WAIT_VN(n) asm volatile("s_waitcnt vmcnt(%0)" :: "n"(n) : "memory")
; #define PG8_WAIT_L(n) asm volatile("s_waitcnt lgkmcnt(" #n ")" ::: "memory")
; #define PG8_BAR __builtin_amdgcn_s_barrier()
; template <class Epi, class Sched, bool ALIGN_EPI = false, bool SP2 = false>
; __device__ __forceinline__ void gemm_phase(PG8_LAS unsigned char* lds, const Gemm g, const Sched& S, const Epi& E, const int wave_id) {
;     ...
;             const bool last = (t == nt - 2);
;             const char* a1 = cA + (size_t)(t + 1) * kstep;
;             const char* a2 = last ? nA : cA + (size_t)(t + 2) * kstep; const char* b2 = last ? nB : cB + (size_t)(t + 2) * kstep;
;             const char* a3 = a2 + kstep; const char* b3 = b2 + kstep;
;             if (last && has_next) S.a_ready(nxt);
;             if constexpr (SP2) {
;             int tz_ = __builtin_amdgcn_readfirstlane(t | (ui > 0 ? 0 : 1)); asm volatile("" : "+s"(tz_));
;             const bool strict = !(Epi::NS > 0 && tz_ == 0);
;             PG8_LDB(B0, 0, 0); PG8_LDB(B1, 0, 1); PG8_SCHED; PG8_LDA(At, 0, 0); PG8_STAGE(PG8_SA(1, 1), a1 + hstep, voffA);
;             PG8_WAIT_VN(8 + Epi::NS); if (strict) PG8_WAIT_V(8); PG8_WAIT_L(0); PG8_BAR; PG8_MMA(0, 0, At, B0); PG8_MMA(0, 1, At, B1); PG8_BAR; PG8_SCHED;
;             PG8_LDA(At, 0, 1); PG8_STAGE(PG8_SB(0, 0), b2, voffB); PG8_STAGE(PG8_SB(0, 1), b2 + hstep, voffB); PG8_STAGE(PG8_SA(0, 0), a2, voffA);
;             PG8_WAIT_VN(8 + Epi::NS); if (strict) PG8_WAIT_V(8); PG8_WAIT_L(0); PG8_BAR; PG8_MMA(1, 0, At, B0); PG8_MMA(1, 1, At, B1); PG8_BAR; PG8_SCHED;
.LBB0_2033:
	s_add_u32 s16, s12, s14
	s_addc_u32 s17, s13, s15
	s_add_u32 s16, s16, 0x100
	s_addc_u32 s17, s17, 0
	s_add_u32 s53, s57, s14
	s_addc_u32 s67, s62, s15
	s_cmpk_eq_i32 s14, 0x1500
	s_cselect_b32 s19, s9, s17
	s_cselect_b32 s18, s8, s16
	s_cselect_b32 s17, s11, s67
	s_cselect_b32 s16, s10, s53
	s_waitcnt lgkmcnt(0)
	s_setprio 1
	s_barrier
	v_mfma_f32_16x16x32_bf16 v[126:129], v[146:149], v[186:189], v[126:129]
	v_mfma_f32_16x16x32_bf16 v[122:125], v[154:157], v[186:189], v[122:125]
	v_mfma_f32_16x16x32_bf16 v[110:113], v[146:149], v[178:181], v[110:113]
	v_mfma_f32_16x16x32_bf16 v[106:109], v[154:157], v[178:181], v[106:109]
	v_mfma_f32_16x16x32_bf16 v[94:97], v[146:149], v[170:173], v[94:97]
	v_mfma_f32_16x16x32_bf16 v[90:93], v[154:157], v[170:173], v[90:93]
	v_mfma_f32_16x16x32_bf16 v[78:81], v[146:149], v[162:165], v[78:81]
	v_mfma_f32_16x16x32_bf16 v[74:77], v[154:157], v[162:165], v[74:77]
	v_mfma_f32_16x16x32_bf16 v[126:129], v[150:153], v[190:193], v[126:129]
	v_mfma_f32_16x16x32_bf16 v[122:125], v[158:161], v[190:193], v[122:125]
	v_mfma_f32_16x16x32_bf16 v[110:113], v[150:153], v[182:185], v[110:113]
	v_mfma_f32_16x16x32_bf16 v[106:109], v[158:161], v[182:185], v[106:109]
	v_mfma_f32_16x16x32_bf16 v[94:97], v[150:153], v[174:177], v[94:97]
	v_mfma_f32_16x16x32_bf16 v[90:93], v[158:161], v[174:177], v[90:93]
	v_mfma_f32_16x16x32_bf16 v[78:81], v[150:153], v[166:169], v[78:81]
	v_mfma_f32_16x16x32_bf16 v[74:77], v[158:161], v[166:169], v[74:77]
	s_setprio 0
	s_setprio 1
	v_mfma_f32_16x16x32_bf16 v[118:121], v[130:133], v[186:189], v[118:121]
	v_mfma_f32_16x16x32_bf16 v[114:117], v[138:141], v[186:189], v[114:117]
	v_mfma_f32_16x16x32_bf16 v[102:105], v[130:133], v[178:181], v[102:105]
	v_mfma_f32_16x16x32_bf16 v[98:101], v[138:141], v[178:181], v[98:101]
	v_mfma_f32_16x16x32_bf16 v[86:89], v[130:133], v[170:173], v[86:89]
	v_mfma_f32_16x16x32_bf16 v[82:85], v[138:141], v[170:173], v[82:85]
	v_mfma_f32_16x16x32_bf16 v[70:73], v[130:133], v[162:165], v[70:73]
	v_mfma_f32_16x16x32_bf16 v[66:69], v[138:141], v[162:165], v[66:69]
	v_mfma_f32_16x16x32_bf16 v[118:121], v[134:137], v[190:193], v[118:121]
	v_mfma_f32_16x16x32_bf16 v[114:117], v[142:145], v[190:193], v[114:117]
	v_mfma_f32_16x16x32_bf16 v[102:105], v[134:137], v[182:185], v[102:105]
	v_mfma_f32_16x16x32_bf16 v[98:101], v[142:145], v[182:185], v[98:101]
	v_mfma_f32_16x16x32_bf16 v[86:89], v[134:137], v[174:177], v[86:89]
	v_mfma_f32_16x16x32_bf16 v[82:85], v[142:145], v[174:177], v[82:85]
	v_mfma_f32_16x16x32_bf16 v[70:73], v[134:137], v[166:169], v[70:73]
	v_mfma_f32_16x16x32_bf16 v[66:69], v[142:145], v[166:169], v[66:69]
	s_setprio 0
	s_barrier
	s_mov_b32 m0, s34
	v_lshl_add_u64 v[232:233], s[16:17], 0, v[212:213]
	s_add_u32 s68, s16, 0xb0000
	ds_read_b128 v[186:189], v247 offset:16384
	ds_read_b128 v[190:193], v247 offset:17408
	ds_read_b128 v[178:181], v247 offset:18432
	ds_read_b128 v[182:185], v247 offset:19456
	ds_read_b128 v[170:173], v247 offset:20480
	ds_read_b128 v[174:177], v247 offset:21504
	ds_read_b128 v[162:165], v247 offset:22528
	ds_read_b128 v[166:169], v247 offset:23552
	global_load_lds_dwordx4 v[232:233], off
	v_lshl_add_u64 v[230:231], s[16:17], 0, v[216:217]
	s_mov_b32 m0, s35
	s_addc_u32 s69, s17, 0
	global_load_lds_dwordx4 v[230:231], off
	v_lshl_add_u64 v[194:195], s[68:69], 0, v[212:213]
	s_mov_b32 m0, s36
	v_lshl_add_u64 v[226:227], s[18:19], 0, v[210:211]
	global_load_lds_dwordx4 v[194:195], off
	v_lshl_add_u64 v[194:195], s[68:69], 0, v[216:217]
	s_mov_b32 m0, s37
	v_lshl_add_u64 v[228:229], s[18:19], 0, v[214:215]
	global_load_lds_dwordx4 v[194:195], off
	s_mov_b32 m0, s31
	s_andn2_b64 vcc, exec, s[20:21]
	global_load_lds_dwordx4 v[226:227], off
	s_mov_b32 m0, s38
	s_nop 0
	global_load_lds_dwordx4 v[228:229], off
	s_waitcnt vmcnt(24)
	s_cbranch_vccnz .LBB0_2030
	s_waitcnt vmcnt(8)
	s_branch .LBB0_2030
